# GEMM load segments: LDS-DMA issues interleaved with ds_reads (first DMA at segment start, A-frag reads between DMAs) so TA and LDS pipes overlap; on top of combo
# baseline (speedup 1.0000x reference)
.LBB0_80:
	s_add_u32 s2, s14, 0x100
	v_mov_b32_e32 v0, 0
	s_addc_u32 s8, s15, 0
	s_mov_b32 s9, -2
	v_mov_b32_e32 v1, v0
	v_mov_b32_e32 v2, v0
	v_mov_b32_e32 v3, v0
	v_mov_b32_e32 v6, v0
	s_waitcnt lgkmcnt(0)
	v_mov_b32_e32 v7, v0
	v_mov_b32_e32 v8, v0
	v_mov_b32_e32 v9, v0
	v_mov_b32_e32 v18, v0
	v_mov_b32_e32 v19, v0
	v_mov_b32_e32 v20, v0
	v_mov_b32_e32 v21, v0
	v_mov_b32_e32 v22, v0
	v_mov_b32_e32 v23, v0
	v_mov_b32_e32 v24, v0
	v_mov_b32_e32 v25, v0
	v_mov_b32_e32 v34, v0
	v_mov_b32_e32 v35, v0
	v_mov_b32_e32 v36, v0
	v_mov_b32_e32 v37, v0
	v_mov_b32_e32 v38, v0
	v_mov_b32_e32 v39, v0
	v_mov_b32_e32 v40, v0
	v_mov_b32_e32 v41, v0
	v_mov_b32_e32 v50, v0
	v_mov_b32_e32 v51, v0
	v_mov_b32_e32 v52, v0
	v_mov_b32_e32 v53, v0
	v_mov_b32_e32 v54, v0
	v_mov_b32_e32 v55, v0
	v_mov_b32_e32 v56, v0
	v_mov_b32_e32 v57, v0
	v_mov_b32_e32 v10, v0
	v_mov_b32_e32 v11, v0
	v_mov_b32_e32 v12, v0
	v_mov_b32_e32 v13, v0
	v_mov_b32_e32 v14, v0
	v_mov_b32_e32 v15, v0
	v_mov_b32_e32 v16, v0
	v_mov_b32_e32 v17, v0
	v_mov_b32_e32 v26, v0
	v_mov_b32_e32 v27, v0
	v_mov_b32_e32 v28, v0
	v_mov_b32_e32 v29, v0
	v_mov_b32_e32 v30, v0
	v_mov_b32_e32 v31, v0
	v_mov_b32_e32 v32, v0
	v_mov_b32_e32 v33, v0
	v_mov_b32_e32 v42, v0
	v_mov_b32_e32 v43, v0
	v_mov_b32_e32 v44, v0
	v_mov_b32_e32 v45, v0
	v_mov_b32_e32 v46, v0
	v_mov_b32_e32 v47, v0
	v_mov_b32_e32 v48, v0
	v_mov_b32_e32 v49, v0
	v_mov_b32_e32 v58, v0
	v_mov_b32_e32 v59, v0
	v_mov_b32_e32 v60, v0
	v_mov_b32_e32 v61, v0
	v_mov_b32_e32 v62, v0
	v_mov_b32_e32 v63, v0
	v_mov_b32_e32 v64, v0
	v_mov_b32_e32 v65, v0
	v_mov_b32_e32 v66, v0
	v_mov_b32_e32 v67, v0
	v_mov_b32_e32 v68, v0
	v_mov_b32_e32 v69, v0
	v_mov_b32_e32 v70, v0
	v_mov_b32_e32 v71, v0
	v_mov_b32_e32 v72, v0
	v_mov_b32_e32 v73, v0
	v_mov_b32_e32 v82, v0
	v_mov_b32_e32 v83, v0
	v_mov_b32_e32 v84, v0
	v_mov_b32_e32 v85, v0
	v_mov_b32_e32 v86, v0
	v_mov_b32_e32 v87, v0
	v_mov_b32_e32 v88, v0
	v_mov_b32_e32 v89, v0
	v_mov_b32_e32 v98, v0
	v_mov_b32_e32 v99, v0
	v_mov_b32_e32 v100, v0
	v_mov_b32_e32 v101, v0
	v_mov_b32_e32 v102, v0
	v_mov_b32_e32 v103, v0
	v_mov_b32_e32 v104, v0
	v_mov_b32_e32 v105, v0
	v_mov_b32_e32 v114, v0
	v_mov_b32_e32 v115, v0
	v_mov_b32_e32 v116, v0
	v_mov_b32_e32 v117, v0
	v_mov_b32_e32 v118, v0
	v_mov_b32_e32 v119, v0
	v_mov_b32_e32 v120, v0
	v_mov_b32_e32 v121, v0
	v_mov_b32_e32 v74, v0
	v_mov_b32_e32 v75, v0
	v_mov_b32_e32 v76, v0
	v_mov_b32_e32 v77, v0
	v_mov_b32_e32 v78, v0
	v_mov_b32_e32 v79, v0
	v_mov_b32_e32 v80, v0
	v_mov_b32_e32 v81, v0
	v_mov_b32_e32 v90, v0
	v_mov_b32_e32 v91, v0
	v_mov_b32_e32 v92, v0
	v_mov_b32_e32 v93, v0
	v_mov_b32_e32 v94, v0
	v_mov_b32_e32 v95, v0
	v_mov_b32_e32 v96, v0
	v_mov_b32_e32 v97, v0
	v_mov_b32_e32 v106, v0
	v_mov_b32_e32 v107, v0
	v_mov_b32_e32 v108, v0
	v_mov_b32_e32 v109, v0
	v_mov_b32_e32 v110, v0
	v_mov_b32_e32 v111, v0
	v_mov_b32_e32 v112, v0
	v_mov_b32_e32 v113, v0
	v_mov_b32_e32 v122, v0
	v_mov_b32_e32 v123, v0
	v_mov_b32_e32 v124, v0
	v_mov_b32_e32 v125, v0
	v_mov_b32_e32 v126, v0
	v_mov_b32_e32 v127, v0
	v_mov_b32_e32 v128, v0
	v_mov_b32_e32 v129, v0
	s_cmp_eq_u32 s36, 1
	s_cbranch_scc1 .LBB0_81
	v_lshl_add_u64 v[162:163], s[0:1], 0, v[136:137]
	s_add_i32 m0, s30, 0xc000
	s_nop 0
	global_load_lds_dwordx4 v[162:163], off
	s_add_u32 s14, s0, 0x100
	s_addc_u32 s15, s1, 0
	s_add_i32 s3, 0, 0x10000
	s_cmpk_eq_i32 s9, 0x7c
	s_cselect_b32 s27, s43, s15
	s_cselect_b32 s26, s42, s14
	v_add_u32_e32 v162, s3, v145
	s_cselect_b32 s23, s79, s8
	s_cselect_b32 s22, s78, s2
	s_add_i32 s4, 0, 0x14000
	ds_read_b128 v[140:143], v162
	ds_read_b128 v[148:151], v162 offset:1024
	ds_read_b128 v[172:175], v162 offset:2048
	ds_read_b128 v[190:193], v162 offset:3072
	v_add_u32_e32 v162, s4, v145
	ds_read_b128 v[194:197], v162
	ds_read_b128 v[198:201], v162 offset:1024
	ds_read_b128 v[202:205], v162 offset:2048
	ds_read_b128 v[206:209], v162 offset:3072
	ds_read_b128 v[210:213], v147
	ds_read_b128 v[214:217], v147 offset:1024
	ds_read_b128 v[218:221], v147 offset:2048
	ds_read_b128 v[222:225], v147 offset:3072
	ds_read_b128 v[226:229], v147 offset:4096
	ds_read_b128 v[230:233], v147 offset:5120
	ds_read_b128 v[234:237], v147 offset:6144
	ds_read_b128 v[238:241], v147 offset:7168
	v_lshl_add_u64 v[162:163], s[0:1], 0, v[138:139]
	s_add_i32 m0, s30, 0xe000
	s_nop 0
	global_load_lds_dwordx4 v[162:163], off
	s_waitcnt vmcnt(24)
	s_waitcnt lgkmcnt(0)
	s_barrier
	s_setprio 1
	s_waitcnt lgkmcnt(0)
	v_mfma_f32_16x16x32_bf16 v[126:129], v[140:143], v[210:213], v[126:129]
	v_mfma_f32_16x16x32_bf16 v[122:125], v[172:175], v[210:213], v[122:125]
	v_mfma_f32_16x16x32_bf16 v[110:113], v[140:143], v[218:221], v[110:113]
	v_mfma_f32_16x16x32_bf16 v[106:109], v[172:175], v[218:221], v[106:109]
	v_mfma_f32_16x16x32_bf16 v[94:97], v[140:143], v[226:229], v[94:97]
	v_mfma_f32_16x16x32_bf16 v[90:93], v[172:175], v[226:229], v[90:93]
	v_mfma_f32_16x16x32_bf16 v[78:81], v[140:143], v[234:237], v[78:81]
	v_mfma_f32_16x16x32_bf16 v[74:77], v[172:175], v[234:237], v[74:77]
	v_mfma_f32_16x16x32_bf16 v[126:129], v[148:151], v[214:217], v[126:129]
	v_mfma_f32_16x16x32_bf16 v[122:125], v[190:193], v[214:217], v[122:125]
	v_mfma_f32_16x16x32_bf16 v[110:113], v[148:151], v[222:225], v[110:113]
	v_mfma_f32_16x16x32_bf16 v[106:109], v[190:193], v[222:225], v[106:109]
	v_mfma_f32_16x16x32_bf16 v[94:97], v[148:151], v[230:233], v[94:97]
	v_mfma_f32_16x16x32_bf16 v[90:93], v[190:193], v[230:233], v[90:93]
	v_mfma_f32_16x16x32_bf16 v[78:81], v[148:151], v[238:241], v[78:81]
	v_mfma_f32_16x16x32_bf16 v[74:77], v[190:193], v[238:241], v[74:77]
	s_setprio 0
	s_setprio 1
	v_mfma_f32_16x16x32_bf16 v[118:121], v[194:197], v[210:213], v[118:121]
	v_mfma_f32_16x16x32_bf16 v[114:117], v[202:205], v[210:213], v[114:117]
	v_mfma_f32_16x16x32_bf16 v[102:105], v[194:197], v[218:221], v[102:105]
	v_mfma_f32_16x16x32_bf16 v[98:101], v[202:205], v[218:221], v[98:101]
	v_mfma_f32_16x16x32_bf16 v[86:89], v[194:197], v[226:229], v[86:89]
	v_mfma_f32_16x16x32_bf16 v[82:85], v[202:205], v[226:229], v[82:85]
	v_mfma_f32_16x16x32_bf16 v[70:73], v[194:197], v[234:237], v[70:73]
	v_mfma_f32_16x16x32_bf16 v[66:69], v[202:205], v[234:237], v[66:69]
	v_mfma_f32_16x16x32_bf16 v[118:121], v[198:201], v[214:217], v[118:121]
	v_mfma_f32_16x16x32_bf16 v[114:117], v[206:209], v[214:217], v[114:117]
	v_mfma_f32_16x16x32_bf16 v[102:105], v[198:201], v[222:225], v[102:105]
	v_mfma_f32_16x16x32_bf16 v[98:101], v[206:209], v[222:225], v[98:101]
	v_mfma_f32_16x16x32_bf16 v[86:89], v[198:201], v[230:233], v[86:89]
	v_mfma_f32_16x16x32_bf16 v[82:85], v[206:209], v[230:233], v[82:85]
	v_mfma_f32_16x16x32_bf16 v[70:73], v[198:201], v[238:241], v[70:73]
	v_mfma_f32_16x16x32_bf16 v[66:69], v[206:209], v[238:241], v[66:69]
	s_setprio 0
	s_barrier
	s_add_i32 s0, s3, s11
	v_lshl_add_u64 v[162:163], s[22:23], 0, v[4:5]
	s_mov_b32 m0, s0
	s_nop 0
	global_load_lds_dwordx4 v[162:163], off
	ds_read_b128 v[210:213], v147 offset:16384
	ds_read_b128 v[214:217], v147 offset:17408
	s_add_i32 m0, s0, 0x2000
	s_add_u32 s0, s22, 0x208000
	v_lshl_add_u64 v[166:167], s[22:23], 0, v[130:131]
	s_addc_u32 s1, s23, 0
	s_add_i32 s3, s4, s11
	global_load_lds_dwordx4 v[166:167], off
	ds_read_b128 v[218:221], v147 offset:18432
	ds_read_b128 v[222:225], v147 offset:19456
	v_lshl_add_u64 v[176:177], s[0:1], 0, v[4:5]
	s_mov_b32 m0, s3
	v_lshl_add_u64 v[180:181], s[26:27], 0, v[132:133]
	global_load_lds_dwordx4 v[176:177], off
	ds_read_b128 v[226:229], v147 offset:20480
	ds_read_b128 v[230:233], v147 offset:21504
	v_lshl_add_u64 v[176:177], s[0:1], 0, v[130:131]
	s_add_i32 m0, s3, 0x2000
	s_nop 0
	global_load_lds_dwordx4 v[176:177], off
	ds_read_b128 v[234:237], v147 offset:22528
	ds_read_b128 v[238:241], v147 offset:23552
	v_lshl_add_u64 v[176:177], s[26:27], 0, v[134:135]
	s_mov_b32 m0, s30
	s_nop 0
	global_load_lds_dwordx4 v[176:177], off
	s_mov_b32 m0, s31
	s_nop 0
	global_load_lds_dwordx4 v[180:181], off
	s_waitcnt vmcnt(24)
	s_waitcnt lgkmcnt(0)
	s_barrier
	s_setprio 1
	s_waitcnt lgkmcnt(0)
	v_mfma_f32_16x16x32_bf16 v[62:65], v[140:143], v[210:213], v[62:65]
	v_mfma_f32_16x16x32_bf16 v[58:61], v[172:175], v[210:213], v[58:61]
	v_mfma_f32_16x16x32_bf16 v[46:49], v[140:143], v[218:221], v[46:49]
	v_mfma_f32_16x16x32_bf16 v[42:45], v[172:175], v[218:221], v[42:45]
	v_mfma_f32_16x16x32_bf16 v[30:33], v[140:143], v[226:229], v[30:33]
	v_mfma_f32_16x16x32_bf16 v[26:29], v[172:175], v[226:229], v[26:29]
	v_mfma_f32_16x16x32_bf16 v[14:17], v[140:143], v[234:237], v[14:17]
	v_mfma_f32_16x16x32_bf16 v[10:13], v[172:175], v[234:237], v[10:13]
	v_mfma_f32_16x16x32_bf16 v[62:65], v[148:151], v[214:217], v[62:65]
	v_mfma_f32_16x16x32_bf16 v[58:61], v[190:193], v[214:217], v[58:61]
	v_mfma_f32_16x16x32_bf16 v[46:49], v[148:151], v[222:225], v[46:49]
	v_mfma_f32_16x16x32_bf16 v[42:45], v[190:193], v[222:225], v[42:45]
	v_mfma_f32_16x16x32_bf16 v[30:33], v[148:151], v[230:233], v[30:33]
	v_mfma_f32_16x16x32_bf16 v[26:29], v[190:193], v[230:233], v[26:29]
	v_mfma_f32_16x16x32_bf16 v[14:17], v[148:151], v[238:241], v[14:17]
	v_mfma_f32_16x16x32_bf16 v[10:13], v[190:193], v[238:241], v[10:13]
	s_setprio 0
	s_setprio 1
	v_mfma_f32_16x16x32_bf16 v[54:57], v[194:197], v[210:213], v[54:57]
	v_mfma_f32_16x16x32_bf16 v[50:53], v[202:205], v[210:213], v[50:53]
	v_mfma_f32_16x16x32_bf16 v[38:41], v[194:197], v[218:221], v[38:41]
	v_mfma_f32_16x16x32_bf16 v[34:37], v[202:205], v[218:221], v[34:37]
	v_mfma_f32_16x16x32_bf16 v[22:25], v[194:197], v[226:229], v[22:25]
	v_mfma_f32_16x16x32_bf16 v[18:21], v[202:205], v[226:229], v[18:21]
	v_mfma_f32_16x16x32_bf16 v[6:9], v[194:197], v[234:237], v[6:9]
	v_mfma_f32_16x16x32_bf16 v[0:3], v[202:205], v[234:237], v[0:3]
	v_mfma_f32_16x16x32_bf16 v[54:57], v[198:201], v[214:217], v[54:57]
	v_mfma_f32_16x16x32_bf16 v[50:53], v[206:209], v[214:217], v[50:53]
	v_mfma_f32_16x16x32_bf16 v[38:41], v[198:201], v[222:225], v[38:41]
	v_mfma_f32_16x16x32_bf16 v[34:37], v[206:209], v[222:225], v[34:37]
	v_mfma_f32_16x16x32_bf16 v[22:25], v[198:201], v[230:233], v[22:25]
	v_mfma_f32_16x16x32_bf16 v[18:21], v[206:209], v[230:233], v[18:21]
	v_mfma_f32_16x16x32_bf16 v[6:9], v[198:201], v[238:241], v[6:9]
	v_mfma_f32_16x16x32_bf16 v[0:3], v[206:209], v[238:241], v[0:3]
	s_setprio 0
	s_barrier
	s_branch .Lpeelmid_81
.LBB0_81:
	v_lshl_add_u64 v[162:163], s[0:1], 0, v[136:137]
	s_add_i32 m0, s30, 0xc000
	s_nop 0
	global_load_lds_dwordx4 v[162:163], off
	s_add_u32 s14, s0, 0x100
	s_addc_u32 s15, s1, 0
	s_add_i32 s3, 0, 0x10000
	s_cmpk_eq_i32 s9, 0x7c
	s_cselect_b32 s27, s43, s15
	s_cselect_b32 s26, s42, s14
	v_add_u32_e32 v162, s3, v145
	s_cselect_b32 s23, s79, s8
	s_cselect_b32 s22, s78, s2
	s_add_i32 s4, 0, 0x14000
	ds_read_b128 v[140:143], v162
	ds_read_b128 v[148:151], v162 offset:1024
	ds_read_b128 v[172:175], v162 offset:2048
	ds_read_b128 v[190:193], v162 offset:3072
	v_add_u32_e32 v162, s4, v145
	ds_read_b128 v[194:197], v162
	ds_read_b128 v[198:201], v162 offset:1024
	ds_read_b128 v[202:205], v162 offset:2048
	ds_read_b128 v[206:209], v162 offset:3072
	ds_read_b128 v[210:213], v147
	ds_read_b128 v[214:217], v147 offset:1024
	ds_read_b128 v[218:221], v147 offset:2048
	ds_read_b128 v[222:225], v147 offset:3072
	ds_read_b128 v[226:229], v147 offset:4096
	ds_read_b128 v[230:233], v147 offset:5120
	ds_read_b128 v[234:237], v147 offset:6144
	ds_read_b128 v[238:241], v147 offset:7168
	v_lshl_add_u64 v[162:163], s[0:1], 0, v[138:139]
	s_add_i32 m0, s30, 0xe000
	s_nop 0
	global_load_lds_dwordx4 v[162:163], off
	s_waitcnt vmcnt(8)
	s_waitcnt lgkmcnt(0)
	s_barrier
	s_setprio 1
	s_waitcnt lgkmcnt(0)
	v_mfma_f32_16x16x32_bf16 v[126:129], v[140:143], v[210:213], v[126:129]
	v_mfma_f32_16x16x32_bf16 v[122:125], v[172:175], v[210:213], v[122:125]
	v_mfma_f32_16x16x32_bf16 v[110:113], v[140:143], v[218:221], v[110:113]
	v_mfma_f32_16x16x32_bf16 v[106:109], v[172:175], v[218:221], v[106:109]
	v_mfma_f32_16x16x32_bf16 v[94:97], v[140:143], v[226:229], v[94:97]
	v_mfma_f32_16x16x32_bf16 v[90:93], v[172:175], v[226:229], v[90:93]
	v_mfma_f32_16x16x32_bf16 v[78:81], v[140:143], v[234:237], v[78:81]
	v_mfma_f32_16x16x32_bf16 v[74:77], v[172:175], v[234:237], v[74:77]
	v_mfma_f32_16x16x32_bf16 v[126:129], v[148:151], v[214:217], v[126:129]
	v_mfma_f32_16x16x32_bf16 v[122:125], v[190:193], v[214:217], v[122:125]
	v_mfma_f32_16x16x32_bf16 v[110:113], v[148:151], v[222:225], v[110:113]
	v_mfma_f32_16x16x32_bf16 v[106:109], v[190:193], v[222:225], v[106:109]
	v_mfma_f32_16x16x32_bf16 v[94:97], v[148:151], v[230:233], v[94:97]
	v_mfma_f32_16x16x32_bf16 v[90:93], v[190:193], v[230:233], v[90:93]
	v_mfma_f32_16x16x32_bf16 v[78:81], v[148:151], v[238:241], v[78:81]
	v_mfma_f32_16x16x32_bf16 v[74:77], v[190:193], v[238:241], v[74:77]
	s_setprio 0
	s_setprio 1
	v_mfma_f32_16x16x32_bf16 v[118:121], v[194:197], v[210:213], v[118:121]
	v_mfma_f32_16x16x32_bf16 v[114:117], v[202:205], v[210:213], v[114:117]
	v_mfma_f32_16x16x32_bf16 v[102:105], v[194:197], v[218:221], v[102:105]
	v_mfma_f32_16x16x32_bf16 v[98:101], v[202:205], v[218:221], v[98:101]
	v_mfma_f32_16x16x32_bf16 v[86:89], v[194:197], v[226:229], v[86:89]
	v_mfma_f32_16x16x32_bf16 v[82:85], v[202:205], v[226:229], v[82:85]
	v_mfma_f32_16x16x32_bf16 v[70:73], v[194:197], v[234:237], v[70:73]
	v_mfma_f32_16x16x32_bf16 v[66:69], v[202:205], v[234:237], v[66:69]
	v_mfma_f32_16x16x32_bf16 v[118:121], v[198:201], v[214:217], v[118:121]
	v_mfma_f32_16x16x32_bf16 v[114:117], v[206:209], v[214:217], v[114:117]
	v_mfma_f32_16x16x32_bf16 v[102:105], v[198:201], v[222:225], v[102:105]
	v_mfma_f32_16x16x32_bf16 v[98:101], v[206:209], v[222:225], v[98:101]
	v_mfma_f32_16x16x32_bf16 v[86:89], v[198:201], v[230:233], v[86:89]
	v_mfma_f32_16x16x32_bf16 v[82:85], v[206:209], v[230:233], v[82:85]
	v_mfma_f32_16x16x32_bf16 v[70:73], v[198:201], v[238:241], v[70:73]
	v_mfma_f32_16x16x32_bf16 v[66:69], v[206:209], v[238:241], v[66:69]
	s_setprio 0
	s_barrier
	s_add_i32 s0, s3, s11
	v_lshl_add_u64 v[162:163], s[22:23], 0, v[4:5]
	s_mov_b32 m0, s0
	s_nop 0
	global_load_lds_dwordx4 v[162:163], off
	ds_read_b128 v[210:213], v147 offset:16384
	ds_read_b128 v[214:217], v147 offset:17408
	s_add_i32 m0, s0, 0x2000
	s_add_u32 s0, s22, 0x208000
	v_lshl_add_u64 v[166:167], s[22:23], 0, v[130:131]
	s_addc_u32 s1, s23, 0
	s_add_i32 s3, s4, s11
	global_load_lds_dwordx4 v[166:167], off
	ds_read_b128 v[218:221], v147 offset:18432
	ds_read_b128 v[222:225], v147 offset:19456
	v_lshl_add_u64 v[176:177], s[0:1], 0, v[4:5]
	s_mov_b32 m0, s3
	v_lshl_add_u64 v[180:181], s[26:27], 0, v[132:133]
	global_load_lds_dwordx4 v[176:177], off
	ds_read_b128 v[226:229], v147 offset:20480
	ds_read_b128 v[230:233], v147 offset:21504
	v_lshl_add_u64 v[176:177], s[0:1], 0, v[130:131]
	s_add_i32 m0, s3, 0x2000
	s_nop 0
	global_load_lds_dwordx4 v[176:177], off
	ds_read_b128 v[234:237], v147 offset:22528
	ds_read_b128 v[238:241], v147 offset:23552
	v_lshl_add_u64 v[176:177], s[26:27], 0, v[134:135]
	s_mov_b32 m0, s30
	s_nop 0
	global_load_lds_dwordx4 v[176:177], off
	s_mov_b32 m0, s31
	s_nop 0
	global_load_lds_dwordx4 v[180:181], off
	s_waitcnt vmcnt(8)
	s_waitcnt lgkmcnt(0)
	s_barrier
	s_setprio 1
	s_waitcnt lgkmcnt(0)
	v_mfma_f32_16x16x32_bf16 v[62:65], v[140:143], v[210:213], v[62:65]
	v_mfma_f32_16x16x32_bf16 v[58:61], v[172:175], v[210:213], v[58:61]
	v_mfma_f32_16x16x32_bf16 v[46:49], v[140:143], v[218:221], v[46:49]
	v_mfma_f32_16x16x32_bf16 v[42:45], v[172:175], v[218:221], v[42:45]
	v_mfma_f32_16x16x32_bf16 v[30:33], v[140:143], v[226:229], v[30:33]
	v_mfma_f32_16x16x32_bf16 v[26:29], v[172:175], v[226:229], v[26:29]
	v_mfma_f32_16x16x32_bf16 v[14:17], v[140:143], v[234:237], v[14:17]
	v_mfma_f32_16x16x32_bf16 v[10:13], v[172:175], v[234:237], v[10:13]
	v_mfma_f32_16x16x32_bf16 v[62:65], v[148:151], v[214:217], v[62:65]
	v_mfma_f32_16x16x32_bf16 v[58:61], v[190:193], v[214:217], v[58:61]
	v_mfma_f32_16x16x32_bf16 v[46:49], v[148:151], v[222:225], v[46:49]
	v_mfma_f32_16x16x32_bf16 v[42:45], v[190:193], v[222:225], v[42:45]
	v_mfma_f32_16x16x32_bf16 v[30:33], v[148:151], v[230:233], v[30:33]
	v_mfma_f32_16x16x32_bf16 v[26:29], v[190:193], v[230:233], v[26:29]
	v_mfma_f32_16x16x32_bf16 v[14:17], v[148:151], v[238:241], v[14:17]
	v_mfma_f32_16x16x32_bf16 v[10:13], v[190:193], v[238:241], v[10:13]
	s_setprio 0
	s_setprio 1
	v_mfma_f32_16x16x32_bf16 v[54:57], v[194:197], v[210:213], v[54:57]
	v_mfma_f32_16x16x32_bf16 v[50:53], v[202:205], v[210:213], v[50:53]
	v_mfma_f32_16x16x32_bf16 v[38:41], v[194:197], v[218:221], v[38:41]
	v_mfma_f32_16x16x32_bf16 v[34:37], v[202:205], v[218:221], v[34:37]
	v_mfma_f32_16x16x32_bf16 v[22:25], v[194:197], v[226:229], v[22:25]
	v_mfma_f32_16x16x32_bf16 v[18:21], v[202:205], v[226:229], v[18:21]
	v_mfma_f32_16x16x32_bf16 v[6:9], v[194:197], v[234:237], v[6:9]
	v_mfma_f32_16x16x32_bf16 v[0:3], v[202:205], v[234:237], v[0:3]
	v_mfma_f32_16x16x32_bf16 v[54:57], v[198:201], v[214:217], v[54:57]
	v_mfma_f32_16x16x32_bf16 v[50:53], v[206:209], v[214:217], v[50:53]
	v_mfma_f32_16x16x32_bf16 v[38:41], v[198:201], v[222:225], v[38:41]
	v_mfma_f32_16x16x32_bf16 v[34:37], v[206:209], v[222:225], v[34:37]
	v_mfma_f32_16x16x32_bf16 v[22:25], v[198:201], v[230:233], v[22:25]
	v_mfma_f32_16x16x32_bf16 v[18:21], v[206:209], v[230:233], v[18:21]
	v_mfma_f32_16x16x32_bf16 v[6:9], v[198:201], v[238:241], v[6:9]
	v_mfma_f32_16x16x32_bf16 v[0:3], v[206:209], v[238:241], v[0:3]
	s_setprio 0
	s_barrier
.Lpeelmid_81:
	s_add_u32 s0, s26, 0x208000
	s_addc_u32 s1, s27, 0
	s_mov_b32 m0, s34
	v_lshl_add_u64 v[242:243], s[0:1], 0, v[134:135]
	global_load_lds_dwordx4 v[242:243], off
	s_add_i32 s3, 0, 0x18000
	v_add_u32_e32 v164, s3, v145
	s_add_i32 s4, 0, 0x1c000
	ds_read_b128 v[140:143], v164
	ds_read_b128 v[148:151], v164 offset:1024
	ds_read_b128 v[172:175], v164 offset:2048
	ds_read_b128 v[190:193], v164 offset:3072
	v_add_u32_e32 v164, s4, v145
	ds_read_b128 v[194:197], v164
	ds_read_b128 v[198:201], v164 offset:1024
	ds_read_b128 v[202:205], v164 offset:2048
	ds_read_b128 v[206:209], v164 offset:3072
	ds_read_b128 v[210:213], v147 offset:32768
	ds_read_b128 v[214:217], v147 offset:33792
	ds_read_b128 v[218:221], v147 offset:34816
	ds_read_b128 v[222:225], v147 offset:35840
	ds_read_b128 v[226:229], v147 offset:36864
	ds_read_b128 v[230:233], v147 offset:37888
	ds_read_b128 v[234:237], v147 offset:38912
	ds_read_b128 v[238:241], v147 offset:39936
	v_lshl_add_u64 v[242:243], s[0:1], 0, v[132:133]
	s_mov_b32 m0, s35
	s_nop 0
	global_load_lds_dwordx4 v[242:243], off
	s_waitcnt vmcnt(8)
	s_waitcnt lgkmcnt(0)
	s_barrier
	s_setprio 1
	s_waitcnt lgkmcnt(0)
	v_mfma_f32_16x16x32_bf16 v[126:129], v[140:143], v[210:213], v[126:129]
	v_mfma_f32_16x16x32_bf16 v[122:125], v[172:175], v[210:213], v[122:125]
	v_mfma_f32_16x16x32_bf16 v[110:113], v[140:143], v[218:221], v[110:113]
	v_mfma_f32_16x16x32_bf16 v[106:109], v[172:175], v[218:221], v[106:109]
	v_mfma_f32_16x16x32_bf16 v[94:97], v[140:143], v[226:229], v[94:97]
	v_mfma_f32_16x16x32_bf16 v[90:93], v[172:175], v[226:229], v[90:93]
	v_mfma_f32_16x16x32_bf16 v[78:81], v[140:143], v[234:237], v[78:81]
	v_mfma_f32_16x16x32_bf16 v[74:77], v[172:175], v[234:237], v[74:77]
	v_mfma_f32_16x16x32_bf16 v[126:129], v[148:151], v[214:217], v[126:129]
	v_mfma_f32_16x16x32_bf16 v[122:125], v[190:193], v[214:217], v[122:125]
	v_mfma_f32_16x16x32_bf16 v[110:113], v[148:151], v[222:225], v[110:113]
	v_mfma_f32_16x16x32_bf16 v[106:109], v[190:193], v[222:225], v[106:109]
	v_mfma_f32_16x16x32_bf16 v[94:97], v[148:151], v[230:233], v[94:97]
	v_mfma_f32_16x16x32_bf16 v[90:93], v[190:193], v[230:233], v[90:93]
	v_mfma_f32_16x16x32_bf16 v[78:81], v[148:151], v[238:241], v[78:81]
	v_mfma_f32_16x16x32_bf16 v[74:77], v[190:193], v[238:241], v[74:77]
	s_setprio 0
	s_setprio 1
	v_mfma_f32_16x16x32_bf16 v[118:121], v[194:197], v[210:213], v[118:121]
	v_mfma_f32_16x16x32_bf16 v[114:117], v[202:205], v[210:213], v[114:117]
	v_mfma_f32_16x16x32_bf16 v[102:105], v[194:197], v[218:221], v[102:105]
	v_mfma_f32_16x16x32_bf16 v[98:101], v[202:205], v[218:221], v[98:101]
	v_mfma_f32_16x16x32_bf16 v[86:89], v[194:197], v[226:229], v[86:89]
	v_mfma_f32_16x16x32_bf16 v[82:85], v[202:205], v[226:229], v[82:85]
	v_mfma_f32_16x16x32_bf16 v[70:73], v[194:197], v[234:237], v[70:73]
	v_mfma_f32_16x16x32_bf16 v[66:69], v[202:205], v[234:237], v[66:69]
	v_mfma_f32_16x16x32_bf16 v[118:121], v[198:201], v[214:217], v[118:121]
	v_mfma_f32_16x16x32_bf16 v[114:117], v[206:209], v[214:217], v[114:117]
	v_mfma_f32_16x16x32_bf16 v[102:105], v[198:201], v[222:225], v[102:105]
	v_mfma_f32_16x16x32_bf16 v[98:101], v[206:209], v[222:225], v[98:101]
	v_mfma_f32_16x16x32_bf16 v[86:89], v[198:201], v[230:233], v[86:89]
	v_mfma_f32_16x16x32_bf16 v[82:85], v[206:209], v[230:233], v[82:85]
	v_mfma_f32_16x16x32_bf16 v[70:73], v[198:201], v[238:241], v[70:73]
	v_mfma_f32_16x16x32_bf16 v[66:69], v[206:209], v[238:241], v[66:69]
	s_setprio 0
	s_barrier
	s_add_i32 s0, s3, s11
	v_lshl_add_u64 v[162:163], v[162:163], 0, s[70:71]
	s_mov_b32 m0, s0
	s_nop 0
	global_load_lds_dwordx4 v[162:163], off
	ds_read_b128 v[210:213], v147 offset:49152
	ds_read_b128 v[214:217], v147 offset:50176
	s_add_i32 m0, s0, 0x2000
	s_add_u32 s0, s22, 0x208080
	v_lshl_add_u64 v[162:163], v[166:167], 0, s[70:71]
	s_addc_u32 s1, s23, 0
	s_add_i32 s3, s4, s11
	global_load_lds_dwordx4 v[162:163], off
	ds_read_b128 v[218:221], v147 offset:51200
	ds_read_b128 v[222:225], v147 offset:52224
	v_lshl_add_u64 v[162:163], s[0:1], 0, v[4:5]
	s_mov_b32 m0, s3
	s_nop 0
	global_load_lds_dwordx4 v[162:163], off
	ds_read_b128 v[226:229], v147 offset:53248
	ds_read_b128 v[230:233], v147 offset:54272
	v_lshl_add_u64 v[162:163], s[0:1], 0, v[130:131]
	s_add_i32 m0, s3, 0x2000
	s_nop 0
	global_load_lds_dwordx4 v[162:163], off
	ds_read_b128 v[234:237], v147 offset:55296
	ds_read_b128 v[238:241], v147 offset:56320
	v_lshl_add_u64 v[162:163], v[176:177], 0, s[70:71]
	s_mov_b32 m0, s51
	s_nop 0
	global_load_lds_dwordx4 v[162:163], off
	v_lshl_add_u64 v[162:163], v[180:181], 0, s[70:71]
	s_mov_b32 m0, s52
	s_nop 0
	global_load_lds_dwordx4 v[162:163], off
	s_waitcnt vmcnt(8)
	s_waitcnt lgkmcnt(0)
	s_barrier
	s_setprio 1
	s_waitcnt lgkmcnt(0)
	v_mfma_f32_16x16x32_bf16 v[62:65], v[140:143], v[210:213], v[62:65]
	v_mfma_f32_16x16x32_bf16 v[58:61], v[172:175], v[210:213], v[58:61]
	v_mfma_f32_16x16x32_bf16 v[46:49], v[140:143], v[218:221], v[46:49]
	v_mfma_f32_16x16x32_bf16 v[42:45], v[172:175], v[218:221], v[42:45]
	v_mfma_f32_16x16x32_bf16 v[30:33], v[140:143], v[226:229], v[30:33]
	v_mfma_f32_16x16x32_bf16 v[26:29], v[172:175], v[226:229], v[26:29]
	v_mfma_f32_16x16x32_bf16 v[14:17], v[140:143], v[234:237], v[14:17]
	v_mfma_f32_16x16x32_bf16 v[10:13], v[172:175], v[234:237], v[10:13]
	v_mfma_f32_16x16x32_bf16 v[62:65], v[148:151], v[214:217], v[62:65]
	v_mfma_f32_16x16x32_bf16 v[58:61], v[190:193], v[214:217], v[58:61]
	v_mfma_f32_16x16x32_bf16 v[46:49], v[148:151], v[222:225], v[46:49]
	v_mfma_f32_16x16x32_bf16 v[42:45], v[190:193], v[222:225], v[42:45]
	v_mfma_f32_16x16x32_bf16 v[30:33], v[148:151], v[230:233], v[30:33]
	v_mfma_f32_16x16x32_bf16 v[26:29], v[190:193], v[230:233], v[26:29]
	v_mfma_f32_16x16x32_bf16 v[14:17], v[148:151], v[238:241], v[14:17]
	v_mfma_f32_16x16x32_bf16 v[10:13], v[190:193], v[238:241], v[10:13]
	s_setprio 0
	s_setprio 1
	v_mfma_f32_16x16x32_bf16 v[54:57], v[194:197], v[210:213], v[54:57]
	v_mfma_f32_16x16x32_bf16 v[50:53], v[202:205], v[210:213], v[50:53]
	v_mfma_f32_16x16x32_bf16 v[38:41], v[194:197], v[218:221], v[38:41]
	v_mfma_f32_16x16x32_bf16 v[34:37], v[202:205], v[218:221], v[34:37]
	v_mfma_f32_16x16x32_bf16 v[22:25], v[194:197], v[226:229], v[22:25]
	v_mfma_f32_16x16x32_bf16 v[18:21], v[202:205], v[226:229], v[18:21]
	v_mfma_f32_16x16x32_bf16 v[6:9], v[194:197], v[234:237], v[6:9]
	v_mfma_f32_16x16x32_bf16 v[0:3], v[202:205], v[234:237], v[0:3]
	v_mfma_f32_16x16x32_bf16 v[54:57], v[198:201], v[214:217], v[54:57]
	v_mfma_f32_16x16x32_bf16 v[50:53], v[206:209], v[214:217], v[50:53]
	v_mfma_f32_16x16x32_bf16 v[38:41], v[198:201], v[222:225], v[38:41]
	v_mfma_f32_16x16x32_bf16 v[34:37], v[206:209], v[222:225], v[34:37]
	v_mfma_f32_16x16x32_bf16 v[22:25], v[198:201], v[230:233], v[22:25]
	v_mfma_f32_16x16x32_bf16 v[18:21], v[206:209], v[230:233], v[18:21]
	v_mfma_f32_16x16x32_bf16 v[6:9], v[198:201], v[238:241], v[6:9]
	v_mfma_f32_16x16x32_bf16 v[0:3], v[206:209], v[238:241], v[0:3]
	s_setprio 0
	s_barrier
	s_add_i32 s9, s9, 2
	s_add_u32 s2, s2, 0x100
	s_addc_u32 s8, s8, 0
	s_cmpk_gt_u32 s9, 0x7d
	s_mov_b64 s[0:1], s[14:15]
	s_cbranch_scc0 .LBB0_81
	s_and_b64 vcc, exec, s[48:49]
	s_cbranch_vccz .LBB0_84
	s_barrier

.LBB0_123:
	s_ashr_i32 s3, s51, 24
	s_lshl_b32 s2, s51, 8
	s_andn2_b32 s3, s3, 63
	s_add_i32 s2, s3, s2
	s_ashr_i32 s3, s2, 31
	s_lshl_b64 s[2:3], s[2:3], 12
	s_add_u32 s48, s11, s2
	s_addc_u32 s49, s26, s3
	s_and_b64 s[2:3], s[38:39], exec
	s_cselect_b32 s2, s49, s1
	s_cselect_b32 s8, s48, s0
	s_ashr_i32 s47, s46, 31
	s_lshl_b64 s[4:5], s[46:47], 20
	v_readlane_b32 s6, v254, 1
	v_readlane_b32 s7, v254, 2
	s_add_u32 s78, s6, s4
	s_addc_u32 s79, s7, s5
	s_and_b64 s[4:5], s[38:39], exec
	s_cselect_b32 s10, s79, s15
	s_cselect_b32 s24, s78, s14
	s_add_u32 s22, s0, 0x80080
	s_addc_u32 s23, s1, 0
	s_add_u32 s9, s14, 0x100
	v_mov_b32_e32 v0, 0
	s_addc_u32 s25, s15, 0
	s_mov_b32 s28, -2
	v_mov_b32_e32 v1, v0
	v_mov_b32_e32 v2, v0
	v_mov_b32_e32 v3, v0
	v_mov_b32_e32 v6, v0
	v_mov_b32_e32 v7, v0
	v_mov_b32_e32 v8, v0
	v_mov_b32_e32 v9, v0
	v_mov_b32_e32 v10, v0
	v_mov_b32_e32 v11, v0
	v_mov_b32_e32 v12, v0
	v_mov_b32_e32 v13, v0
	v_mov_b32_e32 v14, v0
	v_mov_b32_e32 v15, v0
	v_mov_b32_e32 v16, v0
	v_mov_b32_e32 v17, v0
	v_mov_b32_e32 v18, v0
	v_mov_b32_e32 v19, v0
	v_mov_b32_e32 v20, v0
	v_mov_b32_e32 v21, v0
	v_mov_b32_e32 v22, v0
	v_mov_b32_e32 v23, v0
	v_mov_b32_e32 v24, v0
	v_mov_b32_e32 v25, v0
	v_mov_b32_e32 v26, v0
	v_mov_b32_e32 v27, v0
	v_mov_b32_e32 v28, v0
	v_mov_b32_e32 v29, v0
	v_mov_b32_e32 v30, v0
	v_mov_b32_e32 v31, v0
	v_mov_b32_e32 v32, v0
	v_mov_b32_e32 v33, v0
	v_mov_b32_e32 v58, v0
	v_mov_b32_e32 v59, v0
	v_mov_b32_e32 v60, v0
	v_mov_b32_e32 v61, v0
	v_mov_b32_e32 v62, v0
	v_mov_b32_e32 v63, v0
	v_mov_b32_e32 v64, v0
	v_mov_b32_e32 v65, v0
	v_mov_b32_e32 v74, v0
	v_mov_b32_e32 v75, v0
	v_mov_b32_e32 v76, v0
	v_mov_b32_e32 v77, v0
	v_mov_b32_e32 v78, v0
	v_mov_b32_e32 v79, v0
	v_mov_b32_e32 v80, v0
	v_mov_b32_e32 v81, v0
	v_mov_b32_e32 v82, v0
	v_mov_b32_e32 v83, v0
	v_mov_b32_e32 v84, v0
	v_mov_b32_e32 v85, v0
	v_mov_b32_e32 v86, v0
	v_mov_b32_e32 v87, v0
	v_mov_b32_e32 v88, v0
	v_mov_b32_e32 v89, v0
	v_mov_b32_e32 v90, v0
	v_mov_b32_e32 v91, v0
	v_mov_b32_e32 v92, v0
	v_mov_b32_e32 v93, v0
	v_mov_b32_e32 v94, v0
	v_mov_b32_e32 v95, v0
	v_mov_b32_e32 v96, v0
	v_mov_b32_e32 v97, v0
	v_mov_b32_e32 v34, v0
	v_mov_b32_e32 v35, v0
	v_mov_b32_e32 v36, v0
	v_mov_b32_e32 v37, v0
	v_mov_b32_e32 v38, v0
	v_mov_b32_e32 v39, v0
	v_mov_b32_e32 v40, v0
	v_mov_b32_e32 v41, v0
	v_mov_b32_e32 v42, v0
	v_mov_b32_e32 v43, v0
	v_mov_b32_e32 v44, v0
	v_mov_b32_e32 v45, v0
	v_mov_b32_e32 v46, v0
	v_mov_b32_e32 v47, v0
	v_mov_b32_e32 v48, v0
	v_mov_b32_e32 v49, v0
	v_mov_b32_e32 v50, v0
	v_mov_b32_e32 v51, v0
	v_mov_b32_e32 v52, v0
	v_mov_b32_e32 v53, v0
	v_mov_b32_e32 v54, v0
	v_mov_b32_e32 v55, v0
	v_mov_b32_e32 v56, v0
	v_mov_b32_e32 v57, v0
	v_mov_b32_e32 v66, v0
	v_mov_b32_e32 v67, v0
	v_mov_b32_e32 v68, v0
	v_mov_b32_e32 v69, v0
	v_mov_b32_e32 v70, v0
	v_mov_b32_e32 v71, v0
	v_mov_b32_e32 v72, v0
	v_mov_b32_e32 v73, v0
	v_mov_b32_e32 v98, v0
	v_mov_b32_e32 v99, v0
	v_mov_b32_e32 v100, v0
	v_mov_b32_e32 v101, v0
	v_mov_b32_e32 v102, v0
	v_mov_b32_e32 v103, v0
	v_mov_b32_e32 v104, v0
	v_mov_b32_e32 v105, v0
	v_mov_b32_e32 v106, v0
	v_mov_b32_e32 v107, v0
	v_mov_b32_e32 v108, v0
	v_mov_b32_e32 v109, v0
	v_mov_b32_e32 v110, v0
	v_mov_b32_e32 v111, v0
	v_mov_b32_e32 v112, v0
	v_mov_b32_e32 v113, v0
	v_mov_b32_e32 v114, v0
	v_mov_b32_e32 v115, v0
	v_mov_b32_e32 v116, v0
	v_mov_b32_e32 v117, v0
	v_mov_b32_e32 v118, v0
	v_mov_b32_e32 v119, v0
	v_mov_b32_e32 v120, v0
	v_mov_b32_e32 v121, v0
	v_mov_b32_e32 v122, v0
	v_mov_b32_e32 v123, v0
	v_mov_b32_e32 v124, v0
	v_mov_b32_e32 v125, v0
	v_mov_b32_e32 v126, v0
	v_mov_b32_e32 v127, v0
	v_mov_b32_e32 v128, v0
	v_mov_b32_e32 v129, v0
	s_cmp_eq_u32 s50, 1
	s_cbranch_scc1 .LBB0_124
	v_lshl_add_u64 v[162:163], s[22:23], 0, v[136:137]
	s_add_i32 m0, s30, 0xc000
	s_nop 0
	global_load_lds_dwordx4 v[162:163], off
	s_add_u32 s0, s22, 0xfff80080
	s_addc_u32 s1, s23, -1
	s_add_i32 s3, 0, 0x10000
	s_cmp_eq_u32 s28, 28
	s_cselect_b32 s15, s2, s1
	s_cselect_b32 s14, s8, s0
	v_add_u32_e32 v162, s3, v141
	s_cselect_b32 s1, s10, s25
	s_cselect_b32 s0, s24, s9
	s_add_i32 s6, 0, 0x14000
	ds_read_b128 v[144:147], v162
	ds_read_b128 v[148:151], v162 offset:1024
	ds_read_b128 v[172:175], v162 offset:2048
	ds_read_b128 v[190:193], v162 offset:3072
	v_add_u32_e32 v162, s6, v141
	ds_read_b128 v[194:197], v162
	ds_read_b128 v[198:201], v162 offset:1024
	ds_read_b128 v[202:205], v162 offset:2048
	ds_read_b128 v[206:209], v162 offset:3072
	ds_read_b128 v[210:213], v143
	ds_read_b128 v[214:217], v143 offset:1024
	ds_read_b128 v[218:221], v143 offset:2048
	ds_read_b128 v[222:225], v143 offset:3072
	ds_read_b128 v[226:229], v143 offset:4096
	ds_read_b128 v[230:233], v143 offset:5120
	ds_read_b128 v[234:237], v143 offset:6144
	ds_read_b128 v[238:241], v143 offset:7168
	v_lshl_add_u64 v[162:163], s[22:23], 0, v[138:139]
	s_add_i32 m0, s30, 0xe000
	s_nop 0
	global_load_lds_dwordx4 v[162:163], off
	s_waitcnt vmcnt(24)
	s_waitcnt lgkmcnt(0)
	s_barrier
	s_setprio 1
	s_waitcnt lgkmcnt(0)
	v_mfma_f32_16x16x32_bf16 v[126:129], v[144:147], v[210:213], v[126:129]
	v_mfma_f32_16x16x32_bf16 v[122:125], v[172:175], v[210:213], v[122:125]
	v_mfma_f32_16x16x32_bf16 v[118:121], v[144:147], v[218:221], v[118:121]
	v_mfma_f32_16x16x32_bf16 v[114:117], v[172:175], v[218:221], v[114:117]
	v_mfma_f32_16x16x32_bf16 v[110:113], v[144:147], v[226:229], v[110:113]
	v_mfma_f32_16x16x32_bf16 v[106:109], v[172:175], v[226:229], v[106:109]
	v_mfma_f32_16x16x32_bf16 v[102:105], v[144:147], v[234:237], v[102:105]
	v_mfma_f32_16x16x32_bf16 v[98:101], v[172:175], v[234:237], v[98:101]
	v_mfma_f32_16x16x32_bf16 v[126:129], v[148:151], v[214:217], v[126:129]
	v_mfma_f32_16x16x32_bf16 v[122:125], v[190:193], v[214:217], v[122:125]
	v_mfma_f32_16x16x32_bf16 v[118:121], v[148:151], v[222:225], v[118:121]
	v_mfma_f32_16x16x32_bf16 v[114:117], v[190:193], v[222:225], v[114:117]
	v_mfma_f32_16x16x32_bf16 v[110:113], v[148:151], v[230:233], v[110:113]
	v_mfma_f32_16x16x32_bf16 v[106:109], v[190:193], v[230:233], v[106:109]
	v_mfma_f32_16x16x32_bf16 v[102:105], v[148:151], v[238:241], v[102:105]
	v_mfma_f32_16x16x32_bf16 v[98:101], v[190:193], v[238:241], v[98:101]
	s_setprio 0
	s_setprio 1
	v_mfma_f32_16x16x32_bf16 v[70:73], v[194:197], v[210:213], v[70:73]
	v_mfma_f32_16x16x32_bf16 v[66:69], v[202:205], v[210:213], v[66:69]
	v_mfma_f32_16x16x32_bf16 v[54:57], v[194:197], v[218:221], v[54:57]
	v_mfma_f32_16x16x32_bf16 v[50:53], v[202:205], v[218:221], v[50:53]
	v_mfma_f32_16x16x32_bf16 v[46:49], v[194:197], v[226:229], v[46:49]
	v_mfma_f32_16x16x32_bf16 v[42:45], v[202:205], v[226:229], v[42:45]
	v_mfma_f32_16x16x32_bf16 v[38:41], v[194:197], v[234:237], v[38:41]
	v_mfma_f32_16x16x32_bf16 v[34:37], v[202:205], v[234:237], v[34:37]
	v_mfma_f32_16x16x32_bf16 v[70:73], v[198:201], v[214:217], v[70:73]
	v_mfma_f32_16x16x32_bf16 v[66:69], v[206:209], v[214:217], v[66:69]
	v_mfma_f32_16x16x32_bf16 v[54:57], v[198:201], v[222:225], v[54:57]
	v_mfma_f32_16x16x32_bf16 v[50:53], v[206:209], v[222:225], v[50:53]
	v_mfma_f32_16x16x32_bf16 v[46:49], v[198:201], v[230:233], v[46:49]
	v_mfma_f32_16x16x32_bf16 v[42:45], v[206:209], v[230:233], v[42:45]
	v_mfma_f32_16x16x32_bf16 v[38:41], v[198:201], v[238:241], v[38:41]
	v_mfma_f32_16x16x32_bf16 v[34:37], v[206:209], v[238:241], v[34:37]
	s_setprio 0
	s_barrier
	s_add_i32 s3, s3, s27
	v_lshl_add_u64 v[162:163], s[0:1], 0, v[4:5]
	s_mov_b32 m0, s3
	s_nop 0
	global_load_lds_dwordx4 v[162:163], off
	ds_read_b128 v[210:213], v143 offset:16384
	ds_read_b128 v[214:217], v143 offset:17408
	s_add_i32 m0, s3, 0x2000
	s_add_u32 s4, s0, 0x80000
	v_lshl_add_u64 v[166:167], s[0:1], 0, v[130:131]
	s_addc_u32 s5, s1, 0
	s_add_i32 s3, s6, s27
	global_load_lds_dwordx4 v[166:167], off
	ds_read_b128 v[218:221], v143 offset:18432
	ds_read_b128 v[222:225], v143 offset:19456
	v_lshl_add_u64 v[176:177], s[4:5], 0, v[4:5]
	s_mov_b32 m0, s3
	v_lshl_add_u64 v[180:181], s[14:15], 0, v[132:133]
	global_load_lds_dwordx4 v[176:177], off
	ds_read_b128 v[226:229], v143 offset:20480
	ds_read_b128 v[230:233], v143 offset:21504
	v_lshl_add_u64 v[176:177], s[4:5], 0, v[130:131]
	s_add_i32 m0, s3, 0x2000
	s_nop 0
	global_load_lds_dwordx4 v[176:177], off
	ds_read_b128 v[234:237], v143 offset:22528
	ds_read_b128 v[238:241], v143 offset:23552
	v_lshl_add_u64 v[176:177], s[14:15], 0, v[134:135]
	s_mov_b32 m0, s30
	s_nop 0
	global_load_lds_dwordx4 v[176:177], off
	s_mov_b32 m0, s31
	s_nop 0
	global_load_lds_dwordx4 v[180:181], off
	s_waitcnt vmcnt(24)
	s_waitcnt lgkmcnt(0)
	s_barrier
	s_setprio 1
	s_waitcnt lgkmcnt(0)
	v_mfma_f32_16x16x32_bf16 v[94:97], v[144:147], v[210:213], v[94:97]
	v_mfma_f32_16x16x32_bf16 v[90:93], v[172:175], v[210:213], v[90:93]
	v_mfma_f32_16x16x32_bf16 v[86:89], v[144:147], v[218:221], v[86:89]
	v_mfma_f32_16x16x32_bf16 v[82:85], v[172:175], v[218:221], v[82:85]
	v_mfma_f32_16x16x32_bf16 v[78:81], v[144:147], v[226:229], v[78:81]
	v_mfma_f32_16x16x32_bf16 v[74:77], v[172:175], v[226:229], v[74:77]
	v_mfma_f32_16x16x32_bf16 v[62:65], v[144:147], v[234:237], v[62:65]
	v_mfma_f32_16x16x32_bf16 v[58:61], v[172:175], v[234:237], v[58:61]
	v_mfma_f32_16x16x32_bf16 v[94:97], v[148:151], v[214:217], v[94:97]
	v_mfma_f32_16x16x32_bf16 v[90:93], v[190:193], v[214:217], v[90:93]
	v_mfma_f32_16x16x32_bf16 v[86:89], v[148:151], v[222:225], v[86:89]
	v_mfma_f32_16x16x32_bf16 v[82:85], v[190:193], v[222:225], v[82:85]
	v_mfma_f32_16x16x32_bf16 v[78:81], v[148:151], v[230:233], v[78:81]
	v_mfma_f32_16x16x32_bf16 v[74:77], v[190:193], v[230:233], v[74:77]
	v_mfma_f32_16x16x32_bf16 v[62:65], v[148:151], v[238:241], v[62:65]
	v_mfma_f32_16x16x32_bf16 v[58:61], v[190:193], v[238:241], v[58:61]
	s_setprio 0
	s_setprio 1
	v_mfma_f32_16x16x32_bf16 v[30:33], v[194:197], v[210:213], v[30:33]
	v_mfma_f32_16x16x32_bf16 v[26:29], v[202:205], v[210:213], v[26:29]
	v_mfma_f32_16x16x32_bf16 v[22:25], v[194:197], v[218:221], v[22:25]
	v_mfma_f32_16x16x32_bf16 v[18:21], v[202:205], v[218:221], v[18:21]
	v_mfma_f32_16x16x32_bf16 v[14:17], v[194:197], v[226:229], v[14:17]
	v_mfma_f32_16x16x32_bf16 v[10:13], v[202:205], v[226:229], v[10:13]
	v_mfma_f32_16x16x32_bf16 v[6:9], v[194:197], v[234:237], v[6:9]
	v_mfma_f32_16x16x32_bf16 v[0:3], v[202:205], v[234:237], v[0:3]
	v_mfma_f32_16x16x32_bf16 v[30:33], v[198:201], v[214:217], v[30:33]
	v_mfma_f32_16x16x32_bf16 v[26:29], v[206:209], v[214:217], v[26:29]
	v_mfma_f32_16x16x32_bf16 v[22:25], v[198:201], v[222:225], v[22:25]
	v_mfma_f32_16x16x32_bf16 v[18:21], v[206:209], v[222:225], v[18:21]
	v_mfma_f32_16x16x32_bf16 v[14:17], v[198:201], v[230:233], v[14:17]
	v_mfma_f32_16x16x32_bf16 v[10:13], v[206:209], v[230:233], v[10:13]
	v_mfma_f32_16x16x32_bf16 v[6:9], v[198:201], v[238:241], v[6:9]
	v_mfma_f32_16x16x32_bf16 v[0:3], v[206:209], v[238:241], v[0:3]
	s_setprio 0
	s_barrier
	s_branch .Lpeelmid_124
.LBB0_124:
	v_lshl_add_u64 v[162:163], s[22:23], 0, v[136:137]
	s_add_i32 m0, s30, 0xc000
	s_nop 0
	global_load_lds_dwordx4 v[162:163], off
	s_add_u32 s0, s22, 0xfff80080
	s_addc_u32 s1, s23, -1
	s_add_i32 s3, 0, 0x10000
	s_cmp_eq_u32 s28, 28
	s_cselect_b32 s15, s2, s1
	s_cselect_b32 s14, s8, s0
	v_add_u32_e32 v162, s3, v141
	s_cselect_b32 s1, s10, s25
	s_cselect_b32 s0, s24, s9
	s_add_i32 s6, 0, 0x14000
	ds_read_b128 v[144:147], v162
	ds_read_b128 v[148:151], v162 offset:1024
	ds_read_b128 v[172:175], v162 offset:2048
	ds_read_b128 v[190:193], v162 offset:3072
	v_add_u32_e32 v162, s6, v141
	ds_read_b128 v[194:197], v162
	ds_read_b128 v[198:201], v162 offset:1024
	ds_read_b128 v[202:205], v162 offset:2048
	ds_read_b128 v[206:209], v162 offset:3072
	ds_read_b128 v[210:213], v143
	ds_read_b128 v[214:217], v143 offset:1024
	ds_read_b128 v[218:221], v143 offset:2048
	ds_read_b128 v[222:225], v143 offset:3072
	ds_read_b128 v[226:229], v143 offset:4096
	ds_read_b128 v[230:233], v143 offset:5120
	ds_read_b128 v[234:237], v143 offset:6144
	ds_read_b128 v[238:241], v143 offset:7168
	v_lshl_add_u64 v[162:163], s[22:23], 0, v[138:139]
	s_add_i32 m0, s30, 0xe000
	s_nop 0
	global_load_lds_dwordx4 v[162:163], off
	s_waitcnt vmcnt(8)
	s_waitcnt lgkmcnt(0)
	s_barrier
	s_setprio 1
	s_waitcnt lgkmcnt(0)
	v_mfma_f32_16x16x32_bf16 v[126:129], v[144:147], v[210:213], v[126:129]
	v_mfma_f32_16x16x32_bf16 v[122:125], v[172:175], v[210:213], v[122:125]
	v_mfma_f32_16x16x32_bf16 v[118:121], v[144:147], v[218:221], v[118:121]
	v_mfma_f32_16x16x32_bf16 v[114:117], v[172:175], v[218:221], v[114:117]
	v_mfma_f32_16x16x32_bf16 v[110:113], v[144:147], v[226:229], v[110:113]
	v_mfma_f32_16x16x32_bf16 v[106:109], v[172:175], v[226:229], v[106:109]
	v_mfma_f32_16x16x32_bf16 v[102:105], v[144:147], v[234:237], v[102:105]
	v_mfma_f32_16x16x32_bf16 v[98:101], v[172:175], v[234:237], v[98:101]
	v_mfma_f32_16x16x32_bf16 v[126:129], v[148:151], v[214:217], v[126:129]
	v_mfma_f32_16x16x32_bf16 v[122:125], v[190:193], v[214:217], v[122:125]
	v_mfma_f32_16x16x32_bf16 v[118:121], v[148:151], v[222:225], v[118:121]
	v_mfma_f32_16x16x32_bf16 v[114:117], v[190:193], v[222:225], v[114:117]
	v_mfma_f32_16x16x32_bf16 v[110:113], v[148:151], v[230:233], v[110:113]
	v_mfma_f32_16x16x32_bf16 v[106:109], v[190:193], v[230:233], v[106:109]
	v_mfma_f32_16x16x32_bf16 v[102:105], v[148:151], v[238:241], v[102:105]
	v_mfma_f32_16x16x32_bf16 v[98:101], v[190:193], v[238:241], v[98:101]
	s_setprio 0
	s_setprio 1
	v_mfma_f32_16x16x32_bf16 v[70:73], v[194:197], v[210:213], v[70:73]
	v_mfma_f32_16x16x32_bf16 v[66:69], v[202:205], v[210:213], v[66:69]
	v_mfma_f32_16x16x32_bf16 v[54:57], v[194:197], v[218:221], v[54:57]
	v_mfma_f32_16x16x32_bf16 v[50:53], v[202:205], v[218:221], v[50:53]
	v_mfma_f32_16x16x32_bf16 v[46:49], v[194:197], v[226:229], v[46:49]
	v_mfma_f32_16x16x32_bf16 v[42:45], v[202:205], v[226:229], v[42:45]
	v_mfma_f32_16x16x32_bf16 v[38:41], v[194:197], v[234:237], v[38:41]
	v_mfma_f32_16x16x32_bf16 v[34:37], v[202:205], v[234:237], v[34:37]
	v_mfma_f32_16x16x32_bf16 v[70:73], v[198:201], v[214:217], v[70:73]
	v_mfma_f32_16x16x32_bf16 v[66:69], v[206:209], v[214:217], v[66:69]
	v_mfma_f32_16x16x32_bf16 v[54:57], v[198:201], v[222:225], v[54:57]
	v_mfma_f32_16x16x32_bf16 v[50:53], v[206:209], v[222:225], v[50:53]
	v_mfma_f32_16x16x32_bf16 v[46:49], v[198:201], v[230:233], v[46:49]
	v_mfma_f32_16x16x32_bf16 v[42:45], v[206:209], v[230:233], v[42:45]
	v_mfma_f32_16x16x32_bf16 v[38:41], v[198:201], v[238:241], v[38:41]
	v_mfma_f32_16x16x32_bf16 v[34:37], v[206:209], v[238:241], v[34:37]
	s_setprio 0
	s_barrier
	s_add_i32 s3, s3, s27
	v_lshl_add_u64 v[162:163], s[0:1], 0, v[4:5]
	s_mov_b32 m0, s3
	s_nop 0
	global_load_lds_dwordx4 v[162:163], off
	ds_read_b128 v[210:213], v143 offset:16384
	ds_read_b128 v[214:217], v143 offset:17408
	s_add_i32 m0, s3, 0x2000
	s_add_u32 s4, s0, 0x80000
	v_lshl_add_u64 v[166:167], s[0:1], 0, v[130:131]
	s_addc_u32 s5, s1, 0
	s_add_i32 s3, s6, s27
	global_load_lds_dwordx4 v[166:167], off
	ds_read_b128 v[218:221], v143 offset:18432
	ds_read_b128 v[222:225], v143 offset:19456
	v_lshl_add_u64 v[176:177], s[4:5], 0, v[4:5]
	s_mov_b32 m0, s3
	v_lshl_add_u64 v[180:181], s[14:15], 0, v[132:133]
	global_load_lds_dwordx4 v[176:177], off
	ds_read_b128 v[226:229], v143 offset:20480
	ds_read_b128 v[230:233], v143 offset:21504
	v_lshl_add_u64 v[176:177], s[4:5], 0, v[130:131]
	s_add_i32 m0, s3, 0x2000
	s_nop 0
	global_load_lds_dwordx4 v[176:177], off
	ds_read_b128 v[234:237], v143 offset:22528
	ds_read_b128 v[238:241], v143 offset:23552
	v_lshl_add_u64 v[176:177], s[14:15], 0, v[134:135]
	s_mov_b32 m0, s30
	s_nop 0
	global_load_lds_dwordx4 v[176:177], off
	s_mov_b32 m0, s31
	s_nop 0
	global_load_lds_dwordx4 v[180:181], off
	s_waitcnt vmcnt(8)
	s_waitcnt lgkmcnt(0)
	s_barrier
	s_setprio 1
	s_waitcnt lgkmcnt(0)
	v_mfma_f32_16x16x32_bf16 v[94:97], v[144:147], v[210:213], v[94:97]
	v_mfma_f32_16x16x32_bf16 v[90:93], v[172:175], v[210:213], v[90:93]
	v_mfma_f32_16x16x32_bf16 v[86:89], v[144:147], v[218:221], v[86:89]
	v_mfma_f32_16x16x32_bf16 v[82:85], v[172:175], v[218:221], v[82:85]
	v_mfma_f32_16x16x32_bf16 v[78:81], v[144:147], v[226:229], v[78:81]
	v_mfma_f32_16x16x32_bf16 v[74:77], v[172:175], v[226:229], v[74:77]
	v_mfma_f32_16x16x32_bf16 v[62:65], v[144:147], v[234:237], v[62:65]
	v_mfma_f32_16x16x32_bf16 v[58:61], v[172:175], v[234:237], v[58:61]
	v_mfma_f32_16x16x32_bf16 v[94:97], v[148:151], v[214:217], v[94:97]
	v_mfma_f32_16x16x32_bf16 v[90:93], v[190:193], v[214:217], v[90:93]
	v_mfma_f32_16x16x32_bf16 v[86:89], v[148:151], v[222:225], v[86:89]
	v_mfma_f32_16x16x32_bf16 v[82:85], v[190:193], v[222:225], v[82:85]
	v_mfma_f32_16x16x32_bf16 v[78:81], v[148:151], v[230:233], v[78:81]
	v_mfma_f32_16x16x32_bf16 v[74:77], v[190:193], v[230:233], v[74:77]
	v_mfma_f32_16x16x32_bf16 v[62:65], v[148:151], v[238:241], v[62:65]
	v_mfma_f32_16x16x32_bf16 v[58:61], v[190:193], v[238:241], v[58:61]
	s_setprio 0
	s_setprio 1
	v_mfma_f32_16x16x32_bf16 v[30:33], v[194:197], v[210:213], v[30:33]
	v_mfma_f32_16x16x32_bf16 v[26:29], v[202:205], v[210:213], v[26:29]
	v_mfma_f32_16x16x32_bf16 v[22:25], v[194:197], v[218:221], v[22:25]
	v_mfma_f32_16x16x32_bf16 v[18:21], v[202:205], v[218:221], v[18:21]
	v_mfma_f32_16x16x32_bf16 v[14:17], v[194:197], v[226:229], v[14:17]
	v_mfma_f32_16x16x32_bf16 v[10:13], v[202:205], v[226:229], v[10:13]
	v_mfma_f32_16x16x32_bf16 v[6:9], v[194:197], v[234:237], v[6:9]
	v_mfma_f32_16x16x32_bf16 v[0:3], v[202:205], v[234:237], v[0:3]
	v_mfma_f32_16x16x32_bf16 v[30:33], v[198:201], v[214:217], v[30:33]
	v_mfma_f32_16x16x32_bf16 v[26:29], v[206:209], v[214:217], v[26:29]
	v_mfma_f32_16x16x32_bf16 v[22:25], v[198:201], v[222:225], v[22:25]
	v_mfma_f32_16x16x32_bf16 v[18:21], v[206:209], v[222:225], v[18:21]
	v_mfma_f32_16x16x32_bf16 v[14:17], v[198:201], v[230:233], v[14:17]
	v_mfma_f32_16x16x32_bf16 v[10:13], v[206:209], v[230:233], v[10:13]
	v_mfma_f32_16x16x32_bf16 v[6:9], v[198:201], v[238:241], v[6:9]
	v_mfma_f32_16x16x32_bf16 v[0:3], v[206:209], v[238:241], v[0:3]
	s_setprio 0
	s_barrier
.Lpeelmid_124:
	s_add_u32 s4, s14, 0x80000
	s_addc_u32 s5, s15, 0
	s_mov_b32 m0, s34
	v_lshl_add_u64 v[242:243], s[4:5], 0, v[134:135]
	global_load_lds_dwordx4 v[242:243], off
	s_add_i32 s3, 0, 0x18000
	v_add_u32_e32 v164, s3, v141
	s_add_i32 s6, 0, 0x1c000
	ds_read_b128 v[144:147], v164
	ds_read_b128 v[148:151], v164 offset:1024
	ds_read_b128 v[172:175], v164 offset:2048
	ds_read_b128 v[190:193], v164 offset:3072
	v_add_u32_e32 v164, s6, v141
	ds_read_b128 v[194:197], v164
	ds_read_b128 v[198:201], v164 offset:1024
	ds_read_b128 v[202:205], v164 offset:2048
	ds_read_b128 v[206:209], v164 offset:3072
	ds_read_b128 v[210:213], v143 offset:32768
	ds_read_b128 v[214:217], v143 offset:33792
	ds_read_b128 v[218:221], v143 offset:34816
	ds_read_b128 v[222:225], v143 offset:35840
	ds_read_b128 v[226:229], v143 offset:36864
	ds_read_b128 v[230:233], v143 offset:37888
	ds_read_b128 v[234:237], v143 offset:38912
	ds_read_b128 v[238:241], v143 offset:39936
	v_lshl_add_u64 v[242:243], s[4:5], 0, v[132:133]
	s_mov_b32 m0, s35
	s_nop 0
	global_load_lds_dwordx4 v[242:243], off
	s_waitcnt vmcnt(8)
	s_waitcnt lgkmcnt(0)
	s_barrier
	s_setprio 1
	s_waitcnt lgkmcnt(0)
	v_mfma_f32_16x16x32_bf16 v[126:129], v[144:147], v[210:213], v[126:129]
	v_mfma_f32_16x16x32_bf16 v[122:125], v[172:175], v[210:213], v[122:125]
	v_mfma_f32_16x16x32_bf16 v[118:121], v[144:147], v[218:221], v[118:121]
	v_mfma_f32_16x16x32_bf16 v[114:117], v[172:175], v[218:221], v[114:117]
	v_mfma_f32_16x16x32_bf16 v[110:113], v[144:147], v[226:229], v[110:113]
	v_mfma_f32_16x16x32_bf16 v[106:109], v[172:175], v[226:229], v[106:109]
	v_mfma_f32_16x16x32_bf16 v[102:105], v[144:147], v[234:237], v[102:105]
	v_mfma_f32_16x16x32_bf16 v[98:101], v[172:175], v[234:237], v[98:101]
	v_mfma_f32_16x16x32_bf16 v[126:129], v[148:151], v[214:217], v[126:129]
	v_mfma_f32_16x16x32_bf16 v[122:125], v[190:193], v[214:217], v[122:125]
	v_mfma_f32_16x16x32_bf16 v[118:121], v[148:151], v[222:225], v[118:121]
	v_mfma_f32_16x16x32_bf16 v[114:117], v[190:193], v[222:225], v[114:117]
	v_mfma_f32_16x16x32_bf16 v[110:113], v[148:151], v[230:233], v[110:113]
	v_mfma_f32_16x16x32_bf16 v[106:109], v[190:193], v[230:233], v[106:109]
	v_mfma_f32_16x16x32_bf16 v[102:105], v[148:151], v[238:241], v[102:105]
	v_mfma_f32_16x16x32_bf16 v[98:101], v[190:193], v[238:241], v[98:101]
	s_setprio 0
	s_setprio 1
	v_mfma_f32_16x16x32_bf16 v[70:73], v[194:197], v[210:213], v[70:73]
	v_mfma_f32_16x16x32_bf16 v[66:69], v[202:205], v[210:213], v[66:69]
	v_mfma_f32_16x16x32_bf16 v[54:57], v[194:197], v[218:221], v[54:57]
	v_mfma_f32_16x16x32_bf16 v[50:53], v[202:205], v[218:221], v[50:53]
	v_mfma_f32_16x16x32_bf16 v[46:49], v[194:197], v[226:229], v[46:49]
	v_mfma_f32_16x16x32_bf16 v[42:45], v[202:205], v[226:229], v[42:45]
	v_mfma_f32_16x16x32_bf16 v[38:41], v[194:197], v[234:237], v[38:41]
	v_mfma_f32_16x16x32_bf16 v[34:37], v[202:205], v[234:237], v[34:37]
	v_mfma_f32_16x16x32_bf16 v[70:73], v[198:201], v[214:217], v[70:73]
	v_mfma_f32_16x16x32_bf16 v[66:69], v[206:209], v[214:217], v[66:69]
	v_mfma_f32_16x16x32_bf16 v[54:57], v[198:201], v[222:225], v[54:57]
	v_mfma_f32_16x16x32_bf16 v[50:53], v[206:209], v[222:225], v[50:53]
	v_mfma_f32_16x16x32_bf16 v[46:49], v[198:201], v[230:233], v[46:49]
	v_mfma_f32_16x16x32_bf16 v[42:45], v[206:209], v[230:233], v[42:45]
	v_mfma_f32_16x16x32_bf16 v[38:41], v[198:201], v[238:241], v[38:41]
	v_mfma_f32_16x16x32_bf16 v[34:37], v[206:209], v[238:241], v[34:37]
	s_setprio 0
	s_barrier
	s_add_i32 s3, s3, s27
	v_lshl_add_u64 v[162:163], v[162:163], 0, s[70:71]
	s_mov_b32 m0, s3
	s_nop 0
	global_load_lds_dwordx4 v[162:163], off
	ds_read_b128 v[210:213], v143 offset:49152
	ds_read_b128 v[214:217], v143 offset:50176
	s_add_i32 m0, s3, 0x2000
	s_add_u32 s0, s0, 0x80080
	v_lshl_add_u64 v[162:163], v[166:167], 0, s[70:71]
	s_addc_u32 s1, s1, 0
	s_add_i32 s3, s6, s27
	global_load_lds_dwordx4 v[162:163], off
	ds_read_b128 v[218:221], v143 offset:51200
	ds_read_b128 v[222:225], v143 offset:52224
	v_lshl_add_u64 v[162:163], s[0:1], 0, v[4:5]
	s_mov_b32 m0, s3
	s_nop 0
	global_load_lds_dwordx4 v[162:163], off
	ds_read_b128 v[226:229], v143 offset:53248
	ds_read_b128 v[230:233], v143 offset:54272
	v_lshl_add_u64 v[162:163], s[0:1], 0, v[130:131]
	s_add_i32 m0, s3, 0x2000
	s_nop 0
	global_load_lds_dwordx4 v[162:163], off
	ds_read_b128 v[234:237], v143 offset:55296
	ds_read_b128 v[238:241], v143 offset:56320
	v_lshl_add_u64 v[162:163], v[176:177], 0, s[70:71]
	s_mov_b32 m0, s36
	s_nop 0
	global_load_lds_dwordx4 v[162:163], off
	v_lshl_add_u64 v[162:163], v[180:181], 0, s[70:71]
	s_mov_b32 m0, s37
	s_nop 0
	global_load_lds_dwordx4 v[162:163], off
	s_waitcnt vmcnt(8)
	s_waitcnt lgkmcnt(0)
	s_barrier
	s_setprio 1
	s_waitcnt lgkmcnt(0)
	v_mfma_f32_16x16x32_bf16 v[94:97], v[144:147], v[210:213], v[94:97]
	v_mfma_f32_16x16x32_bf16 v[90:93], v[172:175], v[210:213], v[90:93]
	v_mfma_f32_16x16x32_bf16 v[86:89], v[144:147], v[218:221], v[86:89]
	v_mfma_f32_16x16x32_bf16 v[82:85], v[172:175], v[218:221], v[82:85]
	v_mfma_f32_16x16x32_bf16 v[78:81], v[144:147], v[226:229], v[78:81]
	v_mfma_f32_16x16x32_bf16 v[74:77], v[172:175], v[226:229], v[74:77]
	v_mfma_f32_16x16x32_bf16 v[62:65], v[144:147], v[234:237], v[62:65]
	v_mfma_f32_16x16x32_bf16 v[58:61], v[172:175], v[234:237], v[58:61]
	v_mfma_f32_16x16x32_bf16 v[94:97], v[148:151], v[214:217], v[94:97]
	v_mfma_f32_16x16x32_bf16 v[90:93], v[190:193], v[214:217], v[90:93]
	v_mfma_f32_16x16x32_bf16 v[86:89], v[148:151], v[222:225], v[86:89]
	v_mfma_f32_16x16x32_bf16 v[82:85], v[190:193], v[222:225], v[82:85]
	v_mfma_f32_16x16x32_bf16 v[78:81], v[148:151], v[230:233], v[78:81]
	v_mfma_f32_16x16x32_bf16 v[74:77], v[190:193], v[230:233], v[74:77]
	v_mfma_f32_16x16x32_bf16 v[62:65], v[148:151], v[238:241], v[62:65]
	v_mfma_f32_16x16x32_bf16 v[58:61], v[190:193], v[238:241], v[58:61]
	s_setprio 0
	s_setprio 1
	v_mfma_f32_16x16x32_bf16 v[30:33], v[194:197], v[210:213], v[30:33]
	v_mfma_f32_16x16x32_bf16 v[26:29], v[202:205], v[210:213], v[26:29]
	v_mfma_f32_16x16x32_bf16 v[22:25], v[194:197], v[218:221], v[22:25]
	v_mfma_f32_16x16x32_bf16 v[18:21], v[202:205], v[218:221], v[18:21]
	v_mfma_f32_16x16x32_bf16 v[14:17], v[194:197], v[226:229], v[14:17]
	v_mfma_f32_16x16x32_bf16 v[10:13], v[202:205], v[226:229], v[10:13]
	v_mfma_f32_16x16x32_bf16 v[6:9], v[194:197], v[234:237], v[6:9]
	v_mfma_f32_16x16x32_bf16 v[0:3], v[202:205], v[234:237], v[0:3]
	v_mfma_f32_16x16x32_bf16 v[30:33], v[198:201], v[214:217], v[30:33]
	v_mfma_f32_16x16x32_bf16 v[26:29], v[206:209], v[214:217], v[26:29]
	v_mfma_f32_16x16x32_bf16 v[22:25], v[198:201], v[222:225], v[22:25]
	v_mfma_f32_16x16x32_bf16 v[18:21], v[206:209], v[222:225], v[18:21]
	v_mfma_f32_16x16x32_bf16 v[14:17], v[198:201], v[230:233], v[14:17]
	v_mfma_f32_16x16x32_bf16 v[10:13], v[206:209], v[230:233], v[10:13]
	v_mfma_f32_16x16x32_bf16 v[6:9], v[198:201], v[238:241], v[6:9]
	v_mfma_f32_16x16x32_bf16 v[0:3], v[206:209], v[238:241], v[0:3]
	s_setprio 0
	s_barrier
	s_add_i32 s28, s28, 2
	s_add_u32 s22, s22, 0x100
	s_addc_u32 s23, s23, 0
	s_add_u32 s9, s9, 0x100
	s_addc_u32 s25, s25, 0
	s_cmp_gt_u32 s28, 29
	s_cbranch_scc0 .LBB0_124
	s_and_b64 vcc, exec, s[42:43]
	s_cbranch_vccz .LBB0_127
	s_barrier

.LBB0_162:
	s_ashr_i32 s49, s48, 31
	s_lshl_b64 s[2:3], s[48:49], 20
	v_readlane_b32 s4, v253, 61
	v_readlane_b32 s5, v253, 62
	s_add_u32 s82, s4, s2
	s_addc_u32 s83, s5, s3
	s_and_b64 s[2:3], s[42:43], exec
	s_cselect_b32 s2, s83, s1
	s_cselect_b32 s8, s82, s0
	s_add_u32 s22, s14, 0x80080
	s_addc_u32 s23, s15, 0
	s_add_u32 s9, s0, 0x100
	v_mov_b32_e32 v0, 0
	s_addc_u32 s10, s1, 0
	s_mov_b32 s24, -2
	v_mov_b32_e32 v1, v0
	v_mov_b32_e32 v2, v0
	v_mov_b32_e32 v3, v0
	v_mov_b32_e32 v6, v0
	s_waitcnt lgkmcnt(0)
	v_mov_b32_e32 v7, v0
	v_mov_b32_e32 v8, v0
	v_mov_b32_e32 v9, v0
	v_mov_b32_e32 v18, v0
	v_mov_b32_e32 v19, v0
	v_mov_b32_e32 v20, v0
	v_mov_b32_e32 v21, v0
	v_mov_b32_e32 v22, v0
	v_mov_b32_e32 v23, v0
	v_mov_b32_e32 v24, v0
	v_mov_b32_e32 v25, v0
	v_mov_b32_e32 v34, v0
	v_mov_b32_e32 v35, v0
	v_mov_b32_e32 v36, v0
	v_mov_b32_e32 v37, v0
	v_mov_b32_e32 v38, v0
	v_mov_b32_e32 v39, v0
	v_mov_b32_e32 v40, v0
	v_mov_b32_e32 v41, v0
	v_mov_b32_e32 v50, v0
	v_mov_b32_e32 v51, v0
	v_mov_b32_e32 v52, v0
	v_mov_b32_e32 v53, v0
	v_mov_b32_e32 v54, v0
	v_mov_b32_e32 v55, v0
	v_mov_b32_e32 v56, v0
	v_mov_b32_e32 v57, v0
	v_mov_b32_e32 v10, v0
	v_mov_b32_e32 v11, v0
	v_mov_b32_e32 v12, v0
	v_mov_b32_e32 v13, v0
	v_mov_b32_e32 v14, v0
	v_mov_b32_e32 v15, v0
	v_mov_b32_e32 v16, v0
	v_mov_b32_e32 v17, v0
	v_mov_b32_e32 v26, v0
	v_mov_b32_e32 v27, v0
	v_mov_b32_e32 v28, v0
	v_mov_b32_e32 v29, v0
	v_mov_b32_e32 v30, v0
	v_mov_b32_e32 v31, v0
	v_mov_b32_e32 v32, v0
	v_mov_b32_e32 v33, v0
	v_mov_b32_e32 v42, v0
	v_mov_b32_e32 v43, v0
	v_mov_b32_e32 v44, v0
	v_mov_b32_e32 v45, v0
	v_mov_b32_e32 v46, v0
	v_mov_b32_e32 v47, v0
	v_mov_b32_e32 v48, v0
	v_mov_b32_e32 v49, v0
	v_mov_b32_e32 v58, v0
	v_mov_b32_e32 v59, v0
	v_mov_b32_e32 v60, v0
	v_mov_b32_e32 v61, v0
	v_mov_b32_e32 v62, v0
	v_mov_b32_e32 v63, v0
	v_mov_b32_e32 v64, v0
	v_mov_b32_e32 v65, v0
	v_mov_b32_e32 v66, v0
	v_mov_b32_e32 v67, v0
	v_mov_b32_e32 v68, v0
	v_mov_b32_e32 v69, v0
	v_mov_b32_e32 v70, v0
	v_mov_b32_e32 v71, v0
	v_mov_b32_e32 v72, v0
	v_mov_b32_e32 v73, v0
	v_mov_b32_e32 v82, v0
	v_mov_b32_e32 v83, v0
	v_mov_b32_e32 v84, v0
	v_mov_b32_e32 v85, v0
	v_mov_b32_e32 v86, v0
	v_mov_b32_e32 v87, v0
	v_mov_b32_e32 v88, v0
	v_mov_b32_e32 v89, v0
	v_mov_b32_e32 v98, v0
	v_mov_b32_e32 v99, v0
	v_mov_b32_e32 v100, v0
	v_mov_b32_e32 v101, v0
	v_mov_b32_e32 v102, v0
	v_mov_b32_e32 v103, v0
	v_mov_b32_e32 v104, v0
	v_mov_b32_e32 v105, v0
	v_mov_b32_e32 v114, v0
	v_mov_b32_e32 v115, v0
	v_mov_b32_e32 v116, v0
	v_mov_b32_e32 v117, v0
	v_mov_b32_e32 v118, v0
	v_mov_b32_e32 v119, v0
	v_mov_b32_e32 v120, v0
	v_mov_b32_e32 v121, v0
	v_mov_b32_e32 v74, v0
	v_mov_b32_e32 v75, v0
	v_mov_b32_e32 v76, v0
	v_mov_b32_e32 v77, v0
	v_mov_b32_e32 v78, v0
	v_mov_b32_e32 v79, v0
	v_mov_b32_e32 v80, v0
	v_mov_b32_e32 v81, v0
	v_mov_b32_e32 v90, v0
	v_mov_b32_e32 v91, v0
	v_mov_b32_e32 v92, v0
	v_mov_b32_e32 v93, v0
	v_mov_b32_e32 v94, v0
	v_mov_b32_e32 v95, v0
	v_mov_b32_e32 v96, v0
	v_mov_b32_e32 v97, v0
	v_mov_b32_e32 v106, v0
	v_mov_b32_e32 v107, v0
	v_mov_b32_e32 v108, v0
	v_mov_b32_e32 v109, v0
	v_mov_b32_e32 v110, v0
	v_mov_b32_e32 v111, v0
	v_mov_b32_e32 v112, v0
	v_mov_b32_e32 v113, v0
	v_mov_b32_e32 v122, v0
	v_mov_b32_e32 v123, v0
	v_mov_b32_e32 v124, v0
	v_mov_b32_e32 v125, v0
	v_mov_b32_e32 v126, v0
	v_mov_b32_e32 v127, v0
	v_mov_b32_e32 v128, v0
	v_mov_b32_e32 v129, v0
	s_cmp_eq_u32 s37, 1
	s_cbranch_scc1 .LBB0_163
	v_lshl_add_u64 v[162:163], s[22:23], 0, v[136:137]
	s_add_i32 m0, s26, 0xc000
	s_nop 0
	global_load_lds_dwordx4 v[162:163], off
	s_add_u32 s0, s22, 0xfff80080
	s_addc_u32 s1, s23, -1
	s_add_i32 s3, 0, 0x10000
	s_cmp_eq_u32 s24, 28
	s_cselect_b32 s15, s79, s1
	s_cselect_b32 s14, s78, s0
	v_add_u32_e32 v162, s3, v145
	s_cselect_b32 s1, s2, s10
	s_cselect_b32 s0, s8, s9
	s_add_i32 s6, 0, 0x14000
	ds_read_b128 v[140:143], v162
	ds_read_b128 v[148:151], v162 offset:1024
	ds_read_b128 v[172:175], v162 offset:2048
	ds_read_b128 v[190:193], v162 offset:3072
	v_add_u32_e32 v162, s6, v145
	ds_read_b128 v[194:197], v162
	ds_read_b128 v[198:201], v162 offset:1024
	ds_read_b128 v[202:205], v162 offset:2048
	ds_read_b128 v[206:209], v162 offset:3072
	ds_read_b128 v[210:213], v147
	ds_read_b128 v[214:217], v147 offset:1024
	ds_read_b128 v[218:221], v147 offset:2048
	ds_read_b128 v[222:225], v147 offset:3072
	ds_read_b128 v[226:229], v147 offset:4096
	ds_read_b128 v[230:233], v147 offset:5120
	ds_read_b128 v[234:237], v147 offset:6144
	ds_read_b128 v[238:241], v147 offset:7168
	v_lshl_add_u64 v[162:163], s[22:23], 0, v[138:139]
	s_add_i32 m0, s26, 0xe000
	s_nop 0
	global_load_lds_dwordx4 v[162:163], off
	s_waitcnt vmcnt(24)
	s_waitcnt lgkmcnt(0)
	s_barrier
	s_setprio 1
	s_waitcnt lgkmcnt(0)
	v_mfma_f32_16x16x32_bf16 v[126:129], v[140:143], v[210:213], v[126:129]
	v_mfma_f32_16x16x32_bf16 v[122:125], v[172:175], v[210:213], v[122:125]
	v_mfma_f32_16x16x32_bf16 v[110:113], v[140:143], v[218:221], v[110:113]
	v_mfma_f32_16x16x32_bf16 v[106:109], v[172:175], v[218:221], v[106:109]
	v_mfma_f32_16x16x32_bf16 v[94:97], v[140:143], v[226:229], v[94:97]
	v_mfma_f32_16x16x32_bf16 v[90:93], v[172:175], v[226:229], v[90:93]
	v_mfma_f32_16x16x32_bf16 v[78:81], v[140:143], v[234:237], v[78:81]
	v_mfma_f32_16x16x32_bf16 v[74:77], v[172:175], v[234:237], v[74:77]
	v_mfma_f32_16x16x32_bf16 v[126:129], v[148:151], v[214:217], v[126:129]
	v_mfma_f32_16x16x32_bf16 v[122:125], v[190:193], v[214:217], v[122:125]
	v_mfma_f32_16x16x32_bf16 v[110:113], v[148:151], v[222:225], v[110:113]
	v_mfma_f32_16x16x32_bf16 v[106:109], v[190:193], v[222:225], v[106:109]
	v_mfma_f32_16x16x32_bf16 v[94:97], v[148:151], v[230:233], v[94:97]
	v_mfma_f32_16x16x32_bf16 v[90:93], v[190:193], v[230:233], v[90:93]
	v_mfma_f32_16x16x32_bf16 v[78:81], v[148:151], v[238:241], v[78:81]
	v_mfma_f32_16x16x32_bf16 v[74:77], v[190:193], v[238:241], v[74:77]
	s_setprio 0
	s_setprio 1
	v_mfma_f32_16x16x32_bf16 v[118:121], v[194:197], v[210:213], v[118:121]
	v_mfma_f32_16x16x32_bf16 v[114:117], v[202:205], v[210:213], v[114:117]
	v_mfma_f32_16x16x32_bf16 v[102:105], v[194:197], v[218:221], v[102:105]
	v_mfma_f32_16x16x32_bf16 v[98:101], v[202:205], v[218:221], v[98:101]
	v_mfma_f32_16x16x32_bf16 v[86:89], v[194:197], v[226:229], v[86:89]
	v_mfma_f32_16x16x32_bf16 v[82:85], v[202:205], v[226:229], v[82:85]
	v_mfma_f32_16x16x32_bf16 v[70:73], v[194:197], v[234:237], v[70:73]
	v_mfma_f32_16x16x32_bf16 v[66:69], v[202:205], v[234:237], v[66:69]
	v_mfma_f32_16x16x32_bf16 v[118:121], v[198:201], v[214:217], v[118:121]
	v_mfma_f32_16x16x32_bf16 v[114:117], v[206:209], v[214:217], v[114:117]
	v_mfma_f32_16x16x32_bf16 v[102:105], v[198:201], v[222:225], v[102:105]
	v_mfma_f32_16x16x32_bf16 v[98:101], v[206:209], v[222:225], v[98:101]
	v_mfma_f32_16x16x32_bf16 v[86:89], v[198:201], v[230:233], v[86:89]
	v_mfma_f32_16x16x32_bf16 v[82:85], v[206:209], v[230:233], v[82:85]
	v_mfma_f32_16x16x32_bf16 v[70:73], v[198:201], v[238:241], v[70:73]
	v_mfma_f32_16x16x32_bf16 v[66:69], v[206:209], v[238:241], v[66:69]
	s_setprio 0
	s_barrier
	s_add_i32 s3, s3, s11
	v_lshl_add_u64 v[162:163], s[0:1], 0, v[4:5]
	s_mov_b32 m0, s3
	s_nop 0
	global_load_lds_dwordx4 v[162:163], off
	ds_read_b128 v[210:213], v147 offset:16384
	ds_read_b128 v[214:217], v147 offset:17408
	s_add_i32 m0, s3, 0x2000
	s_add_u32 s4, s0, 0x80000
	v_lshl_add_u64 v[166:167], s[0:1], 0, v[130:131]
	s_addc_u32 s5, s1, 0
	s_add_i32 s3, s6, s11
	global_load_lds_dwordx4 v[166:167], off
	ds_read_b128 v[218:221], v147 offset:18432
	ds_read_b128 v[222:225], v147 offset:19456
	v_lshl_add_u64 v[176:177], s[4:5], 0, v[4:5]
	s_mov_b32 m0, s3
	v_lshl_add_u64 v[180:181], s[14:15], 0, v[132:133]
	global_load_lds_dwordx4 v[176:177], off
	ds_read_b128 v[226:229], v147 offset:20480
	ds_read_b128 v[230:233], v147 offset:21504
	v_lshl_add_u64 v[176:177], s[4:5], 0, v[130:131]
	s_add_i32 m0, s3, 0x2000
	s_nop 0
	global_load_lds_dwordx4 v[176:177], off
	ds_read_b128 v[234:237], v147 offset:22528
	ds_read_b128 v[238:241], v147 offset:23552
	v_lshl_add_u64 v[176:177], s[14:15], 0, v[134:135]
	s_mov_b32 m0, s26
	s_nop 0
	global_load_lds_dwordx4 v[176:177], off
	s_mov_b32 m0, s27
	s_nop 0
	global_load_lds_dwordx4 v[180:181], off
	s_waitcnt vmcnt(24)
	s_waitcnt lgkmcnt(0)
	s_barrier
	s_setprio 1
	s_waitcnt lgkmcnt(0)
	v_mfma_f32_16x16x32_bf16 v[62:65], v[140:143], v[210:213], v[62:65]
	v_mfma_f32_16x16x32_bf16 v[58:61], v[172:175], v[210:213], v[58:61]
	v_mfma_f32_16x16x32_bf16 v[46:49], v[140:143], v[218:221], v[46:49]
	v_mfma_f32_16x16x32_bf16 v[42:45], v[172:175], v[218:221], v[42:45]
	v_mfma_f32_16x16x32_bf16 v[30:33], v[140:143], v[226:229], v[30:33]
	v_mfma_f32_16x16x32_bf16 v[26:29], v[172:175], v[226:229], v[26:29]
	v_mfma_f32_16x16x32_bf16 v[14:17], v[140:143], v[234:237], v[14:17]
	v_mfma_f32_16x16x32_bf16 v[10:13], v[172:175], v[234:237], v[10:13]
	v_mfma_f32_16x16x32_bf16 v[62:65], v[148:151], v[214:217], v[62:65]
	v_mfma_f32_16x16x32_bf16 v[58:61], v[190:193], v[214:217], v[58:61]
	v_mfma_f32_16x16x32_bf16 v[46:49], v[148:151], v[222:225], v[46:49]
	v_mfma_f32_16x16x32_bf16 v[42:45], v[190:193], v[222:225], v[42:45]
	v_mfma_f32_16x16x32_bf16 v[30:33], v[148:151], v[230:233], v[30:33]
	v_mfma_f32_16x16x32_bf16 v[26:29], v[190:193], v[230:233], v[26:29]
	v_mfma_f32_16x16x32_bf16 v[14:17], v[148:151], v[238:241], v[14:17]
	v_mfma_f32_16x16x32_bf16 v[10:13], v[190:193], v[238:241], v[10:13]
	s_setprio 0
	s_setprio 1
	v_mfma_f32_16x16x32_bf16 v[54:57], v[194:197], v[210:213], v[54:57]
	v_mfma_f32_16x16x32_bf16 v[50:53], v[202:205], v[210:213], v[50:53]
	v_mfma_f32_16x16x32_bf16 v[38:41], v[194:197], v[218:221], v[38:41]
	v_mfma_f32_16x16x32_bf16 v[34:37], v[202:205], v[218:221], v[34:37]
	v_mfma_f32_16x16x32_bf16 v[22:25], v[194:197], v[226:229], v[22:25]
	v_mfma_f32_16x16x32_bf16 v[18:21], v[202:205], v[226:229], v[18:21]
	v_mfma_f32_16x16x32_bf16 v[6:9], v[194:197], v[234:237], v[6:9]
	v_mfma_f32_16x16x32_bf16 v[0:3], v[202:205], v[234:237], v[0:3]
	v_mfma_f32_16x16x32_bf16 v[54:57], v[198:201], v[214:217], v[54:57]
	v_mfma_f32_16x16x32_bf16 v[50:53], v[206:209], v[214:217], v[50:53]
	v_mfma_f32_16x16x32_bf16 v[38:41], v[198:201], v[222:225], v[38:41]
	v_mfma_f32_16x16x32_bf16 v[34:37], v[206:209], v[222:225], v[34:37]
	v_mfma_f32_16x16x32_bf16 v[22:25], v[198:201], v[230:233], v[22:25]
	v_mfma_f32_16x16x32_bf16 v[18:21], v[206:209], v[230:233], v[18:21]
	v_mfma_f32_16x16x32_bf16 v[6:9], v[198:201], v[238:241], v[6:9]
	v_mfma_f32_16x16x32_bf16 v[0:3], v[206:209], v[238:241], v[0:3]
	s_setprio 0
	s_barrier
	s_branch .Lpeelmid_163
.LBB0_163:
	v_lshl_add_u64 v[162:163], s[22:23], 0, v[136:137]
	s_add_i32 m0, s26, 0xc000
	s_nop 0
	global_load_lds_dwordx4 v[162:163], off
	s_add_u32 s0, s22, 0xfff80080
	s_addc_u32 s1, s23, -1
	s_add_i32 s3, 0, 0x10000
	s_cmp_eq_u32 s24, 28
	s_cselect_b32 s15, s79, s1
	s_cselect_b32 s14, s78, s0
	v_add_u32_e32 v162, s3, v145
	s_cselect_b32 s1, s2, s10
	s_cselect_b32 s0, s8, s9
	s_add_i32 s6, 0, 0x14000
	ds_read_b128 v[140:143], v162
	ds_read_b128 v[148:151], v162 offset:1024
	ds_read_b128 v[172:175], v162 offset:2048
	ds_read_b128 v[190:193], v162 offset:3072
	v_add_u32_e32 v162, s6, v145
	ds_read_b128 v[194:197], v162
	ds_read_b128 v[198:201], v162 offset:1024
	ds_read_b128 v[202:205], v162 offset:2048
	ds_read_b128 v[206:209], v162 offset:3072
	ds_read_b128 v[210:213], v147
	ds_read_b128 v[214:217], v147 offset:1024
	ds_read_b128 v[218:221], v147 offset:2048
	ds_read_b128 v[222:225], v147 offset:3072
	ds_read_b128 v[226:229], v147 offset:4096
	ds_read_b128 v[230:233], v147 offset:5120
	ds_read_b128 v[234:237], v147 offset:6144
	ds_read_b128 v[238:241], v147 offset:7168
	v_lshl_add_u64 v[162:163], s[22:23], 0, v[138:139]
	s_add_i32 m0, s26, 0xe000
	s_nop 0
	global_load_lds_dwordx4 v[162:163], off
	s_waitcnt vmcnt(8)
	s_waitcnt lgkmcnt(0)
	s_barrier
	s_setprio 1
	s_waitcnt lgkmcnt(0)
	v_mfma_f32_16x16x32_bf16 v[126:129], v[140:143], v[210:213], v[126:129]
	v_mfma_f32_16x16x32_bf16 v[122:125], v[172:175], v[210:213], v[122:125]
	v_mfma_f32_16x16x32_bf16 v[110:113], v[140:143], v[218:221], v[110:113]
	v_mfma_f32_16x16x32_bf16 v[106:109], v[172:175], v[218:221], v[106:109]
	v_mfma_f32_16x16x32_bf16 v[94:97], v[140:143], v[226:229], v[94:97]
	v_mfma_f32_16x16x32_bf16 v[90:93], v[172:175], v[226:229], v[90:93]
	v_mfma_f32_16x16x32_bf16 v[78:81], v[140:143], v[234:237], v[78:81]
	v_mfma_f32_16x16x32_bf16 v[74:77], v[172:175], v[234:237], v[74:77]
	v_mfma_f32_16x16x32_bf16 v[126:129], v[148:151], v[214:217], v[126:129]
	v_mfma_f32_16x16x32_bf16 v[122:125], v[190:193], v[214:217], v[122:125]
	v_mfma_f32_16x16x32_bf16 v[110:113], v[148:151], v[222:225], v[110:113]
	v_mfma_f32_16x16x32_bf16 v[106:109], v[190:193], v[222:225], v[106:109]
	v_mfma_f32_16x16x32_bf16 v[94:97], v[148:151], v[230:233], v[94:97]
	v_mfma_f32_16x16x32_bf16 v[90:93], v[190:193], v[230:233], v[90:93]
	v_mfma_f32_16x16x32_bf16 v[78:81], v[148:151], v[238:241], v[78:81]
	v_mfma_f32_16x16x32_bf16 v[74:77], v[190:193], v[238:241], v[74:77]
	s_setprio 0
	s_setprio 1
	v_mfma_f32_16x16x32_bf16 v[118:121], v[194:197], v[210:213], v[118:121]
	v_mfma_f32_16x16x32_bf16 v[114:117], v[202:205], v[210:213], v[114:117]
	v_mfma_f32_16x16x32_bf16 v[102:105], v[194:197], v[218:221], v[102:105]
	v_mfma_f32_16x16x32_bf16 v[98:101], v[202:205], v[218:221], v[98:101]
	v_mfma_f32_16x16x32_bf16 v[86:89], v[194:197], v[226:229], v[86:89]
	v_mfma_f32_16x16x32_bf16 v[82:85], v[202:205], v[226:229], v[82:85]
	v_mfma_f32_16x16x32_bf16 v[70:73], v[194:197], v[234:237], v[70:73]
	v_mfma_f32_16x16x32_bf16 v[66:69], v[202:205], v[234:237], v[66:69]
	v_mfma_f32_16x16x32_bf16 v[118:121], v[198:201], v[214:217], v[118:121]
	v_mfma_f32_16x16x32_bf16 v[114:117], v[206:209], v[214:217], v[114:117]
	v_mfma_f32_16x16x32_bf16 v[102:105], v[198:201], v[222:225], v[102:105]
	v_mfma_f32_16x16x32_bf16 v[98:101], v[206:209], v[222:225], v[98:101]
	v_mfma_f32_16x16x32_bf16 v[86:89], v[198:201], v[230:233], v[86:89]
	v_mfma_f32_16x16x32_bf16 v[82:85], v[206:209], v[230:233], v[82:85]
	v_mfma_f32_16x16x32_bf16 v[70:73], v[198:201], v[238:241], v[70:73]
	v_mfma_f32_16x16x32_bf16 v[66:69], v[206:209], v[238:241], v[66:69]
	s_setprio 0
	s_barrier
	s_add_i32 s3, s3, s11
	v_lshl_add_u64 v[162:163], s[0:1], 0, v[4:5]
	s_mov_b32 m0, s3
	s_nop 0
	global_load_lds_dwordx4 v[162:163], off
	ds_read_b128 v[210:213], v147 offset:16384
	ds_read_b128 v[214:217], v147 offset:17408
	s_add_i32 m0, s3, 0x2000
	s_add_u32 s4, s0, 0x80000
	v_lshl_add_u64 v[166:167], s[0:1], 0, v[130:131]
	s_addc_u32 s5, s1, 0
	s_add_i32 s3, s6, s11
	global_load_lds_dwordx4 v[166:167], off
	ds_read_b128 v[218:221], v147 offset:18432
	ds_read_b128 v[222:225], v147 offset:19456
	v_lshl_add_u64 v[176:177], s[4:5], 0, v[4:5]
	s_mov_b32 m0, s3
	v_lshl_add_u64 v[180:181], s[14:15], 0, v[132:133]
	global_load_lds_dwordx4 v[176:177], off
	ds_read_b128 v[226:229], v147 offset:20480
	ds_read_b128 v[230:233], v147 offset:21504
	v_lshl_add_u64 v[176:177], s[4:5], 0, v[130:131]
	s_add_i32 m0, s3, 0x2000
	s_nop 0
	global_load_lds_dwordx4 v[176:177], off
	ds_read_b128 v[234:237], v147 offset:22528
	ds_read_b128 v[238:241], v147 offset:23552
	v_lshl_add_u64 v[176:177], s[14:15], 0, v[134:135]
	s_mov_b32 m0, s26
	s_nop 0
	global_load_lds_dwordx4 v[176:177], off
	s_mov_b32 m0, s27
	s_nop 0
	global_load_lds_dwordx4 v[180:181], off
	s_waitcnt vmcnt(8)
	s_waitcnt lgkmcnt(0)
	s_barrier
	s_setprio 1
	s_waitcnt lgkmcnt(0)
	v_mfma_f32_16x16x32_bf16 v[62:65], v[140:143], v[210:213], v[62:65]
	v_mfma_f32_16x16x32_bf16 v[58:61], v[172:175], v[210:213], v[58:61]
	v_mfma_f32_16x16x32_bf16 v[46:49], v[140:143], v[218:221], v[46:49]
	v_mfma_f32_16x16x32_bf16 v[42:45], v[172:175], v[218:221], v[42:45]
	v_mfma_f32_16x16x32_bf16 v[30:33], v[140:143], v[226:229], v[30:33]
	v_mfma_f32_16x16x32_bf16 v[26:29], v[172:175], v[226:229], v[26:29]
	v_mfma_f32_16x16x32_bf16 v[14:17], v[140:143], v[234:237], v[14:17]
	v_mfma_f32_16x16x32_bf16 v[10:13], v[172:175], v[234:237], v[10:13]
	v_mfma_f32_16x16x32_bf16 v[62:65], v[148:151], v[214:217], v[62:65]
	v_mfma_f32_16x16x32_bf16 v[58:61], v[190:193], v[214:217], v[58:61]
	v_mfma_f32_16x16x32_bf16 v[46:49], v[148:151], v[222:225], v[46:49]
	v_mfma_f32_16x16x32_bf16 v[42:45], v[190:193], v[222:225], v[42:45]
	v_mfma_f32_16x16x32_bf16 v[30:33], v[148:151], v[230:233], v[30:33]
	v_mfma_f32_16x16x32_bf16 v[26:29], v[190:193], v[230:233], v[26:29]
	v_mfma_f32_16x16x32_bf16 v[14:17], v[148:151], v[238:241], v[14:17]
	v_mfma_f32_16x16x32_bf16 v[10:13], v[190:193], v[238:241], v[10:13]
	s_setprio 0
	s_setprio 1
	v_mfma_f32_16x16x32_bf16 v[54:57], v[194:197], v[210:213], v[54:57]
	v_mfma_f32_16x16x32_bf16 v[50:53], v[202:205], v[210:213], v[50:53]
	v_mfma_f32_16x16x32_bf16 v[38:41], v[194:197], v[218:221], v[38:41]
	v_mfma_f32_16x16x32_bf16 v[34:37], v[202:205], v[218:221], v[34:37]
	v_mfma_f32_16x16x32_bf16 v[22:25], v[194:197], v[226:229], v[22:25]
	v_mfma_f32_16x16x32_bf16 v[18:21], v[202:205], v[226:229], v[18:21]
	v_mfma_f32_16x16x32_bf16 v[6:9], v[194:197], v[234:237], v[6:9]
	v_mfma_f32_16x16x32_bf16 v[0:3], v[202:205], v[234:237], v[0:3]
	v_mfma_f32_16x16x32_bf16 v[54:57], v[198:201], v[214:217], v[54:57]
	v_mfma_f32_16x16x32_bf16 v[50:53], v[206:209], v[214:217], v[50:53]
	v_mfma_f32_16x16x32_bf16 v[38:41], v[198:201], v[222:225], v[38:41]
	v_mfma_f32_16x16x32_bf16 v[34:37], v[206:209], v[222:225], v[34:37]
	v_mfma_f32_16x16x32_bf16 v[22:25], v[198:201], v[230:233], v[22:25]
	v_mfma_f32_16x16x32_bf16 v[18:21], v[206:209], v[230:233], v[18:21]
	v_mfma_f32_16x16x32_bf16 v[6:9], v[198:201], v[238:241], v[6:9]
	v_mfma_f32_16x16x32_bf16 v[0:3], v[206:209], v[238:241], v[0:3]
	s_setprio 0
	s_barrier
.Lpeelmid_163:
	s_add_u32 s4, s14, 0x80000
	s_addc_u32 s5, s15, 0
	s_mov_b32 m0, s30
	v_lshl_add_u64 v[242:243], s[4:5], 0, v[134:135]
	global_load_lds_dwordx4 v[242:243], off
	s_add_i32 s3, 0, 0x18000
	v_add_u32_e32 v164, s3, v145
	s_add_i32 s6, 0, 0x1c000
	ds_read_b128 v[140:143], v164
	ds_read_b128 v[148:151], v164 offset:1024
	ds_read_b128 v[172:175], v164 offset:2048
	ds_read_b128 v[190:193], v164 offset:3072
	v_add_u32_e32 v164, s6, v145
	ds_read_b128 v[194:197], v164
	ds_read_b128 v[198:201], v164 offset:1024
	ds_read_b128 v[202:205], v164 offset:2048
	ds_read_b128 v[206:209], v164 offset:3072
	ds_read_b128 v[210:213], v147 offset:32768
	ds_read_b128 v[214:217], v147 offset:33792
	ds_read_b128 v[218:221], v147 offset:34816
	ds_read_b128 v[222:225], v147 offset:35840
	ds_read_b128 v[226:229], v147 offset:36864
	ds_read_b128 v[230:233], v147 offset:37888
	ds_read_b128 v[234:237], v147 offset:38912
	ds_read_b128 v[238:241], v147 offset:39936
	v_lshl_add_u64 v[242:243], s[4:5], 0, v[132:133]
	s_mov_b32 m0, s31
	s_nop 0
	global_load_lds_dwordx4 v[242:243], off
	s_waitcnt vmcnt(8)
	s_waitcnt lgkmcnt(0)
	s_barrier
	s_setprio 1
	s_waitcnt lgkmcnt(0)
	v_mfma_f32_16x16x32_bf16 v[126:129], v[140:143], v[210:213], v[126:129]
	v_mfma_f32_16x16x32_bf16 v[122:125], v[172:175], v[210:213], v[122:125]
	v_mfma_f32_16x16x32_bf16 v[110:113], v[140:143], v[218:221], v[110:113]
	v_mfma_f32_16x16x32_bf16 v[106:109], v[172:175], v[218:221], v[106:109]
	v_mfma_f32_16x16x32_bf16 v[94:97], v[140:143], v[226:229], v[94:97]
	v_mfma_f32_16x16x32_bf16 v[90:93], v[172:175], v[226:229], v[90:93]
	v_mfma_f32_16x16x32_bf16 v[78:81], v[140:143], v[234:237], v[78:81]
	v_mfma_f32_16x16x32_bf16 v[74:77], v[172:175], v[234:237], v[74:77]
	v_mfma_f32_16x16x32_bf16 v[126:129], v[148:151], v[214:217], v[126:129]
	v_mfma_f32_16x16x32_bf16 v[122:125], v[190:193], v[214:217], v[122:125]
	v_mfma_f32_16x16x32_bf16 v[110:113], v[148:151], v[222:225], v[110:113]
	v_mfma_f32_16x16x32_bf16 v[106:109], v[190:193], v[222:225], v[106:109]
	v_mfma_f32_16x16x32_bf16 v[94:97], v[148:151], v[230:233], v[94:97]
	v_mfma_f32_16x16x32_bf16 v[90:93], v[190:193], v[230:233], v[90:93]
	v_mfma_f32_16x16x32_bf16 v[78:81], v[148:151], v[238:241], v[78:81]
	v_mfma_f32_16x16x32_bf16 v[74:77], v[190:193], v[238:241], v[74:77]
	s_setprio 0
	s_setprio 1
	v_mfma_f32_16x16x32_bf16 v[118:121], v[194:197], v[210:213], v[118:121]
	v_mfma_f32_16x16x32_bf16 v[114:117], v[202:205], v[210:213], v[114:117]
	v_mfma_f32_16x16x32_bf16 v[102:105], v[194:197], v[218:221], v[102:105]
	v_mfma_f32_16x16x32_bf16 v[98:101], v[202:205], v[218:221], v[98:101]
	v_mfma_f32_16x16x32_bf16 v[86:89], v[194:197], v[226:229], v[86:89]
	v_mfma_f32_16x16x32_bf16 v[82:85], v[202:205], v[226:229], v[82:85]
	v_mfma_f32_16x16x32_bf16 v[70:73], v[194:197], v[234:237], v[70:73]
	v_mfma_f32_16x16x32_bf16 v[66:69], v[202:205], v[234:237], v[66:69]
	v_mfma_f32_16x16x32_bf16 v[118:121], v[198:201], v[214:217], v[118:121]
	v_mfma_f32_16x16x32_bf16 v[114:117], v[206:209], v[214:217], v[114:117]
	v_mfma_f32_16x16x32_bf16 v[102:105], v[198:201], v[222:225], v[102:105]
	v_mfma_f32_16x16x32_bf16 v[98:101], v[206:209], v[222:225], v[98:101]
	v_mfma_f32_16x16x32_bf16 v[86:89], v[198:201], v[230:233], v[86:89]
	v_mfma_f32_16x16x32_bf16 v[82:85], v[206:209], v[230:233], v[82:85]
	v_mfma_f32_16x16x32_bf16 v[70:73], v[198:201], v[238:241], v[70:73]
	v_mfma_f32_16x16x32_bf16 v[66:69], v[206:209], v[238:241], v[66:69]
	s_setprio 0
	s_barrier
	s_add_i32 s3, s3, s11
	v_lshl_add_u64 v[162:163], v[162:163], 0, s[70:71]
	s_mov_b32 m0, s3
	s_nop 0
	global_load_lds_dwordx4 v[162:163], off
	ds_read_b128 v[210:213], v147 offset:49152
	ds_read_b128 v[214:217], v147 offset:50176
	s_add_i32 m0, s3, 0x2000
	s_add_u32 s0, s0, 0x80080
	v_lshl_add_u64 v[162:163], v[166:167], 0, s[70:71]
	s_addc_u32 s1, s1, 0
	s_add_i32 s3, s6, s11
	global_load_lds_dwordx4 v[162:163], off
	ds_read_b128 v[218:221], v147 offset:51200
	ds_read_b128 v[222:225], v147 offset:52224
	v_lshl_add_u64 v[162:163], s[0:1], 0, v[4:5]
	s_mov_b32 m0, s3
	s_nop 0
	global_load_lds_dwordx4 v[162:163], off
	ds_read_b128 v[226:229], v147 offset:53248
	ds_read_b128 v[230:233], v147 offset:54272
	v_lshl_add_u64 v[162:163], s[0:1], 0, v[130:131]
	s_add_i32 m0, s3, 0x2000
	s_nop 0
	global_load_lds_dwordx4 v[162:163], off
	ds_read_b128 v[234:237], v147 offset:55296
	ds_read_b128 v[238:241], v147 offset:56320
	v_lshl_add_u64 v[162:163], v[176:177], 0, s[70:71]
	s_mov_b32 m0, s35
	s_nop 0
	global_load_lds_dwordx4 v[162:163], off
	v_lshl_add_u64 v[162:163], v[180:181], 0, s[70:71]
	s_mov_b32 m0, s36
	s_nop 0
	global_load_lds_dwordx4 v[162:163], off
	s_waitcnt vmcnt(8)
	s_waitcnt lgkmcnt(0)
	s_barrier
	s_setprio 1
	s_waitcnt lgkmcnt(0)
	v_mfma_f32_16x16x32_bf16 v[62:65], v[140:143], v[210:213], v[62:65]
	v_mfma_f32_16x16x32_bf16 v[58:61], v[172:175], v[210:213], v[58:61]
	v_mfma_f32_16x16x32_bf16 v[46:49], v[140:143], v[218:221], v[46:49]
	v_mfma_f32_16x16x32_bf16 v[42:45], v[172:175], v[218:221], v[42:45]
	v_mfma_f32_16x16x32_bf16 v[30:33], v[140:143], v[226:229], v[30:33]
	v_mfma_f32_16x16x32_bf16 v[26:29], v[172:175], v[226:229], v[26:29]
	v_mfma_f32_16x16x32_bf16 v[14:17], v[140:143], v[234:237], v[14:17]
	v_mfma_f32_16x16x32_bf16 v[10:13], v[172:175], v[234:237], v[10:13]
	v_mfma_f32_16x16x32_bf16 v[62:65], v[148:151], v[214:217], v[62:65]
	v_mfma_f32_16x16x32_bf16 v[58:61], v[190:193], v[214:217], v[58:61]
	v_mfma_f32_16x16x32_bf16 v[46:49], v[148:151], v[222:225], v[46:49]
	v_mfma_f32_16x16x32_bf16 v[42:45], v[190:193], v[222:225], v[42:45]
	v_mfma_f32_16x16x32_bf16 v[30:33], v[148:151], v[230:233], v[30:33]
	v_mfma_f32_16x16x32_bf16 v[26:29], v[190:193], v[230:233], v[26:29]
	v_mfma_f32_16x16x32_bf16 v[14:17], v[148:151], v[238:241], v[14:17]
	v_mfma_f32_16x16x32_bf16 v[10:13], v[190:193], v[238:241], v[10:13]
	s_setprio 0
	s_setprio 1
	v_mfma_f32_16x16x32_bf16 v[54:57], v[194:197], v[210:213], v[54:57]
	v_mfma_f32_16x16x32_bf16 v[50:53], v[202:205], v[210:213], v[50:53]
	v_mfma_f32_16x16x32_bf16 v[38:41], v[194:197], v[218:221], v[38:41]
	v_mfma_f32_16x16x32_bf16 v[34:37], v[202:205], v[218:221], v[34:37]
	v_mfma_f32_16x16x32_bf16 v[22:25], v[194:197], v[226:229], v[22:25]
	v_mfma_f32_16x16x32_bf16 v[18:21], v[202:205], v[226:229], v[18:21]
	v_mfma_f32_16x16x32_bf16 v[6:9], v[194:197], v[234:237], v[6:9]
	v_mfma_f32_16x16x32_bf16 v[0:3], v[202:205], v[234:237], v[0:3]
	v_mfma_f32_16x16x32_bf16 v[54:57], v[198:201], v[214:217], v[54:57]
	v_mfma_f32_16x16x32_bf16 v[50:53], v[206:209], v[214:217], v[50:53]
	v_mfma_f32_16x16x32_bf16 v[38:41], v[198:201], v[222:225], v[38:41]
	v_mfma_f32_16x16x32_bf16 v[34:37], v[206:209], v[222:225], v[34:37]
	v_mfma_f32_16x16x32_bf16 v[22:25], v[198:201], v[230:233], v[22:25]
	v_mfma_f32_16x16x32_bf16 v[18:21], v[206:209], v[230:233], v[18:21]
	v_mfma_f32_16x16x32_bf16 v[6:9], v[198:201], v[238:241], v[6:9]
	v_mfma_f32_16x16x32_bf16 v[0:3], v[206:209], v[238:241], v[0:3]
	s_setprio 0
	s_barrier
	s_add_i32 s24, s24, 2
	s_add_u32 s22, s22, 0x100
	s_addc_u32 s23, s23, 0
	s_add_u32 s9, s9, 0x100
	s_addc_u32 s10, s10, 0
	s_cmp_gt_u32 s24, 29
	s_cbranch_scc0 .LBB0_163
	s_and_b64 vcc, exec, s[46:47]
	s_cbranch_vccz .LBB0_166
	s_barrier

.LBB0_204:
	s_ashr_i32 s49, s48, 31
	s_lshl_b64 s[2:3], s[48:49], 19
	v_readlane_b32 s4, v253, 17
	v_readlane_b32 s5, v253, 18
	s_add_u32 s84, s4, s2
	s_addc_u32 s85, s5, s3
	s_and_b64 s[2:3], s[42:43], exec
	s_cselect_b32 s2, s85, s15
	s_cselect_b32 s8, s84, s14
	s_add_u32 s22, s0, 0x40080
	s_addc_u32 s23, s1, 0
	s_add_u32 s9, s14, 0x100
	v_mov_b32_e32 v0, 0
	s_addc_u32 s10, s15, 0
	s_mov_b32 s24, -2
	v_mov_b32_e32 v1, v0
	v_mov_b32_e32 v2, v0
	v_mov_b32_e32 v3, v0
	v_mov_b32_e32 v6, v0
	v_mov_b32_e32 v7, v0
	v_mov_b32_e32 v8, v0
	v_mov_b32_e32 v9, v0
	v_mov_b32_e32 v10, v0
	v_mov_b32_e32 v11, v0
	v_mov_b32_e32 v12, v0
	v_mov_b32_e32 v13, v0
	v_mov_b32_e32 v14, v0
	v_mov_b32_e32 v15, v0
	v_mov_b32_e32 v16, v0
	v_mov_b32_e32 v17, v0
	v_mov_b32_e32 v18, v0
	v_mov_b32_e32 v19, v0
	v_mov_b32_e32 v20, v0
	v_mov_b32_e32 v21, v0
	v_mov_b32_e32 v22, v0
	v_mov_b32_e32 v23, v0
	v_mov_b32_e32 v24, v0
	v_mov_b32_e32 v25, v0
	v_mov_b32_e32 v26, v0
	v_mov_b32_e32 v27, v0
	v_mov_b32_e32 v28, v0
	v_mov_b32_e32 v29, v0
	v_mov_b32_e32 v30, v0
	v_mov_b32_e32 v31, v0
	v_mov_b32_e32 v32, v0
	v_mov_b32_e32 v33, v0
	v_mov_b32_e32 v66, v0
	v_mov_b32_e32 v67, v0
	v_mov_b32_e32 v68, v0
	v_mov_b32_e32 v69, v0
	v_mov_b32_e32 v70, v0
	v_mov_b32_e32 v71, v0
	v_mov_b32_e32 v72, v0
	v_mov_b32_e32 v73, v0
	v_mov_b32_e32 v74, v0
	v_mov_b32_e32 v75, v0
	v_mov_b32_e32 v76, v0
	v_mov_b32_e32 v77, v0
	v_mov_b32_e32 v78, v0
	v_mov_b32_e32 v79, v0
	v_mov_b32_e32 v80, v0
	v_mov_b32_e32 v81, v0
	v_mov_b32_e32 v82, v0
	v_mov_b32_e32 v83, v0
	v_mov_b32_e32 v84, v0
	v_mov_b32_e32 v85, v0
	v_mov_b32_e32 v86, v0
	v_mov_b32_e32 v87, v0
	v_mov_b32_e32 v88, v0
	v_mov_b32_e32 v89, v0
	v_mov_b32_e32 v90, v0
	v_mov_b32_e32 v91, v0
	v_mov_b32_e32 v92, v0
	v_mov_b32_e32 v93, v0
	v_mov_b32_e32 v94, v0
	v_mov_b32_e32 v95, v0
	v_mov_b32_e32 v96, v0
	v_mov_b32_e32 v97, v0
	v_mov_b32_e32 v34, v0
	v_mov_b32_e32 v35, v0
	v_mov_b32_e32 v36, v0
	v_mov_b32_e32 v37, v0
	v_mov_b32_e32 v38, v0
	v_mov_b32_e32 v39, v0
	v_mov_b32_e32 v40, v0
	v_mov_b32_e32 v41, v0
	v_mov_b32_e32 v42, v0
	v_mov_b32_e32 v43, v0
	v_mov_b32_e32 v44, v0
	v_mov_b32_e32 v45, v0
	v_mov_b32_e32 v46, v0
	v_mov_b32_e32 v47, v0
	v_mov_b32_e32 v48, v0
	v_mov_b32_e32 v49, v0
	v_mov_b32_e32 v50, v0
	v_mov_b32_e32 v51, v0
	v_mov_b32_e32 v52, v0
	v_mov_b32_e32 v53, v0
	v_mov_b32_e32 v54, v0
	v_mov_b32_e32 v55, v0
	v_mov_b32_e32 v56, v0
	v_mov_b32_e32 v57, v0
	v_mov_b32_e32 v58, v0
	v_mov_b32_e32 v59, v0
	v_mov_b32_e32 v60, v0
	v_mov_b32_e32 v61, v0
	v_mov_b32_e32 v62, v0
	v_mov_b32_e32 v63, v0
	v_mov_b32_e32 v64, v0
	v_mov_b32_e32 v65, v0
	v_mov_b32_e32 v98, v0
	v_mov_b32_e32 v99, v0
	v_mov_b32_e32 v100, v0
	v_mov_b32_e32 v101, v0
	v_mov_b32_e32 v102, v0
	v_mov_b32_e32 v103, v0
	v_mov_b32_e32 v104, v0
	v_mov_b32_e32 v105, v0
	v_mov_b32_e32 v106, v0
	v_mov_b32_e32 v107, v0
	v_mov_b32_e32 v108, v0
	v_mov_b32_e32 v109, v0
	v_mov_b32_e32 v110, v0
	v_mov_b32_e32 v111, v0
	v_mov_b32_e32 v112, v0
	v_mov_b32_e32 v113, v0
	v_mov_b32_e32 v114, v0
	v_mov_b32_e32 v115, v0
	v_mov_b32_e32 v116, v0
	v_mov_b32_e32 v117, v0
	v_mov_b32_e32 v118, v0
	v_mov_b32_e32 v119, v0
	v_mov_b32_e32 v120, v0
	v_mov_b32_e32 v121, v0
	v_mov_b32_e32 v122, v0
	v_mov_b32_e32 v123, v0
	v_mov_b32_e32 v124, v0
	v_mov_b32_e32 v125, v0
	v_mov_b32_e32 v126, v0
	v_mov_b32_e32 v127, v0
	v_mov_b32_e32 v128, v0
	v_mov_b32_e32 v129, v0
	s_cmp_eq_u32 s37, 1
	s_cbranch_scc1 .LBB0_205
	v_lshl_add_u64 v[144:145], s[22:23], 0, v[136:137]
	s_add_i32 m0, s27, 0xc000
	s_nop 0
	global_load_lds_dwordx4 v[144:145], off
	s_add_u32 s0, s22, 0xfffc0080
	s_addc_u32 s1, s23, -1
	s_add_i32 s3, 0, 0x10000
	s_cmp_eq_u32 s24, 12
	s_cselect_b32 s15, s83, s1
	s_cselect_b32 s14, s82, s0
	v_add_u32_e32 v144, s3, v168
	s_cselect_b32 s1, s2, s10
	s_cselect_b32 s0, s8, s9
	s_add_i32 s6, 0, 0x14000
	ds_read_b128 v[140:143], v144
	ds_read_b128 v[174:177], v144 offset:1024
	ds_read_b128 v[190:193], v144 offset:2048
	ds_read_b128 v[194:197], v144 offset:3072
	v_add_u32_e32 v144, s6, v168
	ds_read_b128 v[198:201], v144
	ds_read_b128 v[202:205], v144 offset:1024
	ds_read_b128 v[206:209], v144 offset:2048
	ds_read_b128 v[210:213], v144 offset:3072
	ds_read_b128 v[214:217], v172
	ds_read_b128 v[218:221], v172 offset:1024
	ds_read_b128 v[222:225], v172 offset:2048
	ds_read_b128 v[226:229], v172 offset:3072
	ds_read_b128 v[230:233], v172 offset:4096
	ds_read_b128 v[234:237], v172 offset:5120
	ds_read_b128 v[238:241], v172 offset:6144
	ds_read_b128 v[242:245], v172 offset:7168
	v_lshl_add_u64 v[144:145], s[22:23], 0, v[138:139]
	s_add_i32 m0, s27, 0xe000
	s_nop 0
	global_load_lds_dwordx4 v[144:145], off
	s_waitcnt vmcnt(24)
	s_waitcnt lgkmcnt(0)
	s_barrier
	s_setprio 1
	s_waitcnt lgkmcnt(0)
	v_mfma_f32_16x16x32_bf16 v[126:129], v[140:143], v[214:217], v[126:129]
	v_mfma_f32_16x16x32_bf16 v[122:125], v[190:193], v[214:217], v[122:125]
	v_mfma_f32_16x16x32_bf16 v[118:121], v[140:143], v[222:225], v[118:121]
	v_mfma_f32_16x16x32_bf16 v[114:117], v[190:193], v[222:225], v[114:117]
	v_mfma_f32_16x16x32_bf16 v[110:113], v[140:143], v[230:233], v[110:113]
	v_mfma_f32_16x16x32_bf16 v[106:109], v[190:193], v[230:233], v[106:109]
	v_mfma_f32_16x16x32_bf16 v[102:105], v[140:143], v[238:241], v[102:105]
	v_mfma_f32_16x16x32_bf16 v[98:101], v[190:193], v[238:241], v[98:101]
	v_mfma_f32_16x16x32_bf16 v[126:129], v[174:177], v[218:221], v[126:129]
	v_mfma_f32_16x16x32_bf16 v[122:125], v[194:197], v[218:221], v[122:125]
	v_mfma_f32_16x16x32_bf16 v[118:121], v[174:177], v[226:229], v[118:121]
	v_mfma_f32_16x16x32_bf16 v[114:117], v[194:197], v[226:229], v[114:117]
	v_mfma_f32_16x16x32_bf16 v[110:113], v[174:177], v[234:237], v[110:113]
	v_mfma_f32_16x16x32_bf16 v[106:109], v[194:197], v[234:237], v[106:109]
	v_mfma_f32_16x16x32_bf16 v[102:105], v[174:177], v[242:245], v[102:105]
	v_mfma_f32_16x16x32_bf16 v[98:101], v[194:197], v[242:245], v[98:101]
	s_setprio 0
	s_setprio 1
	v_mfma_f32_16x16x32_bf16 v[62:65], v[198:201], v[214:217], v[62:65]
	v_mfma_f32_16x16x32_bf16 v[58:61], v[206:209], v[214:217], v[58:61]
	v_mfma_f32_16x16x32_bf16 v[54:57], v[198:201], v[222:225], v[54:57]
	v_mfma_f32_16x16x32_bf16 v[50:53], v[206:209], v[222:225], v[50:53]
	v_mfma_f32_16x16x32_bf16 v[46:49], v[198:201], v[230:233], v[46:49]
	v_mfma_f32_16x16x32_bf16 v[42:45], v[206:209], v[230:233], v[42:45]
	v_mfma_f32_16x16x32_bf16 v[38:41], v[198:201], v[238:241], v[38:41]
	v_mfma_f32_16x16x32_bf16 v[34:37], v[206:209], v[238:241], v[34:37]
	v_mfma_f32_16x16x32_bf16 v[62:65], v[202:205], v[218:221], v[62:65]
	v_mfma_f32_16x16x32_bf16 v[58:61], v[210:213], v[218:221], v[58:61]
	v_mfma_f32_16x16x32_bf16 v[54:57], v[202:205], v[226:229], v[54:57]
	v_mfma_f32_16x16x32_bf16 v[50:53], v[210:213], v[226:229], v[50:53]
	v_mfma_f32_16x16x32_bf16 v[46:49], v[202:205], v[234:237], v[46:49]
	v_mfma_f32_16x16x32_bf16 v[42:45], v[210:213], v[234:237], v[42:45]
	v_mfma_f32_16x16x32_bf16 v[38:41], v[202:205], v[242:245], v[38:41]
	v_mfma_f32_16x16x32_bf16 v[34:37], v[210:213], v[242:245], v[34:37]
	s_setprio 0
	s_barrier
	s_add_i32 s3, s3, s26
	v_lshl_add_u64 v[144:145], s[0:1], 0, v[4:5]
	s_mov_b32 m0, s3
	s_nop 0
	global_load_lds_dwordx4 v[144:145], off
	ds_read_b128 v[214:217], v172 offset:16384
	ds_read_b128 v[218:221], v172 offset:17408
	s_add_i32 m0, s3, 0x2000
	s_add_u32 s4, s0, 0x40000
	v_lshl_add_u64 v[246:247], s[0:1], 0, v[134:135]
	s_addc_u32 s5, s1, 0
	s_add_i32 s3, s6, s26
	global_load_lds_dwordx4 v[246:247], off
	ds_read_b128 v[222:225], v172 offset:18432
	ds_read_b128 v[226:229], v172 offset:19456
	v_lshl_add_u64 v[248:249], s[4:5], 0, v[4:5]
	s_mov_b32 m0, s3
	v_lshl_add_u64 v[250:251], s[14:15], 0, v[132:133]
	global_load_lds_dwordx4 v[248:249], off
	ds_read_b128 v[230:233], v172 offset:20480
	ds_read_b128 v[234:237], v172 offset:21504
	v_lshl_add_u64 v[248:249], s[4:5], 0, v[134:135]
	s_add_i32 m0, s3, 0x2000
	s_nop 0
	global_load_lds_dwordx4 v[248:249], off
	ds_read_b128 v[238:241], v172 offset:22528
	ds_read_b128 v[242:245], v172 offset:23552
	v_lshl_add_u64 v[248:249], s[14:15], 0, v[130:131]
	s_mov_b32 m0, s27
	s_nop 0
	global_load_lds_dwordx4 v[248:249], off
	s_mov_b32 m0, s30
	s_nop 0
	global_load_lds_dwordx4 v[250:251], off
	s_waitcnt vmcnt(24)
	s_waitcnt lgkmcnt(0)
	s_barrier
	s_setprio 1
	s_waitcnt lgkmcnt(0)
	v_mfma_f32_16x16x32_bf16 v[94:97], v[140:143], v[214:217], v[94:97]
	v_mfma_f32_16x16x32_bf16 v[90:93], v[190:193], v[214:217], v[90:93]
	v_mfma_f32_16x16x32_bf16 v[86:89], v[140:143], v[222:225], v[86:89]
	v_mfma_f32_16x16x32_bf16 v[82:85], v[190:193], v[222:225], v[82:85]
	v_mfma_f32_16x16x32_bf16 v[78:81], v[140:143], v[230:233], v[78:81]
	v_mfma_f32_16x16x32_bf16 v[74:77], v[190:193], v[230:233], v[74:77]
	v_mfma_f32_16x16x32_bf16 v[70:73], v[140:143], v[238:241], v[70:73]
	v_mfma_f32_16x16x32_bf16 v[66:69], v[190:193], v[238:241], v[66:69]
	v_mfma_f32_16x16x32_bf16 v[94:97], v[174:177], v[218:221], v[94:97]
	v_mfma_f32_16x16x32_bf16 v[90:93], v[194:197], v[218:221], v[90:93]
	v_mfma_f32_16x16x32_bf16 v[86:89], v[174:177], v[226:229], v[86:89]
	v_mfma_f32_16x16x32_bf16 v[82:85], v[194:197], v[226:229], v[82:85]
	v_mfma_f32_16x16x32_bf16 v[78:81], v[174:177], v[234:237], v[78:81]
	v_mfma_f32_16x16x32_bf16 v[74:77], v[194:197], v[234:237], v[74:77]
	v_mfma_f32_16x16x32_bf16 v[70:73], v[174:177], v[242:245], v[70:73]
	v_mfma_f32_16x16x32_bf16 v[66:69], v[194:197], v[242:245], v[66:69]
	s_setprio 0
	s_setprio 1
	v_mfma_f32_16x16x32_bf16 v[30:33], v[198:201], v[214:217], v[30:33]
	v_mfma_f32_16x16x32_bf16 v[26:29], v[206:209], v[214:217], v[26:29]
	v_mfma_f32_16x16x32_bf16 v[22:25], v[198:201], v[222:225], v[22:25]
	v_mfma_f32_16x16x32_bf16 v[18:21], v[206:209], v[222:225], v[18:21]
	v_mfma_f32_16x16x32_bf16 v[14:17], v[198:201], v[230:233], v[14:17]
	v_mfma_f32_16x16x32_bf16 v[10:13], v[206:209], v[230:233], v[10:13]
	v_mfma_f32_16x16x32_bf16 v[6:9], v[198:201], v[238:241], v[6:9]
	v_mfma_f32_16x16x32_bf16 v[0:3], v[206:209], v[238:241], v[0:3]
	v_mfma_f32_16x16x32_bf16 v[30:33], v[202:205], v[218:221], v[30:33]
	v_mfma_f32_16x16x32_bf16 v[26:29], v[210:213], v[218:221], v[26:29]
	v_mfma_f32_16x16x32_bf16 v[22:25], v[202:205], v[226:229], v[22:25]
	v_mfma_f32_16x16x32_bf16 v[18:21], v[210:213], v[226:229], v[18:21]
	v_mfma_f32_16x16x32_bf16 v[14:17], v[202:205], v[234:237], v[14:17]
	v_mfma_f32_16x16x32_bf16 v[10:13], v[210:213], v[234:237], v[10:13]
	v_mfma_f32_16x16x32_bf16 v[6:9], v[202:205], v[242:245], v[6:9]
	v_mfma_f32_16x16x32_bf16 v[0:3], v[210:213], v[242:245], v[0:3]
	s_setprio 0
	s_barrier
	s_branch .Lpeelmid_205
.LBB0_205:
	v_lshl_add_u64 v[144:145], s[22:23], 0, v[136:137]
	s_add_i32 m0, s27, 0xc000
	s_nop 0
	global_load_lds_dwordx4 v[144:145], off
	s_add_u32 s0, s22, 0xfffc0080
	s_addc_u32 s1, s23, -1
	s_add_i32 s3, 0, 0x10000
	s_cmp_eq_u32 s24, 12
	s_cselect_b32 s15, s83, s1
	s_cselect_b32 s14, s82, s0
	v_add_u32_e32 v144, s3, v168
	s_cselect_b32 s1, s2, s10
	s_cselect_b32 s0, s8, s9
	s_add_i32 s6, 0, 0x14000
	ds_read_b128 v[140:143], v144
	ds_read_b128 v[174:177], v144 offset:1024
	ds_read_b128 v[190:193], v144 offset:2048
	ds_read_b128 v[194:197], v144 offset:3072
	v_add_u32_e32 v144, s6, v168
	ds_read_b128 v[198:201], v144
	ds_read_b128 v[202:205], v144 offset:1024
	ds_read_b128 v[206:209], v144 offset:2048
	ds_read_b128 v[210:213], v144 offset:3072
	ds_read_b128 v[214:217], v172
	ds_read_b128 v[218:221], v172 offset:1024
	ds_read_b128 v[222:225], v172 offset:2048
	ds_read_b128 v[226:229], v172 offset:3072
	ds_read_b128 v[230:233], v172 offset:4096
	ds_read_b128 v[234:237], v172 offset:5120
	ds_read_b128 v[238:241], v172 offset:6144
	ds_read_b128 v[242:245], v172 offset:7168
	v_lshl_add_u64 v[144:145], s[22:23], 0, v[138:139]
	s_add_i32 m0, s27, 0xe000
	s_nop 0
	global_load_lds_dwordx4 v[144:145], off
	s_waitcnt vmcnt(8)
	s_waitcnt lgkmcnt(0)
	s_barrier
	s_setprio 1
	s_waitcnt lgkmcnt(0)
	v_mfma_f32_16x16x32_bf16 v[126:129], v[140:143], v[214:217], v[126:129]
	v_mfma_f32_16x16x32_bf16 v[122:125], v[190:193], v[214:217], v[122:125]
	v_mfma_f32_16x16x32_bf16 v[118:121], v[140:143], v[222:225], v[118:121]
	v_mfma_f32_16x16x32_bf16 v[114:117], v[190:193], v[222:225], v[114:117]
	v_mfma_f32_16x16x32_bf16 v[110:113], v[140:143], v[230:233], v[110:113]
	v_mfma_f32_16x16x32_bf16 v[106:109], v[190:193], v[230:233], v[106:109]
	v_mfma_f32_16x16x32_bf16 v[102:105], v[140:143], v[238:241], v[102:105]
	v_mfma_f32_16x16x32_bf16 v[98:101], v[190:193], v[238:241], v[98:101]
	v_mfma_f32_16x16x32_bf16 v[126:129], v[174:177], v[218:221], v[126:129]
	v_mfma_f32_16x16x32_bf16 v[122:125], v[194:197], v[218:221], v[122:125]
	v_mfma_f32_16x16x32_bf16 v[118:121], v[174:177], v[226:229], v[118:121]
	v_mfma_f32_16x16x32_bf16 v[114:117], v[194:197], v[226:229], v[114:117]
	v_mfma_f32_16x16x32_bf16 v[110:113], v[174:177], v[234:237], v[110:113]
	v_mfma_f32_16x16x32_bf16 v[106:109], v[194:197], v[234:237], v[106:109]
	v_mfma_f32_16x16x32_bf16 v[102:105], v[174:177], v[242:245], v[102:105]
	v_mfma_f32_16x16x32_bf16 v[98:101], v[194:197], v[242:245], v[98:101]
	s_setprio 0
	s_setprio 1
	v_mfma_f32_16x16x32_bf16 v[62:65], v[198:201], v[214:217], v[62:65]
	v_mfma_f32_16x16x32_bf16 v[58:61], v[206:209], v[214:217], v[58:61]
	v_mfma_f32_16x16x32_bf16 v[54:57], v[198:201], v[222:225], v[54:57]
	v_mfma_f32_16x16x32_bf16 v[50:53], v[206:209], v[222:225], v[50:53]
	v_mfma_f32_16x16x32_bf16 v[46:49], v[198:201], v[230:233], v[46:49]
	v_mfma_f32_16x16x32_bf16 v[42:45], v[206:209], v[230:233], v[42:45]
	v_mfma_f32_16x16x32_bf16 v[38:41], v[198:201], v[238:241], v[38:41]
	v_mfma_f32_16x16x32_bf16 v[34:37], v[206:209], v[238:241], v[34:37]
	v_mfma_f32_16x16x32_bf16 v[62:65], v[202:205], v[218:221], v[62:65]
	v_mfma_f32_16x16x32_bf16 v[58:61], v[210:213], v[218:221], v[58:61]
	v_mfma_f32_16x16x32_bf16 v[54:57], v[202:205], v[226:229], v[54:57]
	v_mfma_f32_16x16x32_bf16 v[50:53], v[210:213], v[226:229], v[50:53]
	v_mfma_f32_16x16x32_bf16 v[46:49], v[202:205], v[234:237], v[46:49]
	v_mfma_f32_16x16x32_bf16 v[42:45], v[210:213], v[234:237], v[42:45]
	v_mfma_f32_16x16x32_bf16 v[38:41], v[202:205], v[242:245], v[38:41]
	v_mfma_f32_16x16x32_bf16 v[34:37], v[210:213], v[242:245], v[34:37]
	s_setprio 0
	s_barrier
	s_add_i32 s3, s3, s26
	v_lshl_add_u64 v[144:145], s[0:1], 0, v[4:5]
	s_mov_b32 m0, s3
	s_nop 0
	global_load_lds_dwordx4 v[144:145], off
	ds_read_b128 v[214:217], v172 offset:16384
	ds_read_b128 v[218:221], v172 offset:17408
	s_add_i32 m0, s3, 0x2000
	s_add_u32 s4, s0, 0x40000
	v_lshl_add_u64 v[246:247], s[0:1], 0, v[134:135]
	s_addc_u32 s5, s1, 0
	s_add_i32 s3, s6, s26
	global_load_lds_dwordx4 v[246:247], off
	ds_read_b128 v[222:225], v172 offset:18432
	ds_read_b128 v[226:229], v172 offset:19456
	v_lshl_add_u64 v[248:249], s[4:5], 0, v[4:5]
	s_mov_b32 m0, s3
	v_lshl_add_u64 v[250:251], s[14:15], 0, v[132:133]
	global_load_lds_dwordx4 v[248:249], off
	ds_read_b128 v[230:233], v172 offset:20480
	ds_read_b128 v[234:237], v172 offset:21504
	v_lshl_add_u64 v[248:249], s[4:5], 0, v[134:135]
	s_add_i32 m0, s3, 0x2000
	s_nop 0
	global_load_lds_dwordx4 v[248:249], off
	ds_read_b128 v[238:241], v172 offset:22528
	ds_read_b128 v[242:245], v172 offset:23552
	v_lshl_add_u64 v[248:249], s[14:15], 0, v[130:131]
	s_mov_b32 m0, s27
	s_nop 0
	global_load_lds_dwordx4 v[248:249], off
	s_mov_b32 m0, s30
	s_nop 0
	global_load_lds_dwordx4 v[250:251], off
	s_waitcnt vmcnt(8)
	s_waitcnt lgkmcnt(0)
	s_barrier
	s_setprio 1
	s_waitcnt lgkmcnt(0)
	v_mfma_f32_16x16x32_bf16 v[94:97], v[140:143], v[214:217], v[94:97]
	v_mfma_f32_16x16x32_bf16 v[90:93], v[190:193], v[214:217], v[90:93]
	v_mfma_f32_16x16x32_bf16 v[86:89], v[140:143], v[222:225], v[86:89]
	v_mfma_f32_16x16x32_bf16 v[82:85], v[190:193], v[222:225], v[82:85]
	v_mfma_f32_16x16x32_bf16 v[78:81], v[140:143], v[230:233], v[78:81]
	v_mfma_f32_16x16x32_bf16 v[74:77], v[190:193], v[230:233], v[74:77]
	v_mfma_f32_16x16x32_bf16 v[70:73], v[140:143], v[238:241], v[70:73]
	v_mfma_f32_16x16x32_bf16 v[66:69], v[190:193], v[238:241], v[66:69]
	v_mfma_f32_16x16x32_bf16 v[94:97], v[174:177], v[218:221], v[94:97]
	v_mfma_f32_16x16x32_bf16 v[90:93], v[194:197], v[218:221], v[90:93]
	v_mfma_f32_16x16x32_bf16 v[86:89], v[174:177], v[226:229], v[86:89]
	v_mfma_f32_16x16x32_bf16 v[82:85], v[194:197], v[226:229], v[82:85]
	v_mfma_f32_16x16x32_bf16 v[78:81], v[174:177], v[234:237], v[78:81]
	v_mfma_f32_16x16x32_bf16 v[74:77], v[194:197], v[234:237], v[74:77]
	v_mfma_f32_16x16x32_bf16 v[70:73], v[174:177], v[242:245], v[70:73]
	v_mfma_f32_16x16x32_bf16 v[66:69], v[194:197], v[242:245], v[66:69]
	s_setprio 0
	s_setprio 1
	v_mfma_f32_16x16x32_bf16 v[30:33], v[198:201], v[214:217], v[30:33]
	v_mfma_f32_16x16x32_bf16 v[26:29], v[206:209], v[214:217], v[26:29]
	v_mfma_f32_16x16x32_bf16 v[22:25], v[198:201], v[222:225], v[22:25]
	v_mfma_f32_16x16x32_bf16 v[18:21], v[206:209], v[222:225], v[18:21]
	v_mfma_f32_16x16x32_bf16 v[14:17], v[198:201], v[230:233], v[14:17]
	v_mfma_f32_16x16x32_bf16 v[10:13], v[206:209], v[230:233], v[10:13]
	v_mfma_f32_16x16x32_bf16 v[6:9], v[198:201], v[238:241], v[6:9]
	v_mfma_f32_16x16x32_bf16 v[0:3], v[206:209], v[238:241], v[0:3]
	v_mfma_f32_16x16x32_bf16 v[30:33], v[202:205], v[218:221], v[30:33]
	v_mfma_f32_16x16x32_bf16 v[26:29], v[210:213], v[218:221], v[26:29]
	v_mfma_f32_16x16x32_bf16 v[22:25], v[202:205], v[226:229], v[22:25]
	v_mfma_f32_16x16x32_bf16 v[18:21], v[210:213], v[226:229], v[18:21]
	v_mfma_f32_16x16x32_bf16 v[14:17], v[202:205], v[234:237], v[14:17]
	v_mfma_f32_16x16x32_bf16 v[10:13], v[210:213], v[234:237], v[10:13]
	v_mfma_f32_16x16x32_bf16 v[6:9], v[202:205], v[242:245], v[6:9]
	v_mfma_f32_16x16x32_bf16 v[0:3], v[210:213], v[242:245], v[0:3]
	s_setprio 0
	s_barrier
.Lpeelmid_205:
	s_add_u32 s4, s14, 0x40000
	s_addc_u32 s5, s15, 0
	s_mov_b32 m0, s31
	v_lshl_add_u64 v[180:181], s[4:5], 0, v[130:131]
	global_load_lds_dwordx4 v[180:181], off
	s_add_i32 s3, 0, 0x18000
	v_add_u32_e32 v173, s3, v168
	s_add_i32 s6, 0, 0x1c000
	ds_read_b128 v[140:143], v173
	ds_read_b128 v[174:177], v173 offset:1024
	ds_read_b128 v[190:193], v173 offset:2048
	ds_read_b128 v[194:197], v173 offset:3072
	v_add_u32_e32 v173, s6, v168
	ds_read_b128 v[198:201], v173
	ds_read_b128 v[202:205], v173 offset:1024
	ds_read_b128 v[206:209], v173 offset:2048
	ds_read_b128 v[210:213], v173 offset:3072
	ds_read_b128 v[214:217], v172 offset:32768
	ds_read_b128 v[218:221], v172 offset:33792
	ds_read_b128 v[222:225], v172 offset:34816
	ds_read_b128 v[226:229], v172 offset:35840
	ds_read_b128 v[230:233], v172 offset:36864
	ds_read_b128 v[234:237], v172 offset:37888
	ds_read_b128 v[238:241], v172 offset:38912
	ds_read_b128 v[242:245], v172 offset:39936
	v_lshl_add_u64 v[180:181], s[4:5], 0, v[132:133]
	s_mov_b32 m0, s34
	s_nop 0
	global_load_lds_dwordx4 v[180:181], off
	s_waitcnt vmcnt(8)
	s_waitcnt lgkmcnt(0)
	s_barrier
	s_setprio 1
	s_waitcnt lgkmcnt(0)
	v_mfma_f32_16x16x32_bf16 v[126:129], v[140:143], v[214:217], v[126:129]
	v_mfma_f32_16x16x32_bf16 v[122:125], v[190:193], v[214:217], v[122:125]
	v_mfma_f32_16x16x32_bf16 v[118:121], v[140:143], v[222:225], v[118:121]
	v_mfma_f32_16x16x32_bf16 v[114:117], v[190:193], v[222:225], v[114:117]
	v_mfma_f32_16x16x32_bf16 v[110:113], v[140:143], v[230:233], v[110:113]
	v_mfma_f32_16x16x32_bf16 v[106:109], v[190:193], v[230:233], v[106:109]
	v_mfma_f32_16x16x32_bf16 v[102:105], v[140:143], v[238:241], v[102:105]
	v_mfma_f32_16x16x32_bf16 v[98:101], v[190:193], v[238:241], v[98:101]
	v_mfma_f32_16x16x32_bf16 v[126:129], v[174:177], v[218:221], v[126:129]
	v_mfma_f32_16x16x32_bf16 v[122:125], v[194:197], v[218:221], v[122:125]
	v_mfma_f32_16x16x32_bf16 v[118:121], v[174:177], v[226:229], v[118:121]
	v_mfma_f32_16x16x32_bf16 v[114:117], v[194:197], v[226:229], v[114:117]
	v_mfma_f32_16x16x32_bf16 v[110:113], v[174:177], v[234:237], v[110:113]
	v_mfma_f32_16x16x32_bf16 v[106:109], v[194:197], v[234:237], v[106:109]
	v_mfma_f32_16x16x32_bf16 v[102:105], v[174:177], v[242:245], v[102:105]
	v_mfma_f32_16x16x32_bf16 v[98:101], v[194:197], v[242:245], v[98:101]
	s_setprio 0
	s_setprio 1
	v_mfma_f32_16x16x32_bf16 v[62:65], v[198:201], v[214:217], v[62:65]
	v_mfma_f32_16x16x32_bf16 v[58:61], v[206:209], v[214:217], v[58:61]
	v_mfma_f32_16x16x32_bf16 v[54:57], v[198:201], v[222:225], v[54:57]
	v_mfma_f32_16x16x32_bf16 v[50:53], v[206:209], v[222:225], v[50:53]
	v_mfma_f32_16x16x32_bf16 v[46:49], v[198:201], v[230:233], v[46:49]
	v_mfma_f32_16x16x32_bf16 v[42:45], v[206:209], v[230:233], v[42:45]
	v_mfma_f32_16x16x32_bf16 v[38:41], v[198:201], v[238:241], v[38:41]
	v_mfma_f32_16x16x32_bf16 v[34:37], v[206:209], v[238:241], v[34:37]
	v_mfma_f32_16x16x32_bf16 v[62:65], v[202:205], v[218:221], v[62:65]
	v_mfma_f32_16x16x32_bf16 v[58:61], v[210:213], v[218:221], v[58:61]
	v_mfma_f32_16x16x32_bf16 v[54:57], v[202:205], v[226:229], v[54:57]
	v_mfma_f32_16x16x32_bf16 v[50:53], v[210:213], v[226:229], v[50:53]
	v_mfma_f32_16x16x32_bf16 v[46:49], v[202:205], v[234:237], v[46:49]
	v_mfma_f32_16x16x32_bf16 v[42:45], v[210:213], v[234:237], v[42:45]
	v_mfma_f32_16x16x32_bf16 v[38:41], v[202:205], v[242:245], v[38:41]
	v_mfma_f32_16x16x32_bf16 v[34:37], v[210:213], v[242:245], v[34:37]
	s_setprio 0
	s_barrier
	s_add_i32 s3, s3, s26
	v_lshl_add_u64 v[144:145], v[144:145], 0, s[70:71]
	s_mov_b32 m0, s3
	s_nop 0
	global_load_lds_dwordx4 v[144:145], off
	ds_read_b128 v[214:217], v172 offset:49152
	ds_read_b128 v[218:221], v172 offset:50176
	s_add_i32 m0, s3, 0x2000
	s_add_u32 s0, s0, 0x40080
	v_lshl_add_u64 v[144:145], v[246:247], 0, s[70:71]
	s_addc_u32 s1, s1, 0
	s_add_i32 s3, s6, s26
	global_load_lds_dwordx4 v[144:145], off
	ds_read_b128 v[222:225], v172 offset:51200
	ds_read_b128 v[226:229], v172 offset:52224
	v_lshl_add_u64 v[144:145], s[0:1], 0, v[4:5]
	s_mov_b32 m0, s3
	s_nop 0
	global_load_lds_dwordx4 v[144:145], off
	ds_read_b128 v[230:233], v172 offset:53248
	ds_read_b128 v[234:237], v172 offset:54272
	v_lshl_add_u64 v[144:145], s[0:1], 0, v[134:135]
	s_add_i32 m0, s3, 0x2000
	s_nop 0
	global_load_lds_dwordx4 v[144:145], off
	ds_read_b128 v[238:241], v172 offset:55296
	ds_read_b128 v[242:245], v172 offset:56320
	v_lshl_add_u64 v[144:145], v[248:249], 0, s[70:71]
	s_mov_b32 m0, s35
	s_nop 0
	global_load_lds_dwordx4 v[144:145], off
	v_lshl_add_u64 v[144:145], v[250:251], 0, s[70:71]
	s_mov_b32 m0, s36
	s_nop 0
	global_load_lds_dwordx4 v[144:145], off
	s_waitcnt vmcnt(8)
	s_waitcnt lgkmcnt(0)
	s_barrier
	s_setprio 1
	s_waitcnt lgkmcnt(0)
	v_mfma_f32_16x16x32_bf16 v[94:97], v[140:143], v[214:217], v[94:97]
	v_mfma_f32_16x16x32_bf16 v[90:93], v[190:193], v[214:217], v[90:93]
	v_mfma_f32_16x16x32_bf16 v[86:89], v[140:143], v[222:225], v[86:89]
	v_mfma_f32_16x16x32_bf16 v[82:85], v[190:193], v[222:225], v[82:85]
	v_mfma_f32_16x16x32_bf16 v[78:81], v[140:143], v[230:233], v[78:81]
	v_mfma_f32_16x16x32_bf16 v[74:77], v[190:193], v[230:233], v[74:77]
	v_mfma_f32_16x16x32_bf16 v[70:73], v[140:143], v[238:241], v[70:73]
	v_mfma_f32_16x16x32_bf16 v[66:69], v[190:193], v[238:241], v[66:69]
	v_mfma_f32_16x16x32_bf16 v[94:97], v[174:177], v[218:221], v[94:97]
	v_mfma_f32_16x16x32_bf16 v[90:93], v[194:197], v[218:221], v[90:93]
	v_mfma_f32_16x16x32_bf16 v[86:89], v[174:177], v[226:229], v[86:89]
	v_mfma_f32_16x16x32_bf16 v[82:85], v[194:197], v[226:229], v[82:85]
	v_mfma_f32_16x16x32_bf16 v[78:81], v[174:177], v[234:237], v[78:81]
	v_mfma_f32_16x16x32_bf16 v[74:77], v[194:197], v[234:237], v[74:77]
	v_mfma_f32_16x16x32_bf16 v[70:73], v[174:177], v[242:245], v[70:73]
	v_mfma_f32_16x16x32_bf16 v[66:69], v[194:197], v[242:245], v[66:69]
	s_setprio 0
	s_setprio 1
	v_mfma_f32_16x16x32_bf16 v[30:33], v[198:201], v[214:217], v[30:33]
	v_mfma_f32_16x16x32_bf16 v[26:29], v[206:209], v[214:217], v[26:29]
	v_mfma_f32_16x16x32_bf16 v[22:25], v[198:201], v[222:225], v[22:25]
	v_mfma_f32_16x16x32_bf16 v[18:21], v[206:209], v[222:225], v[18:21]
	v_mfma_f32_16x16x32_bf16 v[14:17], v[198:201], v[230:233], v[14:17]
	v_mfma_f32_16x16x32_bf16 v[10:13], v[206:209], v[230:233], v[10:13]
	v_mfma_f32_16x16x32_bf16 v[6:9], v[198:201], v[238:241], v[6:9]
	v_mfma_f32_16x16x32_bf16 v[0:3], v[206:209], v[238:241], v[0:3]
	v_mfma_f32_16x16x32_bf16 v[30:33], v[202:205], v[218:221], v[30:33]
	v_mfma_f32_16x16x32_bf16 v[26:29], v[210:213], v[218:221], v[26:29]
	v_mfma_f32_16x16x32_bf16 v[22:25], v[202:205], v[226:229], v[22:25]
	v_mfma_f32_16x16x32_bf16 v[18:21], v[210:213], v[226:229], v[18:21]
	v_mfma_f32_16x16x32_bf16 v[14:17], v[202:205], v[234:237], v[14:17]
	v_mfma_f32_16x16x32_bf16 v[10:13], v[210:213], v[234:237], v[10:13]
	v_mfma_f32_16x16x32_bf16 v[6:9], v[202:205], v[242:245], v[6:9]
	v_mfma_f32_16x16x32_bf16 v[0:3], v[210:213], v[242:245], v[0:3]
	s_setprio 0
	s_barrier
	s_add_i32 s24, s24, 2
	s_add_u32 s22, s22, 0x100
	s_addc_u32 s23, s23, 0
	s_add_u32 s9, s9, 0x100
	s_addc_u32 s10, s10, 0
	s_cmp_gt_u32 s24, 13
	s_cbranch_scc0 .LBB0_205
	s_and_b64 vcc, exec, s[46:47]
	s_cbranch_vccz .LBB0_208
	s_barrier

.LBB0_227:
	s_ashr_i32 s47, s46, 31
	s_lshl_b64 s[2:3], s[46:47], 19
	v_readlane_b32 s4, v253, 25
	v_readlane_b32 s5, v253, 26
	s_add_u32 s82, s4, s2
	s_addc_u32 s83, s5, s3
	s_and_b64 s[2:3], s[40:41], exec
	s_cselect_b32 s2, s83, s15
	s_cselect_b32 s8, s82, s14
	s_add_u32 s22, s0, 0x40080
	s_addc_u32 s23, s1, 0
	s_add_u32 s9, s14, 0x100
	v_mov_b32_e32 v0, 0
	s_addc_u32 s10, s15, 0
	s_mov_b32 s24, -2
	v_mov_b32_e32 v1, v0
	v_mov_b32_e32 v2, v0
	v_mov_b32_e32 v3, v0
	v_mov_b32_e32 v6, v0
	v_mov_b32_e32 v7, v0
	v_mov_b32_e32 v8, v0
	v_mov_b32_e32 v9, v0
	v_mov_b32_e32 v10, v0
	v_mov_b32_e32 v11, v0
	v_mov_b32_e32 v12, v0
	v_mov_b32_e32 v13, v0
	v_mov_b32_e32 v14, v0
	v_mov_b32_e32 v15, v0
	v_mov_b32_e32 v16, v0
	v_mov_b32_e32 v17, v0
	v_mov_b32_e32 v18, v0
	v_mov_b32_e32 v19, v0
	v_mov_b32_e32 v20, v0
	v_mov_b32_e32 v21, v0
	v_mov_b32_e32 v22, v0
	v_mov_b32_e32 v23, v0
	v_mov_b32_e32 v24, v0
	v_mov_b32_e32 v25, v0
	v_mov_b32_e32 v26, v0
	v_mov_b32_e32 v27, v0
	v_mov_b32_e32 v28, v0
	v_mov_b32_e32 v29, v0
	v_mov_b32_e32 v30, v0
	v_mov_b32_e32 v31, v0
	v_mov_b32_e32 v32, v0
	v_mov_b32_e32 v33, v0
	v_mov_b32_e32 v62, v0
	v_mov_b32_e32 v63, v0
	v_mov_b32_e32 v64, v0
	v_mov_b32_e32 v65, v0
	v_mov_b32_e32 v70, v0
	v_mov_b32_e32 v71, v0
	v_mov_b32_e32 v72, v0
	v_mov_b32_e32 v73, v0
	v_mov_b32_e32 v74, v0
	v_mov_b32_e32 v75, v0
	v_mov_b32_e32 v76, v0
	v_mov_b32_e32 v77, v0
	v_mov_b32_e32 v78, v0
	v_mov_b32_e32 v79, v0
	v_mov_b32_e32 v80, v0
	v_mov_b32_e32 v81, v0
	v_mov_b32_e32 v82, v0
	v_mov_b32_e32 v83, v0
	v_mov_b32_e32 v84, v0
	v_mov_b32_e32 v85, v0
	v_mov_b32_e32 v86, v0
	v_mov_b32_e32 v87, v0
	v_mov_b32_e32 v88, v0
	v_mov_b32_e32 v89, v0
	v_mov_b32_e32 v90, v0
	v_mov_b32_e32 v91, v0
	v_mov_b32_e32 v92, v0
	v_mov_b32_e32 v93, v0
	v_mov_b32_e32 v94, v0
	v_mov_b32_e32 v95, v0
	v_mov_b32_e32 v96, v0
	v_mov_b32_e32 v97, v0
	v_mov_b32_e32 v34, v0
	v_mov_b32_e32 v35, v0
	v_mov_b32_e32 v36, v0
	v_mov_b32_e32 v37, v0
	v_mov_b32_e32 v38, v0
	v_mov_b32_e32 v39, v0
	v_mov_b32_e32 v40, v0
	v_mov_b32_e32 v41, v0
	v_mov_b32_e32 v42, v0
	v_mov_b32_e32 v43, v0
	v_mov_b32_e32 v44, v0
	v_mov_b32_e32 v45, v0
	v_mov_b32_e32 v46, v0
	v_mov_b32_e32 v47, v0
	v_mov_b32_e32 v48, v0
	v_mov_b32_e32 v49, v0
	v_mov_b32_e32 v50, v0
	v_mov_b32_e32 v51, v0
	v_mov_b32_e32 v52, v0
	v_mov_b32_e32 v53, v0
	v_mov_b32_e32 v54, v0
	v_mov_b32_e32 v55, v0
	v_mov_b32_e32 v56, v0
	v_mov_b32_e32 v57, v0
	v_mov_b32_e32 v58, v0
	v_mov_b32_e32 v59, v0
	v_mov_b32_e32 v60, v0
	v_mov_b32_e32 v61, v0
	v_mov_b32_e32 v66, v0
	v_mov_b32_e32 v67, v0
	v_mov_b32_e32 v68, v0
	v_mov_b32_e32 v69, v0
	v_mov_b32_e32 v98, v0
	v_mov_b32_e32 v99, v0
	v_mov_b32_e32 v100, v0
	v_mov_b32_e32 v101, v0
	v_mov_b32_e32 v102, v0
	v_mov_b32_e32 v103, v0
	v_mov_b32_e32 v104, v0
	v_mov_b32_e32 v105, v0
	v_mov_b32_e32 v106, v0
	v_mov_b32_e32 v107, v0
	v_mov_b32_e32 v108, v0
	v_mov_b32_e32 v109, v0
	v_mov_b32_e32 v110, v0
	v_mov_b32_e32 v111, v0
	v_mov_b32_e32 v112, v0
	v_mov_b32_e32 v113, v0
	v_mov_b32_e32 v114, v0
	v_mov_b32_e32 v115, v0
	v_mov_b32_e32 v116, v0
	v_mov_b32_e32 v117, v0
	v_mov_b32_e32 v118, v0
	v_mov_b32_e32 v119, v0
	v_mov_b32_e32 v120, v0
	v_mov_b32_e32 v121, v0
	v_mov_b32_e32 v122, v0
	v_mov_b32_e32 v123, v0
	v_mov_b32_e32 v124, v0
	v_mov_b32_e32 v125, v0
	v_mov_b32_e32 v126, v0
	v_mov_b32_e32 v127, v0
	v_mov_b32_e32 v128, v0
	v_mov_b32_e32 v129, v0
	s_cmp_eq_u32 s37, 1
	s_cbranch_scc1 .LBB0_228
	v_lshl_add_u64 v[162:163], s[22:23], 0, v[136:137]
	s_add_i32 m0, s27, 0xc000
	s_nop 0
	global_load_lds_dwordx4 v[162:163], off
	s_add_u32 s0, s22, 0xfffc0080
	s_addc_u32 s1, s23, -1
	s_add_i32 s3, 0, 0x10000
	s_cmp_eq_u32 s24, 12
	s_cselect_b32 s15, s49, s1
	s_cselect_b32 s14, s48, s0
	v_add_u32_e32 v162, s3, v149
	s_cselect_b32 s1, s2, s10
	s_cselect_b32 s0, s8, s9
	s_add_i32 s6, 0, 0x14000
	ds_read_b128 v[140:143], v162
	ds_read_b128 v[144:147], v162 offset:1024
	ds_read_b128 v[172:175], v162 offset:2048
	ds_read_b128 v[190:193], v162 offset:3072
	v_add_u32_e32 v162, s6, v149
	ds_read_b128 v[194:197], v162
	ds_read_b128 v[198:201], v162 offset:1024
	ds_read_b128 v[202:205], v162 offset:2048
	ds_read_b128 v[206:209], v162 offset:3072
	ds_read_b128 v[210:213], v151
	ds_read_b128 v[214:217], v151 offset:1024
	ds_read_b128 v[218:221], v151 offset:2048
	ds_read_b128 v[222:225], v151 offset:3072
	ds_read_b128 v[226:229], v151 offset:4096
	ds_read_b128 v[230:233], v151 offset:5120
	ds_read_b128 v[234:237], v151 offset:6144
	ds_read_b128 v[238:241], v151 offset:7168
	v_lshl_add_u64 v[162:163], s[22:23], 0, v[138:139]
	s_add_i32 m0, s27, 0xe000
	s_nop 0
	global_load_lds_dwordx4 v[162:163], off
	s_waitcnt vmcnt(24)
	s_waitcnt lgkmcnt(0)
	s_barrier
	s_setprio 1
	s_waitcnt lgkmcnt(0)
	v_mfma_f32_16x16x32_bf16 v[126:129], v[140:143], v[210:213], v[126:129]
	v_mfma_f32_16x16x32_bf16 v[122:125], v[172:175], v[210:213], v[122:125]
	v_mfma_f32_16x16x32_bf16 v[118:121], v[140:143], v[218:221], v[118:121]
	v_mfma_f32_16x16x32_bf16 v[114:117], v[172:175], v[218:221], v[114:117]
	v_mfma_f32_16x16x32_bf16 v[110:113], v[140:143], v[226:229], v[110:113]
	v_mfma_f32_16x16x32_bf16 v[106:109], v[172:175], v[226:229], v[106:109]
	v_mfma_f32_16x16x32_bf16 v[102:105], v[140:143], v[234:237], v[102:105]
	v_mfma_f32_16x16x32_bf16 v[98:101], v[172:175], v[234:237], v[98:101]
	v_mfma_f32_16x16x32_bf16 v[126:129], v[144:147], v[214:217], v[126:129]
	v_mfma_f32_16x16x32_bf16 v[122:125], v[190:193], v[214:217], v[122:125]
	v_mfma_f32_16x16x32_bf16 v[118:121], v[144:147], v[222:225], v[118:121]
	v_mfma_f32_16x16x32_bf16 v[114:117], v[190:193], v[222:225], v[114:117]
	v_mfma_f32_16x16x32_bf16 v[110:113], v[144:147], v[230:233], v[110:113]
	v_mfma_f32_16x16x32_bf16 v[106:109], v[190:193], v[230:233], v[106:109]
	v_mfma_f32_16x16x32_bf16 v[102:105], v[144:147], v[238:241], v[102:105]
	v_mfma_f32_16x16x32_bf16 v[98:101], v[190:193], v[238:241], v[98:101]
	s_setprio 0
	s_setprio 1
	v_mfma_f32_16x16x32_bf16 v[66:69], v[194:197], v[210:213], v[66:69]
	v_mfma_f32_16x16x32_bf16 v[58:61], v[202:205], v[210:213], v[58:61]
	v_mfma_f32_16x16x32_bf16 v[54:57], v[194:197], v[218:221], v[54:57]
	v_mfma_f32_16x16x32_bf16 v[50:53], v[202:205], v[218:221], v[50:53]
	v_mfma_f32_16x16x32_bf16 v[46:49], v[194:197], v[226:229], v[46:49]
	v_mfma_f32_16x16x32_bf16 v[42:45], v[202:205], v[226:229], v[42:45]
	v_mfma_f32_16x16x32_bf16 v[38:41], v[194:197], v[234:237], v[38:41]
	v_mfma_f32_16x16x32_bf16 v[34:37], v[202:205], v[234:237], v[34:37]
	v_mfma_f32_16x16x32_bf16 v[66:69], v[198:201], v[214:217], v[66:69]
	v_mfma_f32_16x16x32_bf16 v[58:61], v[206:209], v[214:217], v[58:61]
	v_mfma_f32_16x16x32_bf16 v[54:57], v[198:201], v[222:225], v[54:57]
	v_mfma_f32_16x16x32_bf16 v[50:53], v[206:209], v[222:225], v[50:53]
	v_mfma_f32_16x16x32_bf16 v[46:49], v[198:201], v[230:233], v[46:49]
	v_mfma_f32_16x16x32_bf16 v[42:45], v[206:209], v[230:233], v[42:45]
	v_mfma_f32_16x16x32_bf16 v[38:41], v[198:201], v[238:241], v[38:41]
	v_mfma_f32_16x16x32_bf16 v[34:37], v[206:209], v[238:241], v[34:37]
	s_setprio 0
	s_barrier
	s_add_i32 s3, s3, s26
	v_lshl_add_u64 v[162:163], s[0:1], 0, v[4:5]
	s_mov_b32 m0, s3
	s_nop 0
	global_load_lds_dwordx4 v[162:163], off
	ds_read_b128 v[210:213], v151 offset:16384
	ds_read_b128 v[214:217], v151 offset:17408
	s_add_i32 m0, s3, 0x2000
	s_add_u32 s4, s0, 0x40000
	v_lshl_add_u64 v[166:167], s[0:1], 0, v[134:135]
	s_addc_u32 s5, s1, 0
	s_add_i32 s3, s6, s26
	global_load_lds_dwordx4 v[166:167], off
	ds_read_b128 v[218:221], v151 offset:18432
	ds_read_b128 v[222:225], v151 offset:19456
	v_lshl_add_u64 v[176:177], s[4:5], 0, v[4:5]
	s_mov_b32 m0, s3
	v_lshl_add_u64 v[180:181], s[14:15], 0, v[132:133]
	global_load_lds_dwordx4 v[176:177], off
	ds_read_b128 v[226:229], v151 offset:20480
	ds_read_b128 v[230:233], v151 offset:21504
	v_lshl_add_u64 v[176:177], s[4:5], 0, v[134:135]
	s_add_i32 m0, s3, 0x2000
	s_nop 0
	global_load_lds_dwordx4 v[176:177], off
	ds_read_b128 v[234:237], v151 offset:22528
	ds_read_b128 v[238:241], v151 offset:23552
	v_lshl_add_u64 v[176:177], s[14:15], 0, v[130:131]
	s_mov_b32 m0, s27
	s_nop 0
	global_load_lds_dwordx4 v[176:177], off
	s_mov_b32 m0, s30
	s_nop 0
	global_load_lds_dwordx4 v[180:181], off
	s_waitcnt vmcnt(24)
	s_waitcnt lgkmcnt(0)
	s_barrier
	s_setprio 1
	s_waitcnt lgkmcnt(0)
	v_mfma_f32_16x16x32_bf16 v[94:97], v[140:143], v[210:213], v[94:97]
	v_mfma_f32_16x16x32_bf16 v[90:93], v[172:175], v[210:213], v[90:93]
	v_mfma_f32_16x16x32_bf16 v[86:89], v[140:143], v[218:221], v[86:89]
	v_mfma_f32_16x16x32_bf16 v[82:85], v[172:175], v[218:221], v[82:85]
	v_mfma_f32_16x16x32_bf16 v[78:81], v[140:143], v[226:229], v[78:81]
	v_mfma_f32_16x16x32_bf16 v[74:77], v[172:175], v[226:229], v[74:77]
	v_mfma_f32_16x16x32_bf16 v[70:73], v[140:143], v[234:237], v[70:73]
	v_mfma_f32_16x16x32_bf16 v[62:65], v[172:175], v[234:237], v[62:65]
	v_mfma_f32_16x16x32_bf16 v[94:97], v[144:147], v[214:217], v[94:97]
	v_mfma_f32_16x16x32_bf16 v[90:93], v[190:193], v[214:217], v[90:93]
	v_mfma_f32_16x16x32_bf16 v[86:89], v[144:147], v[222:225], v[86:89]
	v_mfma_f32_16x16x32_bf16 v[82:85], v[190:193], v[222:225], v[82:85]
	v_mfma_f32_16x16x32_bf16 v[78:81], v[144:147], v[230:233], v[78:81]
	v_mfma_f32_16x16x32_bf16 v[74:77], v[190:193], v[230:233], v[74:77]
	v_mfma_f32_16x16x32_bf16 v[70:73], v[144:147], v[238:241], v[70:73]
	v_mfma_f32_16x16x32_bf16 v[62:65], v[190:193], v[238:241], v[62:65]
	s_setprio 0
	s_setprio 1
	v_mfma_f32_16x16x32_bf16 v[30:33], v[194:197], v[210:213], v[30:33]
	v_mfma_f32_16x16x32_bf16 v[26:29], v[202:205], v[210:213], v[26:29]
	v_mfma_f32_16x16x32_bf16 v[22:25], v[194:197], v[218:221], v[22:25]
	v_mfma_f32_16x16x32_bf16 v[18:21], v[202:205], v[218:221], v[18:21]
	v_mfma_f32_16x16x32_bf16 v[14:17], v[194:197], v[226:229], v[14:17]
	v_mfma_f32_16x16x32_bf16 v[10:13], v[202:205], v[226:229], v[10:13]
	v_mfma_f32_16x16x32_bf16 v[6:9], v[194:197], v[234:237], v[6:9]
	v_mfma_f32_16x16x32_bf16 v[0:3], v[202:205], v[234:237], v[0:3]
	v_mfma_f32_16x16x32_bf16 v[30:33], v[198:201], v[214:217], v[30:33]
	v_mfma_f32_16x16x32_bf16 v[26:29], v[206:209], v[214:217], v[26:29]
	v_mfma_f32_16x16x32_bf16 v[22:25], v[198:201], v[222:225], v[22:25]
	v_mfma_f32_16x16x32_bf16 v[18:21], v[206:209], v[222:225], v[18:21]
	v_mfma_f32_16x16x32_bf16 v[14:17], v[198:201], v[230:233], v[14:17]
	v_mfma_f32_16x16x32_bf16 v[10:13], v[206:209], v[230:233], v[10:13]
	v_mfma_f32_16x16x32_bf16 v[6:9], v[198:201], v[238:241], v[6:9]
	v_mfma_f32_16x16x32_bf16 v[0:3], v[206:209], v[238:241], v[0:3]
	s_setprio 0
	s_barrier
	s_branch .Lpeelmid_228
.LBB0_228:
	v_lshl_add_u64 v[162:163], s[22:23], 0, v[136:137]
	s_add_i32 m0, s27, 0xc000
	s_nop 0
	global_load_lds_dwordx4 v[162:163], off
	s_add_u32 s0, s22, 0xfffc0080
	s_addc_u32 s1, s23, -1
	s_add_i32 s3, 0, 0x10000
	s_cmp_eq_u32 s24, 12
	s_cselect_b32 s15, s49, s1
	s_cselect_b32 s14, s48, s0
	v_add_u32_e32 v162, s3, v149
	s_cselect_b32 s1, s2, s10
	s_cselect_b32 s0, s8, s9
	s_add_i32 s6, 0, 0x14000
	ds_read_b128 v[140:143], v162
	ds_read_b128 v[144:147], v162 offset:1024
	ds_read_b128 v[172:175], v162 offset:2048
	ds_read_b128 v[190:193], v162 offset:3072
	v_add_u32_e32 v162, s6, v149
	ds_read_b128 v[194:197], v162
	ds_read_b128 v[198:201], v162 offset:1024
	ds_read_b128 v[202:205], v162 offset:2048
	ds_read_b128 v[206:209], v162 offset:3072
	ds_read_b128 v[210:213], v151
	ds_read_b128 v[214:217], v151 offset:1024
	ds_read_b128 v[218:221], v151 offset:2048
	ds_read_b128 v[222:225], v151 offset:3072
	ds_read_b128 v[226:229], v151 offset:4096
	ds_read_b128 v[230:233], v151 offset:5120
	ds_read_b128 v[234:237], v151 offset:6144
	ds_read_b128 v[238:241], v151 offset:7168
	v_lshl_add_u64 v[162:163], s[22:23], 0, v[138:139]
	s_add_i32 m0, s27, 0xe000
	s_nop 0
	global_load_lds_dwordx4 v[162:163], off
	s_waitcnt vmcnt(8)
	s_waitcnt lgkmcnt(0)
	s_barrier
	s_setprio 1
	s_waitcnt lgkmcnt(0)
	v_mfma_f32_16x16x32_bf16 v[126:129], v[140:143], v[210:213], v[126:129]
	v_mfma_f32_16x16x32_bf16 v[122:125], v[172:175], v[210:213], v[122:125]
	v_mfma_f32_16x16x32_bf16 v[118:121], v[140:143], v[218:221], v[118:121]
	v_mfma_f32_16x16x32_bf16 v[114:117], v[172:175], v[218:221], v[114:117]
	v_mfma_f32_16x16x32_bf16 v[110:113], v[140:143], v[226:229], v[110:113]
	v_mfma_f32_16x16x32_bf16 v[106:109], v[172:175], v[226:229], v[106:109]
	v_mfma_f32_16x16x32_bf16 v[102:105], v[140:143], v[234:237], v[102:105]
	v_mfma_f32_16x16x32_bf16 v[98:101], v[172:175], v[234:237], v[98:101]
	v_mfma_f32_16x16x32_bf16 v[126:129], v[144:147], v[214:217], v[126:129]
	v_mfma_f32_16x16x32_bf16 v[122:125], v[190:193], v[214:217], v[122:125]
	v_mfma_f32_16x16x32_bf16 v[118:121], v[144:147], v[222:225], v[118:121]
	v_mfma_f32_16x16x32_bf16 v[114:117], v[190:193], v[222:225], v[114:117]
	v_mfma_f32_16x16x32_bf16 v[110:113], v[144:147], v[230:233], v[110:113]
	v_mfma_f32_16x16x32_bf16 v[106:109], v[190:193], v[230:233], v[106:109]
	v_mfma_f32_16x16x32_bf16 v[102:105], v[144:147], v[238:241], v[102:105]
	v_mfma_f32_16x16x32_bf16 v[98:101], v[190:193], v[238:241], v[98:101]
	s_setprio 0
	s_setprio 1
	v_mfma_f32_16x16x32_bf16 v[66:69], v[194:197], v[210:213], v[66:69]
	v_mfma_f32_16x16x32_bf16 v[58:61], v[202:205], v[210:213], v[58:61]
	v_mfma_f32_16x16x32_bf16 v[54:57], v[194:197], v[218:221], v[54:57]
	v_mfma_f32_16x16x32_bf16 v[50:53], v[202:205], v[218:221], v[50:53]
	v_mfma_f32_16x16x32_bf16 v[46:49], v[194:197], v[226:229], v[46:49]
	v_mfma_f32_16x16x32_bf16 v[42:45], v[202:205], v[226:229], v[42:45]
	v_mfma_f32_16x16x32_bf16 v[38:41], v[194:197], v[234:237], v[38:41]
	v_mfma_f32_16x16x32_bf16 v[34:37], v[202:205], v[234:237], v[34:37]
	v_mfma_f32_16x16x32_bf16 v[66:69], v[198:201], v[214:217], v[66:69]
	v_mfma_f32_16x16x32_bf16 v[58:61], v[206:209], v[214:217], v[58:61]
	v_mfma_f32_16x16x32_bf16 v[54:57], v[198:201], v[222:225], v[54:57]
	v_mfma_f32_16x16x32_bf16 v[50:53], v[206:209], v[222:225], v[50:53]
	v_mfma_f32_16x16x32_bf16 v[46:49], v[198:201], v[230:233], v[46:49]
	v_mfma_f32_16x16x32_bf16 v[42:45], v[206:209], v[230:233], v[42:45]
	v_mfma_f32_16x16x32_bf16 v[38:41], v[198:201], v[238:241], v[38:41]
	v_mfma_f32_16x16x32_bf16 v[34:37], v[206:209], v[238:241], v[34:37]
	s_setprio 0
	s_barrier
	s_add_i32 s3, s3, s26
	v_lshl_add_u64 v[162:163], s[0:1], 0, v[4:5]
	s_mov_b32 m0, s3
	s_nop 0
	global_load_lds_dwordx4 v[162:163], off
	ds_read_b128 v[210:213], v151 offset:16384
	ds_read_b128 v[214:217], v151 offset:17408
	s_add_i32 m0, s3, 0x2000
	s_add_u32 s4, s0, 0x40000
	v_lshl_add_u64 v[166:167], s[0:1], 0, v[134:135]
	s_addc_u32 s5, s1, 0
	s_add_i32 s3, s6, s26
	global_load_lds_dwordx4 v[166:167], off
	ds_read_b128 v[218:221], v151 offset:18432
	ds_read_b128 v[222:225], v151 offset:19456
	v_lshl_add_u64 v[176:177], s[4:5], 0, v[4:5]
	s_mov_b32 m0, s3
	v_lshl_add_u64 v[180:181], s[14:15], 0, v[132:133]
	global_load_lds_dwordx4 v[176:177], off
	ds_read_b128 v[226:229], v151 offset:20480
	ds_read_b128 v[230:233], v151 offset:21504
	v_lshl_add_u64 v[176:177], s[4:5], 0, v[134:135]
	s_add_i32 m0, s3, 0x2000
	s_nop 0
	global_load_lds_dwordx4 v[176:177], off
	ds_read_b128 v[234:237], v151 offset:22528
	ds_read_b128 v[238:241], v151 offset:23552
	v_lshl_add_u64 v[176:177], s[14:15], 0, v[130:131]
	s_mov_b32 m0, s27
	s_nop 0
	global_load_lds_dwordx4 v[176:177], off
	s_mov_b32 m0, s30
	s_nop 0
	global_load_lds_dwordx4 v[180:181], off
	s_waitcnt vmcnt(8)
	s_waitcnt lgkmcnt(0)
	s_barrier
	s_setprio 1
	s_waitcnt lgkmcnt(0)
	v_mfma_f32_16x16x32_bf16 v[94:97], v[140:143], v[210:213], v[94:97]
	v_mfma_f32_16x16x32_bf16 v[90:93], v[172:175], v[210:213], v[90:93]
	v_mfma_f32_16x16x32_bf16 v[86:89], v[140:143], v[218:221], v[86:89]
	v_mfma_f32_16x16x32_bf16 v[82:85], v[172:175], v[218:221], v[82:85]
	v_mfma_f32_16x16x32_bf16 v[78:81], v[140:143], v[226:229], v[78:81]
	v_mfma_f32_16x16x32_bf16 v[74:77], v[172:175], v[226:229], v[74:77]
	v_mfma_f32_16x16x32_bf16 v[70:73], v[140:143], v[234:237], v[70:73]
	v_mfma_f32_16x16x32_bf16 v[62:65], v[172:175], v[234:237], v[62:65]
	v_mfma_f32_16x16x32_bf16 v[94:97], v[144:147], v[214:217], v[94:97]
	v_mfma_f32_16x16x32_bf16 v[90:93], v[190:193], v[214:217], v[90:93]
	v_mfma_f32_16x16x32_bf16 v[86:89], v[144:147], v[222:225], v[86:89]
	v_mfma_f32_16x16x32_bf16 v[82:85], v[190:193], v[222:225], v[82:85]
	v_mfma_f32_16x16x32_bf16 v[78:81], v[144:147], v[230:233], v[78:81]
	v_mfma_f32_16x16x32_bf16 v[74:77], v[190:193], v[230:233], v[74:77]
	v_mfma_f32_16x16x32_bf16 v[70:73], v[144:147], v[238:241], v[70:73]
	v_mfma_f32_16x16x32_bf16 v[62:65], v[190:193], v[238:241], v[62:65]
	s_setprio 0
	s_setprio 1
	v_mfma_f32_16x16x32_bf16 v[30:33], v[194:197], v[210:213], v[30:33]
	v_mfma_f32_16x16x32_bf16 v[26:29], v[202:205], v[210:213], v[26:29]
	v_mfma_f32_16x16x32_bf16 v[22:25], v[194:197], v[218:221], v[22:25]
	v_mfma_f32_16x16x32_bf16 v[18:21], v[202:205], v[218:221], v[18:21]
	v_mfma_f32_16x16x32_bf16 v[14:17], v[194:197], v[226:229], v[14:17]
	v_mfma_f32_16x16x32_bf16 v[10:13], v[202:205], v[226:229], v[10:13]
	v_mfma_f32_16x16x32_bf16 v[6:9], v[194:197], v[234:237], v[6:9]
	v_mfma_f32_16x16x32_bf16 v[0:3], v[202:205], v[234:237], v[0:3]
	v_mfma_f32_16x16x32_bf16 v[30:33], v[198:201], v[214:217], v[30:33]
	v_mfma_f32_16x16x32_bf16 v[26:29], v[206:209], v[214:217], v[26:29]
	v_mfma_f32_16x16x32_bf16 v[22:25], v[198:201], v[222:225], v[22:25]
	v_mfma_f32_16x16x32_bf16 v[18:21], v[206:209], v[222:225], v[18:21]
	v_mfma_f32_16x16x32_bf16 v[14:17], v[198:201], v[230:233], v[14:17]
	v_mfma_f32_16x16x32_bf16 v[10:13], v[206:209], v[230:233], v[10:13]
	v_mfma_f32_16x16x32_bf16 v[6:9], v[198:201], v[238:241], v[6:9]
	v_mfma_f32_16x16x32_bf16 v[0:3], v[206:209], v[238:241], v[0:3]
	s_setprio 0
	s_barrier
.Lpeelmid_228:
	s_add_u32 s4, s14, 0x40000
	s_addc_u32 s5, s15, 0
	s_mov_b32 m0, s31
	v_lshl_add_u64 v[242:243], s[4:5], 0, v[130:131]
	global_load_lds_dwordx4 v[242:243], off
	s_add_i32 s3, 0, 0x18000
	v_add_u32_e32 v164, s3, v149
	s_add_i32 s6, 0, 0x1c000
	ds_read_b128 v[140:143], v164
	ds_read_b128 v[144:147], v164 offset:1024
	ds_read_b128 v[172:175], v164 offset:2048
	ds_read_b128 v[190:193], v164 offset:3072
	v_add_u32_e32 v164, s6, v149
	ds_read_b128 v[194:197], v164
	ds_read_b128 v[198:201], v164 offset:1024
	ds_read_b128 v[202:205], v164 offset:2048
	ds_read_b128 v[206:209], v164 offset:3072
	ds_read_b128 v[210:213], v151 offset:32768
	ds_read_b128 v[214:217], v151 offset:33792
	ds_read_b128 v[218:221], v151 offset:34816
	ds_read_b128 v[222:225], v151 offset:35840
	ds_read_b128 v[226:229], v151 offset:36864
	ds_read_b128 v[230:233], v151 offset:37888
	ds_read_b128 v[234:237], v151 offset:38912
	ds_read_b128 v[238:241], v151 offset:39936
	v_lshl_add_u64 v[242:243], s[4:5], 0, v[132:133]
	s_mov_b32 m0, s34
	s_nop 0
	global_load_lds_dwordx4 v[242:243], off
	s_waitcnt vmcnt(8)
	s_waitcnt lgkmcnt(0)
	s_barrier
	s_setprio 1
	s_waitcnt lgkmcnt(0)
	v_mfma_f32_16x16x32_bf16 v[126:129], v[140:143], v[210:213], v[126:129]
	v_mfma_f32_16x16x32_bf16 v[122:125], v[172:175], v[210:213], v[122:125]
	v_mfma_f32_16x16x32_bf16 v[118:121], v[140:143], v[218:221], v[118:121]
	v_mfma_f32_16x16x32_bf16 v[114:117], v[172:175], v[218:221], v[114:117]
	v_mfma_f32_16x16x32_bf16 v[110:113], v[140:143], v[226:229], v[110:113]
	v_mfma_f32_16x16x32_bf16 v[106:109], v[172:175], v[226:229], v[106:109]
	v_mfma_f32_16x16x32_bf16 v[102:105], v[140:143], v[234:237], v[102:105]
	v_mfma_f32_16x16x32_bf16 v[98:101], v[172:175], v[234:237], v[98:101]
	v_mfma_f32_16x16x32_bf16 v[126:129], v[144:147], v[214:217], v[126:129]
	v_mfma_f32_16x16x32_bf16 v[122:125], v[190:193], v[214:217], v[122:125]
	v_mfma_f32_16x16x32_bf16 v[118:121], v[144:147], v[222:225], v[118:121]
	v_mfma_f32_16x16x32_bf16 v[114:117], v[190:193], v[222:225], v[114:117]
	v_mfma_f32_16x16x32_bf16 v[110:113], v[144:147], v[230:233], v[110:113]
	v_mfma_f32_16x16x32_bf16 v[106:109], v[190:193], v[230:233], v[106:109]
	v_mfma_f32_16x16x32_bf16 v[102:105], v[144:147], v[238:241], v[102:105]
	v_mfma_f32_16x16x32_bf16 v[98:101], v[190:193], v[238:241], v[98:101]
	s_setprio 0
	s_setprio 1
	v_mfma_f32_16x16x32_bf16 v[66:69], v[194:197], v[210:213], v[66:69]
	v_mfma_f32_16x16x32_bf16 v[58:61], v[202:205], v[210:213], v[58:61]
	v_mfma_f32_16x16x32_bf16 v[54:57], v[194:197], v[218:221], v[54:57]
	v_mfma_f32_16x16x32_bf16 v[50:53], v[202:205], v[218:221], v[50:53]
	v_mfma_f32_16x16x32_bf16 v[46:49], v[194:197], v[226:229], v[46:49]
	v_mfma_f32_16x16x32_bf16 v[42:45], v[202:205], v[226:229], v[42:45]
	v_mfma_f32_16x16x32_bf16 v[38:41], v[194:197], v[234:237], v[38:41]
	v_mfma_f32_16x16x32_bf16 v[34:37], v[202:205], v[234:237], v[34:37]
	v_mfma_f32_16x16x32_bf16 v[66:69], v[198:201], v[214:217], v[66:69]
	v_mfma_f32_16x16x32_bf16 v[58:61], v[206:209], v[214:217], v[58:61]
	v_mfma_f32_16x16x32_bf16 v[54:57], v[198:201], v[222:225], v[54:57]
	v_mfma_f32_16x16x32_bf16 v[50:53], v[206:209], v[222:225], v[50:53]
	v_mfma_f32_16x16x32_bf16 v[46:49], v[198:201], v[230:233], v[46:49]
	v_mfma_f32_16x16x32_bf16 v[42:45], v[206:209], v[230:233], v[42:45]
	v_mfma_f32_16x16x32_bf16 v[38:41], v[198:201], v[238:241], v[38:41]
	v_mfma_f32_16x16x32_bf16 v[34:37], v[206:209], v[238:241], v[34:37]
	s_setprio 0
	s_barrier
	s_add_i32 s3, s3, s26
	v_lshl_add_u64 v[162:163], v[162:163], 0, s[70:71]
	s_mov_b32 m0, s3
	s_nop 0
	global_load_lds_dwordx4 v[162:163], off
	ds_read_b128 v[210:213], v151 offset:49152
	ds_read_b128 v[214:217], v151 offset:50176
	s_add_i32 m0, s3, 0x2000
	s_add_u32 s0, s0, 0x40080
	v_lshl_add_u64 v[162:163], v[166:167], 0, s[70:71]
	s_addc_u32 s1, s1, 0
	s_add_i32 s3, s6, s26
	global_load_lds_dwordx4 v[162:163], off
	ds_read_b128 v[218:221], v151 offset:51200
	ds_read_b128 v[222:225], v151 offset:52224
	v_lshl_add_u64 v[162:163], s[0:1], 0, v[4:5]
	s_mov_b32 m0, s3
	s_nop 0
	global_load_lds_dwordx4 v[162:163], off
	ds_read_b128 v[226:229], v151 offset:53248
	ds_read_b128 v[230:233], v151 offset:54272
	v_lshl_add_u64 v[162:163], s[0:1], 0, v[134:135]
	s_add_i32 m0, s3, 0x2000
	s_nop 0
	global_load_lds_dwordx4 v[162:163], off
	ds_read_b128 v[234:237], v151 offset:55296
	ds_read_b128 v[238:241], v151 offset:56320
	v_lshl_add_u64 v[162:163], v[176:177], 0, s[70:71]
	s_mov_b32 m0, s35
	s_nop 0
	global_load_lds_dwordx4 v[162:163], off
	v_lshl_add_u64 v[162:163], v[180:181], 0, s[70:71]
	s_mov_b32 m0, s36
	s_nop 0
	global_load_lds_dwordx4 v[162:163], off
	s_waitcnt vmcnt(8)
	s_waitcnt lgkmcnt(0)
	s_barrier
	s_setprio 1
	s_waitcnt lgkmcnt(0)
	v_mfma_f32_16x16x32_bf16 v[94:97], v[140:143], v[210:213], v[94:97]
	v_mfma_f32_16x16x32_bf16 v[90:93], v[172:175], v[210:213], v[90:93]
	v_mfma_f32_16x16x32_bf16 v[86:89], v[140:143], v[218:221], v[86:89]
	v_mfma_f32_16x16x32_bf16 v[82:85], v[172:175], v[218:221], v[82:85]
	v_mfma_f32_16x16x32_bf16 v[78:81], v[140:143], v[226:229], v[78:81]
	v_mfma_f32_16x16x32_bf16 v[74:77], v[172:175], v[226:229], v[74:77]
	v_mfma_f32_16x16x32_bf16 v[70:73], v[140:143], v[234:237], v[70:73]
	v_mfma_f32_16x16x32_bf16 v[62:65], v[172:175], v[234:237], v[62:65]
	v_mfma_f32_16x16x32_bf16 v[94:97], v[144:147], v[214:217], v[94:97]
	v_mfma_f32_16x16x32_bf16 v[90:93], v[190:193], v[214:217], v[90:93]
	v_mfma_f32_16x16x32_bf16 v[86:89], v[144:147], v[222:225], v[86:89]
	v_mfma_f32_16x16x32_bf16 v[82:85], v[190:193], v[222:225], v[82:85]
	v_mfma_f32_16x16x32_bf16 v[78:81], v[144:147], v[230:233], v[78:81]
	v_mfma_f32_16x16x32_bf16 v[74:77], v[190:193], v[230:233], v[74:77]
	v_mfma_f32_16x16x32_bf16 v[70:73], v[144:147], v[238:241], v[70:73]
	v_mfma_f32_16x16x32_bf16 v[62:65], v[190:193], v[238:241], v[62:65]
	s_setprio 0
	s_setprio 1
	v_mfma_f32_16x16x32_bf16 v[30:33], v[194:197], v[210:213], v[30:33]
	v_mfma_f32_16x16x32_bf16 v[26:29], v[202:205], v[210:213], v[26:29]
	v_mfma_f32_16x16x32_bf16 v[22:25], v[194:197], v[218:221], v[22:25]
	v_mfma_f32_16x16x32_bf16 v[18:21], v[202:205], v[218:221], v[18:21]
	v_mfma_f32_16x16x32_bf16 v[14:17], v[194:197], v[226:229], v[14:17]
	v_mfma_f32_16x16x32_bf16 v[10:13], v[202:205], v[226:229], v[10:13]
	v_mfma_f32_16x16x32_bf16 v[6:9], v[194:197], v[234:237], v[6:9]
	v_mfma_f32_16x16x32_bf16 v[0:3], v[202:205], v[234:237], v[0:3]
	v_mfma_f32_16x16x32_bf16 v[30:33], v[198:201], v[214:217], v[30:33]
	v_mfma_f32_16x16x32_bf16 v[26:29], v[206:209], v[214:217], v[26:29]
	v_mfma_f32_16x16x32_bf16 v[22:25], v[198:201], v[222:225], v[22:25]
	v_mfma_f32_16x16x32_bf16 v[18:21], v[206:209], v[222:225], v[18:21]
	v_mfma_f32_16x16x32_bf16 v[14:17], v[198:201], v[230:233], v[14:17]
	v_mfma_f32_16x16x32_bf16 v[10:13], v[206:209], v[230:233], v[10:13]
	v_mfma_f32_16x16x32_bf16 v[6:9], v[198:201], v[238:241], v[6:9]
	v_mfma_f32_16x16x32_bf16 v[0:3], v[206:209], v[238:241], v[0:3]
	s_setprio 0
	s_barrier
	s_add_i32 s24, s24, 2
	s_add_u32 s22, s22, 0x100
	s_addc_u32 s23, s23, 0
	s_add_u32 s9, s9, 0x100
	s_addc_u32 s10, s10, 0
	s_cmp_gt_u32 s24, 13
	s_cbranch_scc0 .LBB0_228
	s_and_b64 vcc, exec, s[44:45]
	s_cbranch_vccz .LBB0_231
	s_barrier

.LBB0_251:
	s_ashr_i32 s47, s46, 31
	s_lshl_b64 s[2:3], s[46:47], 20
	v_readlane_b32 s4, v253, 36
	s_add_u32 s82, s4, s2
	v_readlane_b32 s2, v253, 37
	s_addc_u32 s83, s2, s3
	s_and_b64 s[2:3], s[40:41], exec
	s_cselect_b32 s2, s83, s15
	s_cselect_b32 s8, s82, s14
	s_add_u32 s22, s0, 0x80080
	s_addc_u32 s23, s1, 0
	s_add_u32 s9, s14, 0x100
	v_mov_b32_e32 v0, 0
	s_addc_u32 s10, s15, 0
	s_mov_b32 s24, -2
	v_mov_b32_e32 v1, v0
	v_mov_b32_e32 v2, v0
	v_mov_b32_e32 v3, v0
	v_mov_b32_e32 v6, v0
	v_mov_b32_e32 v7, v0
	v_mov_b32_e32 v8, v0
	v_mov_b32_e32 v9, v0
	v_mov_b32_e32 v10, v0
	v_mov_b32_e32 v11, v0
	v_mov_b32_e32 v12, v0
	v_mov_b32_e32 v13, v0
	v_mov_b32_e32 v14, v0
	v_mov_b32_e32 v15, v0
	v_mov_b32_e32 v16, v0
	v_mov_b32_e32 v17, v0
	v_mov_b32_e32 v18, v0
	v_mov_b32_e32 v19, v0
	v_mov_b32_e32 v20, v0
	v_mov_b32_e32 v21, v0
	v_mov_b32_e32 v22, v0
	v_mov_b32_e32 v23, v0
	v_mov_b32_e32 v24, v0
	v_mov_b32_e32 v25, v0
	v_mov_b32_e32 v26, v0
	v_mov_b32_e32 v27, v0
	v_mov_b32_e32 v28, v0
	v_mov_b32_e32 v29, v0
	v_mov_b32_e32 v30, v0
	v_mov_b32_e32 v31, v0
	v_mov_b32_e32 v32, v0
	v_mov_b32_e32 v33, v0
	v_mov_b32_e32 v62, v0
	v_mov_b32_e32 v63, v0
	v_mov_b32_e32 v64, v0
	v_mov_b32_e32 v65, v0
	v_mov_b32_e32 v70, v0
	v_mov_b32_e32 v71, v0
	v_mov_b32_e32 v72, v0
	v_mov_b32_e32 v73, v0
	v_mov_b32_e32 v74, v0
	v_mov_b32_e32 v75, v0
	v_mov_b32_e32 v76, v0
	v_mov_b32_e32 v77, v0
	v_mov_b32_e32 v78, v0
	v_mov_b32_e32 v79, v0
	v_mov_b32_e32 v80, v0
	v_mov_b32_e32 v81, v0
	v_mov_b32_e32 v82, v0
	v_mov_b32_e32 v83, v0
	v_mov_b32_e32 v84, v0
	v_mov_b32_e32 v85, v0
	v_mov_b32_e32 v86, v0
	v_mov_b32_e32 v87, v0
	v_mov_b32_e32 v88, v0
	v_mov_b32_e32 v89, v0
	v_mov_b32_e32 v90, v0
	v_mov_b32_e32 v91, v0
	v_mov_b32_e32 v92, v0
	v_mov_b32_e32 v93, v0
	v_mov_b32_e32 v94, v0
	v_mov_b32_e32 v95, v0
	v_mov_b32_e32 v96, v0
	v_mov_b32_e32 v97, v0
	v_mov_b32_e32 v34, v0
	v_mov_b32_e32 v35, v0
	v_mov_b32_e32 v36, v0
	v_mov_b32_e32 v37, v0
	v_mov_b32_e32 v38, v0
	v_mov_b32_e32 v39, v0
	v_mov_b32_e32 v40, v0
	v_mov_b32_e32 v41, v0
	v_mov_b32_e32 v42, v0
	v_mov_b32_e32 v43, v0
	v_mov_b32_e32 v44, v0
	v_mov_b32_e32 v45, v0
	v_mov_b32_e32 v46, v0
	v_mov_b32_e32 v47, v0
	v_mov_b32_e32 v48, v0
	v_mov_b32_e32 v49, v0
	v_mov_b32_e32 v50, v0
	v_mov_b32_e32 v51, v0
	v_mov_b32_e32 v52, v0
	v_mov_b32_e32 v53, v0
	v_mov_b32_e32 v54, v0
	v_mov_b32_e32 v55, v0
	v_mov_b32_e32 v56, v0
	v_mov_b32_e32 v57, v0
	v_mov_b32_e32 v58, v0
	v_mov_b32_e32 v59, v0
	v_mov_b32_e32 v60, v0
	v_mov_b32_e32 v61, v0
	v_mov_b32_e32 v66, v0
	v_mov_b32_e32 v67, v0
	v_mov_b32_e32 v68, v0
	v_mov_b32_e32 v69, v0
	v_mov_b32_e32 v98, v0
	v_mov_b32_e32 v99, v0
	v_mov_b32_e32 v100, v0
	v_mov_b32_e32 v101, v0
	v_mov_b32_e32 v102, v0
	v_mov_b32_e32 v103, v0
	v_mov_b32_e32 v104, v0
	v_mov_b32_e32 v105, v0
	v_mov_b32_e32 v106, v0
	v_mov_b32_e32 v107, v0
	v_mov_b32_e32 v108, v0
	v_mov_b32_e32 v109, v0
	v_mov_b32_e32 v110, v0
	v_mov_b32_e32 v111, v0
	v_mov_b32_e32 v112, v0
	v_mov_b32_e32 v113, v0
	v_mov_b32_e32 v114, v0
	v_mov_b32_e32 v115, v0
	v_mov_b32_e32 v116, v0
	v_mov_b32_e32 v117, v0
	v_mov_b32_e32 v118, v0
	v_mov_b32_e32 v119, v0
	v_mov_b32_e32 v120, v0
	v_mov_b32_e32 v121, v0
	v_mov_b32_e32 v122, v0
	v_mov_b32_e32 v123, v0
	v_mov_b32_e32 v124, v0
	v_mov_b32_e32 v125, v0
	v_mov_b32_e32 v126, v0
	v_mov_b32_e32 v127, v0
	v_mov_b32_e32 v128, v0
	v_mov_b32_e32 v129, v0
	s_cmp_eq_u32 s37, 1
	s_cbranch_scc1 .LBB0_252
	v_lshl_add_u64 v[162:163], s[22:23], 0, v[136:137]
	s_add_i32 m0, s27, 0xc000
	s_nop 0
	global_load_lds_dwordx4 v[162:163], off
	s_add_u32 s0, s22, 0xfff80080
	s_addc_u32 s1, s23, -1
	s_add_i32 s3, 0, 0x10000
	s_cmp_eq_u32 s24, 28
	s_cselect_b32 s15, s49, s1
	s_cselect_b32 s14, s48, s0
	v_add_u32_e32 v162, s3, v141
	s_cselect_b32 s1, s2, s10
	s_cselect_b32 s0, s8, s9
	s_add_i32 s6, 0, 0x14000
	ds_read_b128 v[144:147], v162
	ds_read_b128 v[148:151], v162 offset:1024
	ds_read_b128 v[172:175], v162 offset:2048
	ds_read_b128 v[190:193], v162 offset:3072
	v_add_u32_e32 v162, s6, v141
	ds_read_b128 v[194:197], v162
	ds_read_b128 v[198:201], v162 offset:1024
	ds_read_b128 v[202:205], v162 offset:2048
	ds_read_b128 v[206:209], v162 offset:3072
	ds_read_b128 v[210:213], v143
	ds_read_b128 v[214:217], v143 offset:1024
	ds_read_b128 v[218:221], v143 offset:2048
	ds_read_b128 v[222:225], v143 offset:3072
	ds_read_b128 v[226:229], v143 offset:4096
	ds_read_b128 v[230:233], v143 offset:5120
	ds_read_b128 v[234:237], v143 offset:6144
	ds_read_b128 v[238:241], v143 offset:7168
	v_lshl_add_u64 v[162:163], s[22:23], 0, v[138:139]
	s_add_i32 m0, s27, 0xe000
	s_nop 0
	global_load_lds_dwordx4 v[162:163], off
	s_waitcnt vmcnt(24)
	s_waitcnt lgkmcnt(0)
	s_barrier
	s_setprio 1
	s_waitcnt lgkmcnt(0)
	v_mfma_f32_16x16x32_bf16 v[126:129], v[144:147], v[210:213], v[126:129]
	v_mfma_f32_16x16x32_bf16 v[122:125], v[172:175], v[210:213], v[122:125]
	v_mfma_f32_16x16x32_bf16 v[118:121], v[144:147], v[218:221], v[118:121]
	v_mfma_f32_16x16x32_bf16 v[114:117], v[172:175], v[218:221], v[114:117]
	v_mfma_f32_16x16x32_bf16 v[110:113], v[144:147], v[226:229], v[110:113]
	v_mfma_f32_16x16x32_bf16 v[106:109], v[172:175], v[226:229], v[106:109]
	v_mfma_f32_16x16x32_bf16 v[102:105], v[144:147], v[234:237], v[102:105]
	v_mfma_f32_16x16x32_bf16 v[98:101], v[172:175], v[234:237], v[98:101]
	v_mfma_f32_16x16x32_bf16 v[126:129], v[148:151], v[214:217], v[126:129]
	v_mfma_f32_16x16x32_bf16 v[122:125], v[190:193], v[214:217], v[122:125]
	v_mfma_f32_16x16x32_bf16 v[118:121], v[148:151], v[222:225], v[118:121]
	v_mfma_f32_16x16x32_bf16 v[114:117], v[190:193], v[222:225], v[114:117]
	v_mfma_f32_16x16x32_bf16 v[110:113], v[148:151], v[230:233], v[110:113]
	v_mfma_f32_16x16x32_bf16 v[106:109], v[190:193], v[230:233], v[106:109]
	v_mfma_f32_16x16x32_bf16 v[102:105], v[148:151], v[238:241], v[102:105]
	v_mfma_f32_16x16x32_bf16 v[98:101], v[190:193], v[238:241], v[98:101]
	s_setprio 0
	s_setprio 1
	v_mfma_f32_16x16x32_bf16 v[66:69], v[194:197], v[210:213], v[66:69]
	v_mfma_f32_16x16x32_bf16 v[58:61], v[202:205], v[210:213], v[58:61]
	v_mfma_f32_16x16x32_bf16 v[54:57], v[194:197], v[218:221], v[54:57]
	v_mfma_f32_16x16x32_bf16 v[50:53], v[202:205], v[218:221], v[50:53]
	v_mfma_f32_16x16x32_bf16 v[46:49], v[194:197], v[226:229], v[46:49]
	v_mfma_f32_16x16x32_bf16 v[42:45], v[202:205], v[226:229], v[42:45]
	v_mfma_f32_16x16x32_bf16 v[38:41], v[194:197], v[234:237], v[38:41]
	v_mfma_f32_16x16x32_bf16 v[34:37], v[202:205], v[234:237], v[34:37]
	v_mfma_f32_16x16x32_bf16 v[66:69], v[198:201], v[214:217], v[66:69]
	v_mfma_f32_16x16x32_bf16 v[58:61], v[206:209], v[214:217], v[58:61]
	v_mfma_f32_16x16x32_bf16 v[54:57], v[198:201], v[222:225], v[54:57]
	v_mfma_f32_16x16x32_bf16 v[50:53], v[206:209], v[222:225], v[50:53]
	v_mfma_f32_16x16x32_bf16 v[46:49], v[198:201], v[230:233], v[46:49]
	v_mfma_f32_16x16x32_bf16 v[42:45], v[206:209], v[230:233], v[42:45]
	v_mfma_f32_16x16x32_bf16 v[38:41], v[198:201], v[238:241], v[38:41]
	v_mfma_f32_16x16x32_bf16 v[34:37], v[206:209], v[238:241], v[34:37]
	s_setprio 0
	s_barrier
	s_add_i32 s3, s3, s26
	v_lshl_add_u64 v[162:163], s[0:1], 0, v[4:5]
	s_mov_b32 m0, s3
	s_nop 0
	global_load_lds_dwordx4 v[162:163], off
	ds_read_b128 v[210:213], v143 offset:16384
	ds_read_b128 v[214:217], v143 offset:17408
	s_add_i32 m0, s3, 0x2000
	s_add_u32 s4, s0, 0x80000
	v_lshl_add_u64 v[166:167], s[0:1], 0, v[130:131]
	s_addc_u32 s5, s1, 0
	s_add_i32 s3, s6, s26
	global_load_lds_dwordx4 v[166:167], off
	ds_read_b128 v[218:221], v143 offset:18432
	ds_read_b128 v[222:225], v143 offset:19456
	v_lshl_add_u64 v[176:177], s[4:5], 0, v[4:5]
	s_mov_b32 m0, s3
	v_lshl_add_u64 v[242:243], s[14:15], 0, v[132:133]
	global_load_lds_dwordx4 v[176:177], off
	ds_read_b128 v[226:229], v143 offset:20480
	ds_read_b128 v[230:233], v143 offset:21504
	v_lshl_add_u64 v[176:177], s[4:5], 0, v[130:131]
	s_add_i32 m0, s3, 0x2000
	s_nop 0
	global_load_lds_dwordx4 v[176:177], off
	ds_read_b128 v[234:237], v143 offset:22528
	ds_read_b128 v[238:241], v143 offset:23552
	v_lshl_add_u64 v[176:177], s[14:15], 0, v[134:135]
	s_mov_b32 m0, s27
	s_nop 0
	global_load_lds_dwordx4 v[176:177], off
	s_mov_b32 m0, s30
	s_nop 0
	global_load_lds_dwordx4 v[242:243], off
	s_waitcnt vmcnt(24)
	s_waitcnt lgkmcnt(0)
	s_barrier
	s_setprio 1
	s_waitcnt lgkmcnt(0)
	v_mfma_f32_16x16x32_bf16 v[94:97], v[144:147], v[210:213], v[94:97]
	v_mfma_f32_16x16x32_bf16 v[90:93], v[172:175], v[210:213], v[90:93]
	v_mfma_f32_16x16x32_bf16 v[86:89], v[144:147], v[218:221], v[86:89]
	v_mfma_f32_16x16x32_bf16 v[82:85], v[172:175], v[218:221], v[82:85]
	v_mfma_f32_16x16x32_bf16 v[78:81], v[144:147], v[226:229], v[78:81]
	v_mfma_f32_16x16x32_bf16 v[74:77], v[172:175], v[226:229], v[74:77]
	v_mfma_f32_16x16x32_bf16 v[70:73], v[144:147], v[234:237], v[70:73]
	v_mfma_f32_16x16x32_bf16 v[62:65], v[172:175], v[234:237], v[62:65]
	v_mfma_f32_16x16x32_bf16 v[94:97], v[148:151], v[214:217], v[94:97]
	v_mfma_f32_16x16x32_bf16 v[90:93], v[190:193], v[214:217], v[90:93]
	v_mfma_f32_16x16x32_bf16 v[86:89], v[148:151], v[222:225], v[86:89]
	v_mfma_f32_16x16x32_bf16 v[82:85], v[190:193], v[222:225], v[82:85]
	v_mfma_f32_16x16x32_bf16 v[78:81], v[148:151], v[230:233], v[78:81]
	v_mfma_f32_16x16x32_bf16 v[74:77], v[190:193], v[230:233], v[74:77]
	v_mfma_f32_16x16x32_bf16 v[70:73], v[148:151], v[238:241], v[70:73]
	v_mfma_f32_16x16x32_bf16 v[62:65], v[190:193], v[238:241], v[62:65]
	s_setprio 0
	s_setprio 1
	v_mfma_f32_16x16x32_bf16 v[30:33], v[194:197], v[210:213], v[30:33]
	v_mfma_f32_16x16x32_bf16 v[26:29], v[202:205], v[210:213], v[26:29]
	v_mfma_f32_16x16x32_bf16 v[22:25], v[194:197], v[218:221], v[22:25]
	v_mfma_f32_16x16x32_bf16 v[18:21], v[202:205], v[218:221], v[18:21]
	v_mfma_f32_16x16x32_bf16 v[14:17], v[194:197], v[226:229], v[14:17]
	v_mfma_f32_16x16x32_bf16 v[10:13], v[202:205], v[226:229], v[10:13]
	v_mfma_f32_16x16x32_bf16 v[6:9], v[194:197], v[234:237], v[6:9]
	v_mfma_f32_16x16x32_bf16 v[0:3], v[202:205], v[234:237], v[0:3]
	v_mfma_f32_16x16x32_bf16 v[30:33], v[198:201], v[214:217], v[30:33]
	v_mfma_f32_16x16x32_bf16 v[26:29], v[206:209], v[214:217], v[26:29]
	v_mfma_f32_16x16x32_bf16 v[22:25], v[198:201], v[222:225], v[22:25]
	v_mfma_f32_16x16x32_bf16 v[18:21], v[206:209], v[222:225], v[18:21]
	v_mfma_f32_16x16x32_bf16 v[14:17], v[198:201], v[230:233], v[14:17]
	v_mfma_f32_16x16x32_bf16 v[10:13], v[206:209], v[230:233], v[10:13]
	v_mfma_f32_16x16x32_bf16 v[6:9], v[198:201], v[238:241], v[6:9]
	v_mfma_f32_16x16x32_bf16 v[0:3], v[206:209], v[238:241], v[0:3]
	s_setprio 0
	s_barrier
	s_branch .Lpeelmid_252
.LBB0_252:
	v_lshl_add_u64 v[162:163], s[22:23], 0, v[136:137]
	s_add_i32 m0, s27, 0xc000
	s_nop 0
	global_load_lds_dwordx4 v[162:163], off
	s_add_u32 s0, s22, 0xfff80080
	s_addc_u32 s1, s23, -1
	s_add_i32 s3, 0, 0x10000
	s_cmp_eq_u32 s24, 28
	s_cselect_b32 s15, s49, s1
	s_cselect_b32 s14, s48, s0
	v_add_u32_e32 v162, s3, v141
	s_cselect_b32 s1, s2, s10
	s_cselect_b32 s0, s8, s9
	s_add_i32 s6, 0, 0x14000
	ds_read_b128 v[144:147], v162
	ds_read_b128 v[148:151], v162 offset:1024
	ds_read_b128 v[172:175], v162 offset:2048
	ds_read_b128 v[190:193], v162 offset:3072
	v_add_u32_e32 v162, s6, v141
	ds_read_b128 v[194:197], v162
	ds_read_b128 v[198:201], v162 offset:1024
	ds_read_b128 v[202:205], v162 offset:2048
	ds_read_b128 v[206:209], v162 offset:3072
	ds_read_b128 v[210:213], v143
	ds_read_b128 v[214:217], v143 offset:1024
	ds_read_b128 v[218:221], v143 offset:2048
	ds_read_b128 v[222:225], v143 offset:3072
	ds_read_b128 v[226:229], v143 offset:4096
	ds_read_b128 v[230:233], v143 offset:5120
	ds_read_b128 v[234:237], v143 offset:6144
	ds_read_b128 v[238:241], v143 offset:7168
	v_lshl_add_u64 v[162:163], s[22:23], 0, v[138:139]
	s_add_i32 m0, s27, 0xe000
	s_nop 0
	global_load_lds_dwordx4 v[162:163], off
	s_waitcnt vmcnt(8)
	s_waitcnt lgkmcnt(0)
	s_barrier
	s_setprio 1
	s_waitcnt lgkmcnt(0)
	v_mfma_f32_16x16x32_bf16 v[126:129], v[144:147], v[210:213], v[126:129]
	v_mfma_f32_16x16x32_bf16 v[122:125], v[172:175], v[210:213], v[122:125]
	v_mfma_f32_16x16x32_bf16 v[118:121], v[144:147], v[218:221], v[118:121]
	v_mfma_f32_16x16x32_bf16 v[114:117], v[172:175], v[218:221], v[114:117]
	v_mfma_f32_16x16x32_bf16 v[110:113], v[144:147], v[226:229], v[110:113]
	v_mfma_f32_16x16x32_bf16 v[106:109], v[172:175], v[226:229], v[106:109]
	v_mfma_f32_16x16x32_bf16 v[102:105], v[144:147], v[234:237], v[102:105]
	v_mfma_f32_16x16x32_bf16 v[98:101], v[172:175], v[234:237], v[98:101]
	v_mfma_f32_16x16x32_bf16 v[126:129], v[148:151], v[214:217], v[126:129]
	v_mfma_f32_16x16x32_bf16 v[122:125], v[190:193], v[214:217], v[122:125]
	v_mfma_f32_16x16x32_bf16 v[118:121], v[148:151], v[222:225], v[118:121]
	v_mfma_f32_16x16x32_bf16 v[114:117], v[190:193], v[222:225], v[114:117]
	v_mfma_f32_16x16x32_bf16 v[110:113], v[148:151], v[230:233], v[110:113]
	v_mfma_f32_16x16x32_bf16 v[106:109], v[190:193], v[230:233], v[106:109]
	v_mfma_f32_16x16x32_bf16 v[102:105], v[148:151], v[238:241], v[102:105]
	v_mfma_f32_16x16x32_bf16 v[98:101], v[190:193], v[238:241], v[98:101]
	s_setprio 0
	s_setprio 1
	v_mfma_f32_16x16x32_bf16 v[66:69], v[194:197], v[210:213], v[66:69]
	v_mfma_f32_16x16x32_bf16 v[58:61], v[202:205], v[210:213], v[58:61]
	v_mfma_f32_16x16x32_bf16 v[54:57], v[194:197], v[218:221], v[54:57]
	v_mfma_f32_16x16x32_bf16 v[50:53], v[202:205], v[218:221], v[50:53]
	v_mfma_f32_16x16x32_bf16 v[46:49], v[194:197], v[226:229], v[46:49]
	v_mfma_f32_16x16x32_bf16 v[42:45], v[202:205], v[226:229], v[42:45]
	v_mfma_f32_16x16x32_bf16 v[38:41], v[194:197], v[234:237], v[38:41]
	v_mfma_f32_16x16x32_bf16 v[34:37], v[202:205], v[234:237], v[34:37]
	v_mfma_f32_16x16x32_bf16 v[66:69], v[198:201], v[214:217], v[66:69]
	v_mfma_f32_16x16x32_bf16 v[58:61], v[206:209], v[214:217], v[58:61]
	v_mfma_f32_16x16x32_bf16 v[54:57], v[198:201], v[222:225], v[54:57]
	v_mfma_f32_16x16x32_bf16 v[50:53], v[206:209], v[222:225], v[50:53]
	v_mfma_f32_16x16x32_bf16 v[46:49], v[198:201], v[230:233], v[46:49]
	v_mfma_f32_16x16x32_bf16 v[42:45], v[206:209], v[230:233], v[42:45]
	v_mfma_f32_16x16x32_bf16 v[38:41], v[198:201], v[238:241], v[38:41]
	v_mfma_f32_16x16x32_bf16 v[34:37], v[206:209], v[238:241], v[34:37]
	s_setprio 0
	s_barrier
	s_add_i32 s3, s3, s26
	v_lshl_add_u64 v[162:163], s[0:1], 0, v[4:5]
	s_mov_b32 m0, s3
	s_nop 0
	global_load_lds_dwordx4 v[162:163], off
	ds_read_b128 v[210:213], v143 offset:16384
	ds_read_b128 v[214:217], v143 offset:17408
	s_add_i32 m0, s3, 0x2000
	s_add_u32 s4, s0, 0x80000
	v_lshl_add_u64 v[166:167], s[0:1], 0, v[130:131]
	s_addc_u32 s5, s1, 0
	s_add_i32 s3, s6, s26
	global_load_lds_dwordx4 v[166:167], off
	ds_read_b128 v[218:221], v143 offset:18432
	ds_read_b128 v[222:225], v143 offset:19456
	v_lshl_add_u64 v[176:177], s[4:5], 0, v[4:5]
	s_mov_b32 m0, s3
	v_lshl_add_u64 v[242:243], s[14:15], 0, v[132:133]
	global_load_lds_dwordx4 v[176:177], off
	ds_read_b128 v[226:229], v143 offset:20480
	ds_read_b128 v[230:233], v143 offset:21504
	v_lshl_add_u64 v[176:177], s[4:5], 0, v[130:131]
	s_add_i32 m0, s3, 0x2000
	s_nop 0
	global_load_lds_dwordx4 v[176:177], off
	ds_read_b128 v[234:237], v143 offset:22528
	ds_read_b128 v[238:241], v143 offset:23552
	v_lshl_add_u64 v[176:177], s[14:15], 0, v[134:135]
	s_mov_b32 m0, s27
	s_nop 0
	global_load_lds_dwordx4 v[176:177], off
	s_mov_b32 m0, s30
	s_nop 0
	global_load_lds_dwordx4 v[242:243], off
	s_waitcnt vmcnt(8)
	s_waitcnt lgkmcnt(0)
	s_barrier
	s_setprio 1
	s_waitcnt lgkmcnt(0)
	v_mfma_f32_16x16x32_bf16 v[94:97], v[144:147], v[210:213], v[94:97]
	v_mfma_f32_16x16x32_bf16 v[90:93], v[172:175], v[210:213], v[90:93]
	v_mfma_f32_16x16x32_bf16 v[86:89], v[144:147], v[218:221], v[86:89]
	v_mfma_f32_16x16x32_bf16 v[82:85], v[172:175], v[218:221], v[82:85]
	v_mfma_f32_16x16x32_bf16 v[78:81], v[144:147], v[226:229], v[78:81]
	v_mfma_f32_16x16x32_bf16 v[74:77], v[172:175], v[226:229], v[74:77]
	v_mfma_f32_16x16x32_bf16 v[70:73], v[144:147], v[234:237], v[70:73]
	v_mfma_f32_16x16x32_bf16 v[62:65], v[172:175], v[234:237], v[62:65]
	v_mfma_f32_16x16x32_bf16 v[94:97], v[148:151], v[214:217], v[94:97]
	v_mfma_f32_16x16x32_bf16 v[90:93], v[190:193], v[214:217], v[90:93]
	v_mfma_f32_16x16x32_bf16 v[86:89], v[148:151], v[222:225], v[86:89]
	v_mfma_f32_16x16x32_bf16 v[82:85], v[190:193], v[222:225], v[82:85]
	v_mfma_f32_16x16x32_bf16 v[78:81], v[148:151], v[230:233], v[78:81]
	v_mfma_f32_16x16x32_bf16 v[74:77], v[190:193], v[230:233], v[74:77]
	v_mfma_f32_16x16x32_bf16 v[70:73], v[148:151], v[238:241], v[70:73]
	v_mfma_f32_16x16x32_bf16 v[62:65], v[190:193], v[238:241], v[62:65]
	s_setprio 0
	s_setprio 1
	v_mfma_f32_16x16x32_bf16 v[30:33], v[194:197], v[210:213], v[30:33]
	v_mfma_f32_16x16x32_bf16 v[26:29], v[202:205], v[210:213], v[26:29]
	v_mfma_f32_16x16x32_bf16 v[22:25], v[194:197], v[218:221], v[22:25]
	v_mfma_f32_16x16x32_bf16 v[18:21], v[202:205], v[218:221], v[18:21]
	v_mfma_f32_16x16x32_bf16 v[14:17], v[194:197], v[226:229], v[14:17]
	v_mfma_f32_16x16x32_bf16 v[10:13], v[202:205], v[226:229], v[10:13]
	v_mfma_f32_16x16x32_bf16 v[6:9], v[194:197], v[234:237], v[6:9]
	v_mfma_f32_16x16x32_bf16 v[0:3], v[202:205], v[234:237], v[0:3]
	v_mfma_f32_16x16x32_bf16 v[30:33], v[198:201], v[214:217], v[30:33]
	v_mfma_f32_16x16x32_bf16 v[26:29], v[206:209], v[214:217], v[26:29]
	v_mfma_f32_16x16x32_bf16 v[22:25], v[198:201], v[222:225], v[22:25]
	v_mfma_f32_16x16x32_bf16 v[18:21], v[206:209], v[222:225], v[18:21]
	v_mfma_f32_16x16x32_bf16 v[14:17], v[198:201], v[230:233], v[14:17]
	v_mfma_f32_16x16x32_bf16 v[10:13], v[206:209], v[230:233], v[10:13]
	v_mfma_f32_16x16x32_bf16 v[6:9], v[198:201], v[238:241], v[6:9]
	v_mfma_f32_16x16x32_bf16 v[0:3], v[206:209], v[238:241], v[0:3]
	s_setprio 0
	s_barrier
.Lpeelmid_252:
	s_add_u32 s4, s14, 0x80000
	s_addc_u32 s5, s15, 0
	s_mov_b32 m0, s31
	v_lshl_add_u64 v[244:245], s[4:5], 0, v[134:135]
	global_load_lds_dwordx4 v[244:245], off
	s_add_i32 s3, 0, 0x18000
	v_add_u32_e32 v164, s3, v141
	s_add_i32 s6, 0, 0x1c000
	ds_read_b128 v[144:147], v164
	ds_read_b128 v[148:151], v164 offset:1024
	ds_read_b128 v[172:175], v164 offset:2048
	ds_read_b128 v[190:193], v164 offset:3072
	v_add_u32_e32 v164, s6, v141
	ds_read_b128 v[194:197], v164
	ds_read_b128 v[198:201], v164 offset:1024
	ds_read_b128 v[202:205], v164 offset:2048
	ds_read_b128 v[206:209], v164 offset:3072
	ds_read_b128 v[210:213], v143 offset:32768
	ds_read_b128 v[214:217], v143 offset:33792
	ds_read_b128 v[218:221], v143 offset:34816
	ds_read_b128 v[222:225], v143 offset:35840
	ds_read_b128 v[226:229], v143 offset:36864
	ds_read_b128 v[230:233], v143 offset:37888
	ds_read_b128 v[234:237], v143 offset:38912
	ds_read_b128 v[238:241], v143 offset:39936
	v_lshl_add_u64 v[244:245], s[4:5], 0, v[132:133]
	s_mov_b32 m0, s34
	s_nop 0
	global_load_lds_dwordx4 v[244:245], off
	s_waitcnt vmcnt(8)
	s_waitcnt lgkmcnt(0)
	s_barrier
	s_setprio 1
	s_waitcnt lgkmcnt(0)
	v_mfma_f32_16x16x32_bf16 v[126:129], v[144:147], v[210:213], v[126:129]
	v_mfma_f32_16x16x32_bf16 v[122:125], v[172:175], v[210:213], v[122:125]
	v_mfma_f32_16x16x32_bf16 v[118:121], v[144:147], v[218:221], v[118:121]
	v_mfma_f32_16x16x32_bf16 v[114:117], v[172:175], v[218:221], v[114:117]
	v_mfma_f32_16x16x32_bf16 v[110:113], v[144:147], v[226:229], v[110:113]
	v_mfma_f32_16x16x32_bf16 v[106:109], v[172:175], v[226:229], v[106:109]
	v_mfma_f32_16x16x32_bf16 v[102:105], v[144:147], v[234:237], v[102:105]
	v_mfma_f32_16x16x32_bf16 v[98:101], v[172:175], v[234:237], v[98:101]
	v_mfma_f32_16x16x32_bf16 v[126:129], v[148:151], v[214:217], v[126:129]
	v_mfma_f32_16x16x32_bf16 v[122:125], v[190:193], v[214:217], v[122:125]
	v_mfma_f32_16x16x32_bf16 v[118:121], v[148:151], v[222:225], v[118:121]
	v_mfma_f32_16x16x32_bf16 v[114:117], v[190:193], v[222:225], v[114:117]
	v_mfma_f32_16x16x32_bf16 v[110:113], v[148:151], v[230:233], v[110:113]
	v_mfma_f32_16x16x32_bf16 v[106:109], v[190:193], v[230:233], v[106:109]
	v_mfma_f32_16x16x32_bf16 v[102:105], v[148:151], v[238:241], v[102:105]
	v_mfma_f32_16x16x32_bf16 v[98:101], v[190:193], v[238:241], v[98:101]
	s_setprio 0
	s_setprio 1
	v_mfma_f32_16x16x32_bf16 v[66:69], v[194:197], v[210:213], v[66:69]
	v_mfma_f32_16x16x32_bf16 v[58:61], v[202:205], v[210:213], v[58:61]
	v_mfma_f32_16x16x32_bf16 v[54:57], v[194:197], v[218:221], v[54:57]
	v_mfma_f32_16x16x32_bf16 v[50:53], v[202:205], v[218:221], v[50:53]
	v_mfma_f32_16x16x32_bf16 v[46:49], v[194:197], v[226:229], v[46:49]
	v_mfma_f32_16x16x32_bf16 v[42:45], v[202:205], v[226:229], v[42:45]
	v_mfma_f32_16x16x32_bf16 v[38:41], v[194:197], v[234:237], v[38:41]
	v_mfma_f32_16x16x32_bf16 v[34:37], v[202:205], v[234:237], v[34:37]
	v_mfma_f32_16x16x32_bf16 v[66:69], v[198:201], v[214:217], v[66:69]
	v_mfma_f32_16x16x32_bf16 v[58:61], v[206:209], v[214:217], v[58:61]
	v_mfma_f32_16x16x32_bf16 v[54:57], v[198:201], v[222:225], v[54:57]
	v_mfma_f32_16x16x32_bf16 v[50:53], v[206:209], v[222:225], v[50:53]
	v_mfma_f32_16x16x32_bf16 v[46:49], v[198:201], v[230:233], v[46:49]
	v_mfma_f32_16x16x32_bf16 v[42:45], v[206:209], v[230:233], v[42:45]
	v_mfma_f32_16x16x32_bf16 v[38:41], v[198:201], v[238:241], v[38:41]
	v_mfma_f32_16x16x32_bf16 v[34:37], v[206:209], v[238:241], v[34:37]
	s_setprio 0
	s_barrier
	s_add_i32 s3, s3, s26
	v_lshl_add_u64 v[162:163], v[162:163], 0, s[70:71]
	s_mov_b32 m0, s3
	s_nop 0
	global_load_lds_dwordx4 v[162:163], off
	ds_read_b128 v[210:213], v143 offset:49152
	ds_read_b128 v[214:217], v143 offset:50176
	s_add_i32 m0, s3, 0x2000
	s_add_u32 s0, s0, 0x80080
	v_lshl_add_u64 v[162:163], v[166:167], 0, s[70:71]
	s_addc_u32 s1, s1, 0
	s_add_i32 s3, s6, s26
	global_load_lds_dwordx4 v[162:163], off
	ds_read_b128 v[218:221], v143 offset:51200
	ds_read_b128 v[222:225], v143 offset:52224
	v_lshl_add_u64 v[162:163], s[0:1], 0, v[4:5]
	s_mov_b32 m0, s3
	s_nop 0
	global_load_lds_dwordx4 v[162:163], off
	ds_read_b128 v[226:229], v143 offset:53248
	ds_read_b128 v[230:233], v143 offset:54272
	v_lshl_add_u64 v[162:163], s[0:1], 0, v[130:131]
	s_add_i32 m0, s3, 0x2000
	s_nop 0
	global_load_lds_dwordx4 v[162:163], off
	ds_read_b128 v[234:237], v143 offset:55296
	ds_read_b128 v[238:241], v143 offset:56320
	v_lshl_add_u64 v[162:163], v[176:177], 0, s[70:71]
	s_mov_b32 m0, s35
	s_nop 0
	global_load_lds_dwordx4 v[162:163], off
	v_lshl_add_u64 v[162:163], v[242:243], 0, s[70:71]
	s_mov_b32 m0, s36
	s_nop 0
	global_load_lds_dwordx4 v[162:163], off
	s_waitcnt vmcnt(8)
	s_waitcnt lgkmcnt(0)
	s_barrier
	s_setprio 1
	s_waitcnt lgkmcnt(0)
	v_mfma_f32_16x16x32_bf16 v[94:97], v[144:147], v[210:213], v[94:97]
	v_mfma_f32_16x16x32_bf16 v[90:93], v[172:175], v[210:213], v[90:93]
	v_mfma_f32_16x16x32_bf16 v[86:89], v[144:147], v[218:221], v[86:89]
	v_mfma_f32_16x16x32_bf16 v[82:85], v[172:175], v[218:221], v[82:85]
	v_mfma_f32_16x16x32_bf16 v[78:81], v[144:147], v[226:229], v[78:81]
	v_mfma_f32_16x16x32_bf16 v[74:77], v[172:175], v[226:229], v[74:77]
	v_mfma_f32_16x16x32_bf16 v[70:73], v[144:147], v[234:237], v[70:73]
	v_mfma_f32_16x16x32_bf16 v[62:65], v[172:175], v[234:237], v[62:65]
	v_mfma_f32_16x16x32_bf16 v[94:97], v[148:151], v[214:217], v[94:97]
	v_mfma_f32_16x16x32_bf16 v[90:93], v[190:193], v[214:217], v[90:93]
	v_mfma_f32_16x16x32_bf16 v[86:89], v[148:151], v[222:225], v[86:89]
	v_mfma_f32_16x16x32_bf16 v[82:85], v[190:193], v[222:225], v[82:85]
	v_mfma_f32_16x16x32_bf16 v[78:81], v[148:151], v[230:233], v[78:81]
	v_mfma_f32_16x16x32_bf16 v[74:77], v[190:193], v[230:233], v[74:77]
	v_mfma_f32_16x16x32_bf16 v[70:73], v[148:151], v[238:241], v[70:73]
	v_mfma_f32_16x16x32_bf16 v[62:65], v[190:193], v[238:241], v[62:65]
	s_setprio 0
	s_setprio 1
	v_mfma_f32_16x16x32_bf16 v[30:33], v[194:197], v[210:213], v[30:33]
	v_mfma_f32_16x16x32_bf16 v[26:29], v[202:205], v[210:213], v[26:29]
	v_mfma_f32_16x16x32_bf16 v[22:25], v[194:197], v[218:221], v[22:25]
	v_mfma_f32_16x16x32_bf16 v[18:21], v[202:205], v[218:221], v[18:21]
	v_mfma_f32_16x16x32_bf16 v[14:17], v[194:197], v[226:229], v[14:17]
	v_mfma_f32_16x16x32_bf16 v[10:13], v[202:205], v[226:229], v[10:13]
	v_mfma_f32_16x16x32_bf16 v[6:9], v[194:197], v[234:237], v[6:9]
	v_mfma_f32_16x16x32_bf16 v[0:3], v[202:205], v[234:237], v[0:3]
	v_mfma_f32_16x16x32_bf16 v[30:33], v[198:201], v[214:217], v[30:33]
	v_mfma_f32_16x16x32_bf16 v[26:29], v[206:209], v[214:217], v[26:29]
	v_mfma_f32_16x16x32_bf16 v[22:25], v[198:201], v[222:225], v[22:25]
	v_mfma_f32_16x16x32_bf16 v[18:21], v[206:209], v[222:225], v[18:21]
	v_mfma_f32_16x16x32_bf16 v[14:17], v[198:201], v[230:233], v[14:17]
	v_mfma_f32_16x16x32_bf16 v[10:13], v[206:209], v[230:233], v[10:13]
	v_mfma_f32_16x16x32_bf16 v[6:9], v[198:201], v[238:241], v[6:9]
	v_mfma_f32_16x16x32_bf16 v[0:3], v[206:209], v[238:241], v[0:3]
	s_setprio 0
	s_barrier
	s_add_i32 s24, s24, 2
	s_add_u32 s22, s22, 0x100
	s_addc_u32 s23, s23, 0
	s_add_u32 s9, s9, 0x100
	s_addc_u32 s10, s10, 0
	s_cmp_gt_u32 s24, 29
	s_cbranch_scc0 .LBB0_252
	s_and_b64 vcc, exec, s[44:45]
	s_cbranch_vccz .LBB0_255
	s_barrier

.LBB0_851:
	s_ashr_i32 s3, s37, 24
	s_lshl_b32 s2, s37, 8
	s_andn2_b32 s3, s3, 63
	s_add_i32 s2, s3, s2
	s_ashr_i32 s3, s2, 31
	s_lshl_b64 s[2:3], s[2:3], 12
	v_readlane_b32 s4, v252, 6
	v_readlane_b32 s5, v252, 7
	s_add_u32 s76, s4, s2
	s_addc_u32 s77, s5, s3
	s_and_b64 s[2:3], s[38:39], exec
	s_cselect_b32 s2, s77, s15
	s_cselect_b32 s8, s76, s14
	s_ashr_i32 s59, s58, 31
	s_lshl_b64 s[4:5], s[58:59], 20
	v_readlane_b32 s6, v252, 4
	v_readlane_b32 s7, v252, 5
	s_add_u32 s78, s6, s4
	s_addc_u32 s79, s7, s5
	s_and_b64 s[4:5], s[38:39], exec
	s_cselect_b32 s10, s79, s1
	s_cselect_b32 s24, s78, s0
	s_add_u32 s22, s14, 0x80080
	s_addc_u32 s23, s15, 0
	s_add_u32 s9, s0, 0x100
	v_mov_b32_e32 v0, 0
	s_addc_u32 s25, s1, 0
	s_mov_b32 s28, -2
	v_mov_b32_e32 v1, v0
	v_mov_b32_e32 v2, v0
	v_mov_b32_e32 v3, v0
	v_mov_b32_e32 v6, v0
	v_mov_b32_e32 v7, v0
	v_mov_b32_e32 v8, v0
	v_mov_b32_e32 v9, v0
	v_mov_b32_e32 v10, v0
	v_mov_b32_e32 v11, v0
	v_mov_b32_e32 v12, v0
	v_mov_b32_e32 v13, v0
	v_mov_b32_e32 v14, v0
	v_mov_b32_e32 v15, v0
	v_mov_b32_e32 v16, v0
	v_mov_b32_e32 v17, v0
	v_mov_b32_e32 v18, v0
	v_mov_b32_e32 v19, v0
	v_mov_b32_e32 v20, v0
	v_mov_b32_e32 v21, v0
	v_mov_b32_e32 v22, v0
	v_mov_b32_e32 v23, v0
	v_mov_b32_e32 v24, v0
	v_mov_b32_e32 v25, v0
	v_mov_b32_e32 v26, v0
	v_mov_b32_e32 v27, v0
	v_mov_b32_e32 v28, v0
	v_mov_b32_e32 v29, v0
	v_mov_b32_e32 v30, v0
	v_mov_b32_e32 v31, v0
	v_mov_b32_e32 v32, v0
	v_mov_b32_e32 v33, v0
	v_mov_b32_e32 v66, v0
	v_mov_b32_e32 v67, v0
	v_mov_b32_e32 v68, v0
	v_mov_b32_e32 v69, v0
	v_mov_b32_e32 v70, v0
	v_mov_b32_e32 v71, v0
	v_mov_b32_e32 v72, v0
	v_mov_b32_e32 v73, v0
	v_mov_b32_e32 v74, v0
	v_mov_b32_e32 v75, v0
	v_mov_b32_e32 v76, v0
	v_mov_b32_e32 v77, v0
	v_mov_b32_e32 v78, v0
	v_mov_b32_e32 v79, v0
	v_mov_b32_e32 v80, v0
	v_mov_b32_e32 v81, v0
	v_mov_b32_e32 v82, v0
	v_mov_b32_e32 v83, v0
	v_mov_b32_e32 v84, v0
	v_mov_b32_e32 v85, v0
	v_mov_b32_e32 v86, v0
	v_mov_b32_e32 v87, v0
	v_mov_b32_e32 v88, v0
	v_mov_b32_e32 v89, v0
	v_mov_b32_e32 v90, v0
	v_mov_b32_e32 v91, v0
	v_mov_b32_e32 v92, v0
	v_mov_b32_e32 v93, v0
	v_mov_b32_e32 v94, v0
	v_mov_b32_e32 v95, v0
	v_mov_b32_e32 v96, v0
	v_mov_b32_e32 v97, v0
	v_mov_b32_e32 v34, v0
	v_mov_b32_e32 v35, v0
	v_mov_b32_e32 v36, v0
	v_mov_b32_e32 v37, v0
	v_mov_b32_e32 v38, v0
	v_mov_b32_e32 v39, v0
	v_mov_b32_e32 v40, v0
	v_mov_b32_e32 v41, v0
	v_mov_b32_e32 v42, v0
	v_mov_b32_e32 v43, v0
	v_mov_b32_e32 v44, v0
	v_mov_b32_e32 v45, v0
	v_mov_b32_e32 v46, v0
	v_mov_b32_e32 v47, v0
	v_mov_b32_e32 v48, v0
	v_mov_b32_e32 v49, v0
	v_mov_b32_e32 v50, v0
	v_mov_b32_e32 v51, v0
	v_mov_b32_e32 v52, v0
	v_mov_b32_e32 v53, v0
	v_mov_b32_e32 v54, v0
	v_mov_b32_e32 v55, v0
	v_mov_b32_e32 v56, v0
	v_mov_b32_e32 v57, v0
	v_mov_b32_e32 v58, v0
	v_mov_b32_e32 v59, v0
	v_mov_b32_e32 v60, v0
	v_mov_b32_e32 v61, v0
	v_mov_b32_e32 v62, v0
	v_mov_b32_e32 v63, v0
	v_mov_b32_e32 v64, v0
	v_mov_b32_e32 v65, v0
	v_mov_b32_e32 v98, v0
	v_mov_b32_e32 v99, v0
	v_mov_b32_e32 v100, v0
	v_mov_b32_e32 v101, v0
	v_mov_b32_e32 v102, v0
	v_mov_b32_e32 v103, v0
	v_mov_b32_e32 v104, v0
	v_mov_b32_e32 v105, v0
	v_mov_b32_e32 v106, v0
	v_mov_b32_e32 v107, v0
	v_mov_b32_e32 v108, v0
	v_mov_b32_e32 v109, v0
	v_mov_b32_e32 v110, v0
	v_mov_b32_e32 v111, v0
	v_mov_b32_e32 v112, v0
	v_mov_b32_e32 v113, v0
	v_mov_b32_e32 v114, v0
	v_mov_b32_e32 v115, v0
	v_mov_b32_e32 v116, v0
	v_mov_b32_e32 v117, v0
	v_mov_b32_e32 v118, v0
	v_mov_b32_e32 v119, v0
	v_mov_b32_e32 v120, v0
	v_mov_b32_e32 v121, v0
	v_mov_b32_e32 v122, v0
	v_mov_b32_e32 v123, v0
	v_mov_b32_e32 v124, v0
	v_mov_b32_e32 v125, v0
	v_mov_b32_e32 v126, v0
	v_mov_b32_e32 v127, v0
	v_mov_b32_e32 v128, v0
	v_mov_b32_e32 v129, v0
	s_cmp_eq_u32 s36, 1
	s_cbranch_scc1 .LBB0_852
	v_lshl_add_u64 v[176:177], s[22:23], 0, v[136:137]
	s_add_i32 m0, s26, 0xc000
	s_nop 0
	global_load_lds_dwordx4 v[176:177], off
	s_add_u32 s0, s22, 0xfff80080
	s_addc_u32 s1, s23, -1
	s_add_i32 s3, 0, 0x10000
	s_cmp_eq_u32 s28, 28
	s_cselect_b32 s15, s2, s1
	s_cselect_b32 s14, s8, s0
	v_add_u32_e32 v167, s3, v163
	s_cselect_b32 s1, s10, s25
	s_cselect_b32 s0, s24, s9
	s_add_i32 s6, 0, 0x14000
	ds_read_b128 v[140:143], v167
	ds_read_b128 v[144:147], v167 offset:1024
	ds_read_b128 v[148:151], v167 offset:2048
	ds_read_b128 v[172:175], v167 offset:3072
	v_add_u32_e32 v167, s6, v163
	ds_read_b128 v[190:193], v167
	ds_read_b128 v[194:197], v167 offset:1024
	ds_read_b128 v[198:201], v167 offset:2048
	ds_read_b128 v[202:205], v167 offset:3072
	ds_read_b128 v[206:209], v166
	ds_read_b128 v[210:213], v166 offset:1024
	ds_read_b128 v[214:217], v166 offset:2048
	ds_read_b128 v[218:221], v166 offset:3072
	ds_read_b128 v[222:225], v166 offset:4096
	ds_read_b128 v[226:229], v166 offset:5120
	ds_read_b128 v[230:233], v166 offset:6144
	ds_read_b128 v[234:237], v166 offset:7168
	v_lshl_add_u64 v[176:177], s[22:23], 0, v[138:139]
	s_add_i32 m0, s26, 0xe000
	s_nop 0
	global_load_lds_dwordx4 v[176:177], off
	s_waitcnt vmcnt(24)
	s_waitcnt lgkmcnt(0)
	s_barrier
	s_setprio 1
	s_waitcnt lgkmcnt(0)
	v_mfma_f32_16x16x32_bf16 v[126:129], v[140:143], v[206:209], v[126:129]
	v_mfma_f32_16x16x32_bf16 v[122:125], v[148:151], v[206:209], v[122:125]
	v_mfma_f32_16x16x32_bf16 v[118:121], v[140:143], v[214:217], v[118:121]
	v_mfma_f32_16x16x32_bf16 v[114:117], v[148:151], v[214:217], v[114:117]
	v_mfma_f32_16x16x32_bf16 v[110:113], v[140:143], v[222:225], v[110:113]
	v_mfma_f32_16x16x32_bf16 v[106:109], v[148:151], v[222:225], v[106:109]
	v_mfma_f32_16x16x32_bf16 v[102:105], v[140:143], v[230:233], v[102:105]
	v_mfma_f32_16x16x32_bf16 v[98:101], v[148:151], v[230:233], v[98:101]
	v_mfma_f32_16x16x32_bf16 v[126:129], v[144:147], v[210:213], v[126:129]
	v_mfma_f32_16x16x32_bf16 v[122:125], v[172:175], v[210:213], v[122:125]
	v_mfma_f32_16x16x32_bf16 v[118:121], v[144:147], v[218:221], v[118:121]
	v_mfma_f32_16x16x32_bf16 v[114:117], v[172:175], v[218:221], v[114:117]
	v_mfma_f32_16x16x32_bf16 v[110:113], v[144:147], v[226:229], v[110:113]
	v_mfma_f32_16x16x32_bf16 v[106:109], v[172:175], v[226:229], v[106:109]
	v_mfma_f32_16x16x32_bf16 v[102:105], v[144:147], v[234:237], v[102:105]
	v_mfma_f32_16x16x32_bf16 v[98:101], v[172:175], v[234:237], v[98:101]
	s_setprio 0
	s_setprio 1
	v_mfma_f32_16x16x32_bf16 v[62:65], v[190:193], v[206:209], v[62:65]
	v_mfma_f32_16x16x32_bf16 v[58:61], v[198:201], v[206:209], v[58:61]
	v_mfma_f32_16x16x32_bf16 v[54:57], v[190:193], v[214:217], v[54:57]
	v_mfma_f32_16x16x32_bf16 v[50:53], v[198:201], v[214:217], v[50:53]
	v_mfma_f32_16x16x32_bf16 v[46:49], v[190:193], v[222:225], v[46:49]
	v_mfma_f32_16x16x32_bf16 v[42:45], v[198:201], v[222:225], v[42:45]
	v_mfma_f32_16x16x32_bf16 v[38:41], v[190:193], v[230:233], v[38:41]
	v_mfma_f32_16x16x32_bf16 v[34:37], v[198:201], v[230:233], v[34:37]
	v_mfma_f32_16x16x32_bf16 v[62:65], v[194:197], v[210:213], v[62:65]
	v_mfma_f32_16x16x32_bf16 v[58:61], v[202:205], v[210:213], v[58:61]
	v_mfma_f32_16x16x32_bf16 v[54:57], v[194:197], v[218:221], v[54:57]
	v_mfma_f32_16x16x32_bf16 v[50:53], v[202:205], v[218:221], v[50:53]
	v_mfma_f32_16x16x32_bf16 v[46:49], v[194:197], v[226:229], v[46:49]
	v_mfma_f32_16x16x32_bf16 v[42:45], v[202:205], v[226:229], v[42:45]
	v_mfma_f32_16x16x32_bf16 v[38:41], v[194:197], v[234:237], v[38:41]
	v_mfma_f32_16x16x32_bf16 v[34:37], v[202:205], v[234:237], v[34:37]
	s_setprio 0
	s_barrier
	s_add_i32 s3, s3, s11
	v_lshl_add_u64 v[176:177], s[0:1], 0, v[4:5]
	s_mov_b32 m0, s3
	s_nop 0
	global_load_lds_dwordx4 v[176:177], off
	ds_read_b128 v[206:209], v166 offset:16384
	ds_read_b128 v[210:213], v166 offset:17408
	s_add_i32 m0, s3, 0x2000
	s_add_u32 s4, s0, 0x80000
	v_lshl_add_u64 v[238:239], s[0:1], 0, v[134:135]
	s_addc_u32 s5, s1, 0
	s_add_i32 s3, s6, s11
	global_load_lds_dwordx4 v[238:239], off
	ds_read_b128 v[214:217], v166 offset:18432
	ds_read_b128 v[218:221], v166 offset:19456
	v_lshl_add_u64 v[240:241], s[4:5], 0, v[4:5]
	s_mov_b32 m0, s3
	v_lshl_add_u64 v[242:243], s[14:15], 0, v[132:133]
	global_load_lds_dwordx4 v[240:241], off
	ds_read_b128 v[222:225], v166 offset:20480
	ds_read_b128 v[226:229], v166 offset:21504
	v_lshl_add_u64 v[240:241], s[4:5], 0, v[134:135]
	s_add_i32 m0, s3, 0x2000
	s_nop 0
	global_load_lds_dwordx4 v[240:241], off
	ds_read_b128 v[230:233], v166 offset:22528
	ds_read_b128 v[234:237], v166 offset:23552
	v_lshl_add_u64 v[240:241], s[14:15], 0, v[130:131]
	s_mov_b32 m0, s26
	s_nop 0
	global_load_lds_dwordx4 v[240:241], off
	s_mov_b32 m0, s27
	s_nop 0
	global_load_lds_dwordx4 v[242:243], off
	s_waitcnt vmcnt(24)
	s_waitcnt lgkmcnt(0)
	s_barrier
	s_setprio 1
	s_waitcnt lgkmcnt(0)
	v_mfma_f32_16x16x32_bf16 v[94:97], v[140:143], v[206:209], v[94:97]
	v_mfma_f32_16x16x32_bf16 v[90:93], v[148:151], v[206:209], v[90:93]
	v_mfma_f32_16x16x32_bf16 v[86:89], v[140:143], v[214:217], v[86:89]
	v_mfma_f32_16x16x32_bf16 v[82:85], v[148:151], v[214:217], v[82:85]
	v_mfma_f32_16x16x32_bf16 v[78:81], v[140:143], v[222:225], v[78:81]
	v_mfma_f32_16x16x32_bf16 v[74:77], v[148:151], v[222:225], v[74:77]
	v_mfma_f32_16x16x32_bf16 v[70:73], v[140:143], v[230:233], v[70:73]
	v_mfma_f32_16x16x32_bf16 v[66:69], v[148:151], v[230:233], v[66:69]
	v_mfma_f32_16x16x32_bf16 v[94:97], v[144:147], v[210:213], v[94:97]
	v_mfma_f32_16x16x32_bf16 v[90:93], v[172:175], v[210:213], v[90:93]
	v_mfma_f32_16x16x32_bf16 v[86:89], v[144:147], v[218:221], v[86:89]
	v_mfma_f32_16x16x32_bf16 v[82:85], v[172:175], v[218:221], v[82:85]
	v_mfma_f32_16x16x32_bf16 v[78:81], v[144:147], v[226:229], v[78:81]
	v_mfma_f32_16x16x32_bf16 v[74:77], v[172:175], v[226:229], v[74:77]
	v_mfma_f32_16x16x32_bf16 v[70:73], v[144:147], v[234:237], v[70:73]
	v_mfma_f32_16x16x32_bf16 v[66:69], v[172:175], v[234:237], v[66:69]
	s_setprio 0
	s_setprio 1
	v_mfma_f32_16x16x32_bf16 v[30:33], v[190:193], v[206:209], v[30:33]
	v_mfma_f32_16x16x32_bf16 v[26:29], v[198:201], v[206:209], v[26:29]
	v_mfma_f32_16x16x32_bf16 v[22:25], v[190:193], v[214:217], v[22:25]
	v_mfma_f32_16x16x32_bf16 v[18:21], v[198:201], v[214:217], v[18:21]
	v_mfma_f32_16x16x32_bf16 v[14:17], v[190:193], v[222:225], v[14:17]
	v_mfma_f32_16x16x32_bf16 v[10:13], v[198:201], v[222:225], v[10:13]
	v_mfma_f32_16x16x32_bf16 v[6:9], v[190:193], v[230:233], v[6:9]
	v_mfma_f32_16x16x32_bf16 v[0:3], v[198:201], v[230:233], v[0:3]
	v_mfma_f32_16x16x32_bf16 v[30:33], v[194:197], v[210:213], v[30:33]
	v_mfma_f32_16x16x32_bf16 v[26:29], v[202:205], v[210:213], v[26:29]
	v_mfma_f32_16x16x32_bf16 v[22:25], v[194:197], v[218:221], v[22:25]
	v_mfma_f32_16x16x32_bf16 v[18:21], v[202:205], v[218:221], v[18:21]
	v_mfma_f32_16x16x32_bf16 v[14:17], v[194:197], v[226:229], v[14:17]
	v_mfma_f32_16x16x32_bf16 v[10:13], v[202:205], v[226:229], v[10:13]
	v_mfma_f32_16x16x32_bf16 v[6:9], v[194:197], v[234:237], v[6:9]
	v_mfma_f32_16x16x32_bf16 v[0:3], v[202:205], v[234:237], v[0:3]
	s_setprio 0
	s_barrier
	s_branch .Lpeelmid_852
.LBB0_852:
	v_lshl_add_u64 v[176:177], s[22:23], 0, v[136:137]
	s_add_i32 m0, s26, 0xc000
	s_nop 0
	global_load_lds_dwordx4 v[176:177], off
	s_add_u32 s0, s22, 0xfff80080
	s_addc_u32 s1, s23, -1
	s_add_i32 s3, 0, 0x10000
	s_cmp_eq_u32 s28, 28
	s_cselect_b32 s15, s2, s1
	s_cselect_b32 s14, s8, s0
	v_add_u32_e32 v167, s3, v163
	s_cselect_b32 s1, s10, s25
	s_cselect_b32 s0, s24, s9
	s_add_i32 s6, 0, 0x14000
	ds_read_b128 v[140:143], v167
	ds_read_b128 v[144:147], v167 offset:1024
	ds_read_b128 v[148:151], v167 offset:2048
	ds_read_b128 v[172:175], v167 offset:3072
	v_add_u32_e32 v167, s6, v163
	ds_read_b128 v[190:193], v167
	ds_read_b128 v[194:197], v167 offset:1024
	ds_read_b128 v[198:201], v167 offset:2048
	ds_read_b128 v[202:205], v167 offset:3072
	ds_read_b128 v[206:209], v166
	ds_read_b128 v[210:213], v166 offset:1024
	ds_read_b128 v[214:217], v166 offset:2048
	ds_read_b128 v[218:221], v166 offset:3072
	ds_read_b128 v[222:225], v166 offset:4096
	ds_read_b128 v[226:229], v166 offset:5120
	ds_read_b128 v[230:233], v166 offset:6144
	ds_read_b128 v[234:237], v166 offset:7168
	v_lshl_add_u64 v[176:177], s[22:23], 0, v[138:139]
	s_add_i32 m0, s26, 0xe000
	s_nop 0
	global_load_lds_dwordx4 v[176:177], off
	s_waitcnt vmcnt(8)
	s_waitcnt lgkmcnt(0)
	s_barrier
	s_setprio 1
	s_waitcnt lgkmcnt(0)
	v_mfma_f32_16x16x32_bf16 v[126:129], v[140:143], v[206:209], v[126:129]
	v_mfma_f32_16x16x32_bf16 v[122:125], v[148:151], v[206:209], v[122:125]
	v_mfma_f32_16x16x32_bf16 v[118:121], v[140:143], v[214:217], v[118:121]
	v_mfma_f32_16x16x32_bf16 v[114:117], v[148:151], v[214:217], v[114:117]
	v_mfma_f32_16x16x32_bf16 v[110:113], v[140:143], v[222:225], v[110:113]
	v_mfma_f32_16x16x32_bf16 v[106:109], v[148:151], v[222:225], v[106:109]
	v_mfma_f32_16x16x32_bf16 v[102:105], v[140:143], v[230:233], v[102:105]
	v_mfma_f32_16x16x32_bf16 v[98:101], v[148:151], v[230:233], v[98:101]
	v_mfma_f32_16x16x32_bf16 v[126:129], v[144:147], v[210:213], v[126:129]
	v_mfma_f32_16x16x32_bf16 v[122:125], v[172:175], v[210:213], v[122:125]
	v_mfma_f32_16x16x32_bf16 v[118:121], v[144:147], v[218:221], v[118:121]
	v_mfma_f32_16x16x32_bf16 v[114:117], v[172:175], v[218:221], v[114:117]
	v_mfma_f32_16x16x32_bf16 v[110:113], v[144:147], v[226:229], v[110:113]
	v_mfma_f32_16x16x32_bf16 v[106:109], v[172:175], v[226:229], v[106:109]
	v_mfma_f32_16x16x32_bf16 v[102:105], v[144:147], v[234:237], v[102:105]
	v_mfma_f32_16x16x32_bf16 v[98:101], v[172:175], v[234:237], v[98:101]
	s_setprio 0
	s_setprio 1
	v_mfma_f32_16x16x32_bf16 v[62:65], v[190:193], v[206:209], v[62:65]
	v_mfma_f32_16x16x32_bf16 v[58:61], v[198:201], v[206:209], v[58:61]
	v_mfma_f32_16x16x32_bf16 v[54:57], v[190:193], v[214:217], v[54:57]
	v_mfma_f32_16x16x32_bf16 v[50:53], v[198:201], v[214:217], v[50:53]
	v_mfma_f32_16x16x32_bf16 v[46:49], v[190:193], v[222:225], v[46:49]
	v_mfma_f32_16x16x32_bf16 v[42:45], v[198:201], v[222:225], v[42:45]
	v_mfma_f32_16x16x32_bf16 v[38:41], v[190:193], v[230:233], v[38:41]
	v_mfma_f32_16x16x32_bf16 v[34:37], v[198:201], v[230:233], v[34:37]
	v_mfma_f32_16x16x32_bf16 v[62:65], v[194:197], v[210:213], v[62:65]
	v_mfma_f32_16x16x32_bf16 v[58:61], v[202:205], v[210:213], v[58:61]
	v_mfma_f32_16x16x32_bf16 v[54:57], v[194:197], v[218:221], v[54:57]
	v_mfma_f32_16x16x32_bf16 v[50:53], v[202:205], v[218:221], v[50:53]
	v_mfma_f32_16x16x32_bf16 v[46:49], v[194:197], v[226:229], v[46:49]
	v_mfma_f32_16x16x32_bf16 v[42:45], v[202:205], v[226:229], v[42:45]
	v_mfma_f32_16x16x32_bf16 v[38:41], v[194:197], v[234:237], v[38:41]
	v_mfma_f32_16x16x32_bf16 v[34:37], v[202:205], v[234:237], v[34:37]
	s_setprio 0
	s_barrier
	s_add_i32 s3, s3, s11
	v_lshl_add_u64 v[176:177], s[0:1], 0, v[4:5]
	s_mov_b32 m0, s3
	s_nop 0
	global_load_lds_dwordx4 v[176:177], off
	ds_read_b128 v[206:209], v166 offset:16384
	ds_read_b128 v[210:213], v166 offset:17408
	s_add_i32 m0, s3, 0x2000
	s_add_u32 s4, s0, 0x80000
	v_lshl_add_u64 v[238:239], s[0:1], 0, v[134:135]
	s_addc_u32 s5, s1, 0
	s_add_i32 s3, s6, s11
	global_load_lds_dwordx4 v[238:239], off
	ds_read_b128 v[214:217], v166 offset:18432
	ds_read_b128 v[218:221], v166 offset:19456
	v_lshl_add_u64 v[240:241], s[4:5], 0, v[4:5]
	s_mov_b32 m0, s3
	v_lshl_add_u64 v[242:243], s[14:15], 0, v[132:133]
	global_load_lds_dwordx4 v[240:241], off
	ds_read_b128 v[222:225], v166 offset:20480
	ds_read_b128 v[226:229], v166 offset:21504
	v_lshl_add_u64 v[240:241], s[4:5], 0, v[134:135]
	s_add_i32 m0, s3, 0x2000
	s_nop 0
	global_load_lds_dwordx4 v[240:241], off
	ds_read_b128 v[230:233], v166 offset:22528
	ds_read_b128 v[234:237], v166 offset:23552
	v_lshl_add_u64 v[240:241], s[14:15], 0, v[130:131]
	s_mov_b32 m0, s26
	s_nop 0
	global_load_lds_dwordx4 v[240:241], off
	s_mov_b32 m0, s27
	s_nop 0
	global_load_lds_dwordx4 v[242:243], off
	s_waitcnt vmcnt(8)
	s_waitcnt lgkmcnt(0)
	s_barrier
	s_setprio 1
	s_waitcnt lgkmcnt(0)
	v_mfma_f32_16x16x32_bf16 v[94:97], v[140:143], v[206:209], v[94:97]
	v_mfma_f32_16x16x32_bf16 v[90:93], v[148:151], v[206:209], v[90:93]
	v_mfma_f32_16x16x32_bf16 v[86:89], v[140:143], v[214:217], v[86:89]
	v_mfma_f32_16x16x32_bf16 v[82:85], v[148:151], v[214:217], v[82:85]
	v_mfma_f32_16x16x32_bf16 v[78:81], v[140:143], v[222:225], v[78:81]
	v_mfma_f32_16x16x32_bf16 v[74:77], v[148:151], v[222:225], v[74:77]
	v_mfma_f32_16x16x32_bf16 v[70:73], v[140:143], v[230:233], v[70:73]
	v_mfma_f32_16x16x32_bf16 v[66:69], v[148:151], v[230:233], v[66:69]
	v_mfma_f32_16x16x32_bf16 v[94:97], v[144:147], v[210:213], v[94:97]
	v_mfma_f32_16x16x32_bf16 v[90:93], v[172:175], v[210:213], v[90:93]
	v_mfma_f32_16x16x32_bf16 v[86:89], v[144:147], v[218:221], v[86:89]
	v_mfma_f32_16x16x32_bf16 v[82:85], v[172:175], v[218:221], v[82:85]
	v_mfma_f32_16x16x32_bf16 v[78:81], v[144:147], v[226:229], v[78:81]
	v_mfma_f32_16x16x32_bf16 v[74:77], v[172:175], v[226:229], v[74:77]
	v_mfma_f32_16x16x32_bf16 v[70:73], v[144:147], v[234:237], v[70:73]
	v_mfma_f32_16x16x32_bf16 v[66:69], v[172:175], v[234:237], v[66:69]
	s_setprio 0
	s_setprio 1
	v_mfma_f32_16x16x32_bf16 v[30:33], v[190:193], v[206:209], v[30:33]
	v_mfma_f32_16x16x32_bf16 v[26:29], v[198:201], v[206:209], v[26:29]
	v_mfma_f32_16x16x32_bf16 v[22:25], v[190:193], v[214:217], v[22:25]
	v_mfma_f32_16x16x32_bf16 v[18:21], v[198:201], v[214:217], v[18:21]
	v_mfma_f32_16x16x32_bf16 v[14:17], v[190:193], v[222:225], v[14:17]
	v_mfma_f32_16x16x32_bf16 v[10:13], v[198:201], v[222:225], v[10:13]
	v_mfma_f32_16x16x32_bf16 v[6:9], v[190:193], v[230:233], v[6:9]
	v_mfma_f32_16x16x32_bf16 v[0:3], v[198:201], v[230:233], v[0:3]
	v_mfma_f32_16x16x32_bf16 v[30:33], v[194:197], v[210:213], v[30:33]
	v_mfma_f32_16x16x32_bf16 v[26:29], v[202:205], v[210:213], v[26:29]
	v_mfma_f32_16x16x32_bf16 v[22:25], v[194:197], v[218:221], v[22:25]
	v_mfma_f32_16x16x32_bf16 v[18:21], v[202:205], v[218:221], v[18:21]
	v_mfma_f32_16x16x32_bf16 v[14:17], v[194:197], v[226:229], v[14:17]
	v_mfma_f32_16x16x32_bf16 v[10:13], v[202:205], v[226:229], v[10:13]
	v_mfma_f32_16x16x32_bf16 v[6:9], v[194:197], v[234:237], v[6:9]
	v_mfma_f32_16x16x32_bf16 v[0:3], v[202:205], v[234:237], v[0:3]
	s_setprio 0
	s_barrier
.Lpeelmid_852:
	s_add_u32 s4, s14, 0x80000
	s_addc_u32 s5, s15, 0
	s_mov_b32 m0, s30
	v_lshl_add_u64 v[244:245], s[4:5], 0, v[130:131]
	global_load_lds_dwordx4 v[244:245], off
	s_add_i32 s3, 0, 0x18000
	v_add_u32_e32 v167, s3, v163
	s_add_i32 s6, 0, 0x1c000
	ds_read_b128 v[140:143], v167
	ds_read_b128 v[144:147], v167 offset:1024
	ds_read_b128 v[148:151], v167 offset:2048
	ds_read_b128 v[172:175], v167 offset:3072
	v_add_u32_e32 v167, s6, v163
	ds_read_b128 v[190:193], v167
	ds_read_b128 v[194:197], v167 offset:1024
	ds_read_b128 v[198:201], v167 offset:2048
	ds_read_b128 v[202:205], v167 offset:3072
	ds_read_b128 v[206:209], v166 offset:32768
	ds_read_b128 v[210:213], v166 offset:33792
	ds_read_b128 v[214:217], v166 offset:34816
	ds_read_b128 v[218:221], v166 offset:35840
	ds_read_b128 v[222:225], v166 offset:36864
	ds_read_b128 v[226:229], v166 offset:37888
	ds_read_b128 v[230:233], v166 offset:38912
	ds_read_b128 v[234:237], v166 offset:39936
	v_lshl_add_u64 v[244:245], s[4:5], 0, v[132:133]
	s_mov_b32 m0, s31
	s_nop 0
	global_load_lds_dwordx4 v[244:245], off
	s_waitcnt vmcnt(8)
	s_waitcnt lgkmcnt(0)
	s_barrier
	s_setprio 1
	s_waitcnt lgkmcnt(0)
	v_mfma_f32_16x16x32_bf16 v[126:129], v[140:143], v[206:209], v[126:129]
	v_mfma_f32_16x16x32_bf16 v[122:125], v[148:151], v[206:209], v[122:125]
	v_mfma_f32_16x16x32_bf16 v[118:121], v[140:143], v[214:217], v[118:121]
	v_mfma_f32_16x16x32_bf16 v[114:117], v[148:151], v[214:217], v[114:117]
	v_mfma_f32_16x16x32_bf16 v[110:113], v[140:143], v[222:225], v[110:113]
	v_mfma_f32_16x16x32_bf16 v[106:109], v[148:151], v[222:225], v[106:109]
	v_mfma_f32_16x16x32_bf16 v[102:105], v[140:143], v[230:233], v[102:105]
	v_mfma_f32_16x16x32_bf16 v[98:101], v[148:151], v[230:233], v[98:101]
	v_mfma_f32_16x16x32_bf16 v[126:129], v[144:147], v[210:213], v[126:129]
	v_mfma_f32_16x16x32_bf16 v[122:125], v[172:175], v[210:213], v[122:125]
	v_mfma_f32_16x16x32_bf16 v[118:121], v[144:147], v[218:221], v[118:121]
	v_mfma_f32_16x16x32_bf16 v[114:117], v[172:175], v[218:221], v[114:117]
	v_mfma_f32_16x16x32_bf16 v[110:113], v[144:147], v[226:229], v[110:113]
	v_mfma_f32_16x16x32_bf16 v[106:109], v[172:175], v[226:229], v[106:109]
	v_mfma_f32_16x16x32_bf16 v[102:105], v[144:147], v[234:237], v[102:105]
	v_mfma_f32_16x16x32_bf16 v[98:101], v[172:175], v[234:237], v[98:101]
	s_setprio 0
	s_setprio 1
	v_mfma_f32_16x16x32_bf16 v[62:65], v[190:193], v[206:209], v[62:65]
	v_mfma_f32_16x16x32_bf16 v[58:61], v[198:201], v[206:209], v[58:61]
	v_mfma_f32_16x16x32_bf16 v[54:57], v[190:193], v[214:217], v[54:57]
	v_mfma_f32_16x16x32_bf16 v[50:53], v[198:201], v[214:217], v[50:53]
	v_mfma_f32_16x16x32_bf16 v[46:49], v[190:193], v[222:225], v[46:49]
	v_mfma_f32_16x16x32_bf16 v[42:45], v[198:201], v[222:225], v[42:45]
	v_mfma_f32_16x16x32_bf16 v[38:41], v[190:193], v[230:233], v[38:41]
	v_mfma_f32_16x16x32_bf16 v[34:37], v[198:201], v[230:233], v[34:37]
	v_mfma_f32_16x16x32_bf16 v[62:65], v[194:197], v[210:213], v[62:65]
	v_mfma_f32_16x16x32_bf16 v[58:61], v[202:205], v[210:213], v[58:61]
	v_mfma_f32_16x16x32_bf16 v[54:57], v[194:197], v[218:221], v[54:57]
	v_mfma_f32_16x16x32_bf16 v[50:53], v[202:205], v[218:221], v[50:53]
	v_mfma_f32_16x16x32_bf16 v[46:49], v[194:197], v[226:229], v[46:49]
	v_mfma_f32_16x16x32_bf16 v[42:45], v[202:205], v[226:229], v[42:45]
	v_mfma_f32_16x16x32_bf16 v[38:41], v[194:197], v[234:237], v[38:41]
	v_mfma_f32_16x16x32_bf16 v[34:37], v[202:205], v[234:237], v[34:37]
	s_setprio 0
	s_barrier
	s_add_i32 s3, s3, s11
	v_lshl_add_u64 v[176:177], v[176:177], 0, s[70:71]
	s_mov_b32 m0, s3
	s_nop 0
	global_load_lds_dwordx4 v[176:177], off
	ds_read_b128 v[206:209], v166 offset:49152
	ds_read_b128 v[210:213], v166 offset:50176
	s_add_i32 m0, s3, 0x2000
	s_add_u32 s0, s0, 0x80080
	v_lshl_add_u64 v[176:177], v[238:239], 0, s[70:71]
	s_addc_u32 s1, s1, 0
	s_add_i32 s3, s6, s11
	global_load_lds_dwordx4 v[176:177], off
	ds_read_b128 v[214:217], v166 offset:51200
	ds_read_b128 v[218:221], v166 offset:52224
	v_lshl_add_u64 v[176:177], s[0:1], 0, v[4:5]
	s_mov_b32 m0, s3
	s_nop 0
	global_load_lds_dwordx4 v[176:177], off
	ds_read_b128 v[222:225], v166 offset:53248
	ds_read_b128 v[226:229], v166 offset:54272
	v_lshl_add_u64 v[176:177], s[0:1], 0, v[134:135]
	s_add_i32 m0, s3, 0x2000
	s_nop 0
	global_load_lds_dwordx4 v[176:177], off
	ds_read_b128 v[230:233], v166 offset:55296
	ds_read_b128 v[234:237], v166 offset:56320
	v_lshl_add_u64 v[176:177], v[240:241], 0, s[70:71]
	s_mov_b32 m0, s34
	s_nop 0
	global_load_lds_dwordx4 v[176:177], off
	v_lshl_add_u64 v[176:177], v[242:243], 0, s[70:71]
	s_mov_b32 m0, s35
	s_nop 0
	global_load_lds_dwordx4 v[176:177], off
	s_waitcnt vmcnt(8)
	s_waitcnt lgkmcnt(0)
	s_barrier
	s_setprio 1
	s_waitcnt lgkmcnt(0)
	v_mfma_f32_16x16x32_bf16 v[94:97], v[140:143], v[206:209], v[94:97]
	v_mfma_f32_16x16x32_bf16 v[90:93], v[148:151], v[206:209], v[90:93]
	v_mfma_f32_16x16x32_bf16 v[86:89], v[140:143], v[214:217], v[86:89]
	v_mfma_f32_16x16x32_bf16 v[82:85], v[148:151], v[214:217], v[82:85]
	v_mfma_f32_16x16x32_bf16 v[78:81], v[140:143], v[222:225], v[78:81]
	v_mfma_f32_16x16x32_bf16 v[74:77], v[148:151], v[222:225], v[74:77]
	v_mfma_f32_16x16x32_bf16 v[70:73], v[140:143], v[230:233], v[70:73]
	v_mfma_f32_16x16x32_bf16 v[66:69], v[148:151], v[230:233], v[66:69]
	v_mfma_f32_16x16x32_bf16 v[94:97], v[144:147], v[210:213], v[94:97]
	v_mfma_f32_16x16x32_bf16 v[90:93], v[172:175], v[210:213], v[90:93]
	v_mfma_f32_16x16x32_bf16 v[86:89], v[144:147], v[218:221], v[86:89]
	v_mfma_f32_16x16x32_bf16 v[82:85], v[172:175], v[218:221], v[82:85]
	v_mfma_f32_16x16x32_bf16 v[78:81], v[144:147], v[226:229], v[78:81]
	v_mfma_f32_16x16x32_bf16 v[74:77], v[172:175], v[226:229], v[74:77]
	v_mfma_f32_16x16x32_bf16 v[70:73], v[144:147], v[234:237], v[70:73]
	v_mfma_f32_16x16x32_bf16 v[66:69], v[172:175], v[234:237], v[66:69]
	s_setprio 0
	s_setprio 1
	v_mfma_f32_16x16x32_bf16 v[30:33], v[190:193], v[206:209], v[30:33]
	v_mfma_f32_16x16x32_bf16 v[26:29], v[198:201], v[206:209], v[26:29]
	v_mfma_f32_16x16x32_bf16 v[22:25], v[190:193], v[214:217], v[22:25]
	v_mfma_f32_16x16x32_bf16 v[18:21], v[198:201], v[214:217], v[18:21]
	v_mfma_f32_16x16x32_bf16 v[14:17], v[190:193], v[222:225], v[14:17]
	v_mfma_f32_16x16x32_bf16 v[10:13], v[198:201], v[222:225], v[10:13]
	v_mfma_f32_16x16x32_bf16 v[6:9], v[190:193], v[230:233], v[6:9]
	v_mfma_f32_16x16x32_bf16 v[0:3], v[198:201], v[230:233], v[0:3]
	v_mfma_f32_16x16x32_bf16 v[30:33], v[194:197], v[210:213], v[30:33]
	v_mfma_f32_16x16x32_bf16 v[26:29], v[202:205], v[210:213], v[26:29]
	v_mfma_f32_16x16x32_bf16 v[22:25], v[194:197], v[218:221], v[22:25]
	v_mfma_f32_16x16x32_bf16 v[18:21], v[202:205], v[218:221], v[18:21]
	v_mfma_f32_16x16x32_bf16 v[14:17], v[194:197], v[226:229], v[14:17]
	v_mfma_f32_16x16x32_bf16 v[10:13], v[202:205], v[226:229], v[10:13]
	v_mfma_f32_16x16x32_bf16 v[6:9], v[194:197], v[234:237], v[6:9]
	v_mfma_f32_16x16x32_bf16 v[0:3], v[202:205], v[234:237], v[0:3]
	s_setprio 0
	s_barrier
	s_add_i32 s28, s28, 2
	s_add_u32 s22, s22, 0x100
	s_addc_u32 s23, s23, 0
	s_add_u32 s9, s9, 0x100
	s_addc_u32 s25, s25, 0
	s_cmp_gt_u32 s28, 29
	s_cbranch_scc0 .LBB0_852
	s_and_b64 vcc, exec, s[48:49]
	s_cbranch_vccz .LBB0_855
	s_barrier
